# GEMM K-loops: setprio moved off the barrier-to-MFMA chain, redundant lgkmcnt dropped; NA mask p1 bias reads de-serialized; diff S-wave VALU interleave
# speedup vs baseline: 1.0050x; 1.0050x over previous
.LBB0_236:
	ds_read_b128 v[146:149], v162
	ds_read_b128 v[150:153], v162 offset:1024
	ds_read_b128 v[166:169], v162 offset:2048
	ds_read_b128 v[170:173], v162 offset:3072
	ds_read_b128 v[174:177], v163
	ds_read_b128 v[182:185], v163 offset:1024
	ds_read_b128 v[186:189], v163 offset:2048
	ds_read_b128 v[190:193], v163 offset:3072
	s_add_u32 s26, s4, 0xfff80080
	s_addc_u32 s27, s5, -1
	s_cmp_eq_u32 s63, 28
	s_cselect_b32 s29, s17, s27
	s_cselect_b32 s28, s58, s26
	s_cselect_b32 s27, s15, s62
	s_cselect_b32 s26, s59, s60
	v_lshl_add_u64 v[226:227], s[4:5], 0, v[138:139]
	s_add_i32 m0, s23, 0xc000
	ds_read_b128 v[194:197], v164
	ds_read_b128 v[198:201], v164 offset:1024
	ds_read_b128 v[202:205], v164 offset:2048
	ds_read_b128 v[206:209], v164 offset:3072
	ds_read_b128 v[210:213], v164 offset:4096
	ds_read_b128 v[214:217], v164 offset:5120
	ds_read_b128 v[218:221], v164 offset:6144
	ds_read_b128 v[222:225], v164 offset:7168
	global_load_lds_dwordx4 v[226:227], off
	v_lshl_add_u64 v[226:227], s[4:5], 0, v[140:141]
	s_add_i32 m0, s23, 0xe000
	s_nop 0
	global_load_lds_dwordx4 v[226:227], off
	s_waitcnt vmcnt(8)
	s_waitcnt lgkmcnt(0)
	s_setprio 1
	s_barrier
	v_mfma_f32_16x16x32_bf16 v[126:129], v[146:149], v[194:197], v[126:129]
	v_mfma_f32_16x16x32_bf16 v[122:125], v[166:169], v[194:197], v[122:125]
	v_mfma_f32_16x16x32_bf16 v[110:113], v[146:149], v[202:205], v[110:113]
	v_mfma_f32_16x16x32_bf16 v[106:109], v[166:169], v[202:205], v[106:109]
	v_mfma_f32_16x16x32_bf16 v[94:97], v[146:149], v[210:213], v[94:97]
	v_mfma_f32_16x16x32_bf16 v[90:93], v[166:169], v[210:213], v[90:93]
	v_mfma_f32_16x16x32_bf16 v[78:81], v[146:149], v[218:221], v[78:81]
	v_mfma_f32_16x16x32_bf16 v[74:77], v[166:169], v[218:221], v[74:77]
	v_mfma_f32_16x16x32_bf16 v[126:129], v[150:153], v[198:201], v[126:129]
	v_mfma_f32_16x16x32_bf16 v[122:125], v[170:173], v[198:201], v[122:125]
	v_mfma_f32_16x16x32_bf16 v[110:113], v[150:153], v[206:209], v[110:113]
	v_mfma_f32_16x16x32_bf16 v[106:109], v[170:173], v[206:209], v[106:109]
	v_mfma_f32_16x16x32_bf16 v[94:97], v[150:153], v[214:217], v[94:97]
	v_mfma_f32_16x16x32_bf16 v[90:93], v[170:173], v[214:217], v[90:93]
	v_mfma_f32_16x16x32_bf16 v[78:81], v[150:153], v[222:225], v[78:81]
	v_mfma_f32_16x16x32_bf16 v[74:77], v[170:173], v[222:225], v[74:77]
	v_mfma_f32_16x16x32_bf16 v[118:121], v[174:177], v[194:197], v[118:121]
	v_mfma_f32_16x16x32_bf16 v[114:117], v[186:189], v[194:197], v[114:117]
	v_mfma_f32_16x16x32_bf16 v[102:105], v[174:177], v[202:205], v[102:105]
	v_mfma_f32_16x16x32_bf16 v[98:101], v[186:189], v[202:205], v[98:101]
	v_mfma_f32_16x16x32_bf16 v[86:89], v[174:177], v[210:213], v[86:89]
	v_mfma_f32_16x16x32_bf16 v[82:85], v[186:189], v[210:213], v[82:85]
	v_mfma_f32_16x16x32_bf16 v[70:73], v[174:177], v[218:221], v[70:73]
	v_mfma_f32_16x16x32_bf16 v[66:69], v[186:189], v[218:221], v[66:69]
	v_mfma_f32_16x16x32_bf16 v[118:121], v[182:185], v[198:201], v[118:121]
	v_mfma_f32_16x16x32_bf16 v[114:117], v[190:193], v[198:201], v[114:117]
	v_mfma_f32_16x16x32_bf16 v[102:105], v[182:185], v[206:209], v[102:105]
	v_mfma_f32_16x16x32_bf16 v[98:101], v[190:193], v[206:209], v[98:101]
	v_mfma_f32_16x16x32_bf16 v[86:89], v[182:185], v[214:217], v[86:89]
	v_mfma_f32_16x16x32_bf16 v[82:85], v[190:193], v[214:217], v[82:85]
	v_mfma_f32_16x16x32_bf16 v[70:73], v[182:185], v[222:225], v[70:73]
	v_mfma_f32_16x16x32_bf16 v[66:69], v[190:193], v[222:225], v[66:69]
	s_barrier
	s_setprio 0
	s_add_i32 s64, s55, s30
	v_lshl_add_u64 v[226:227], s[26:27], 0, v[132:133]
	s_mov_b32 m0, s64
	ds_read_b128 v[194:197], v164 offset:16384
	ds_read_b128 v[198:201], v164 offset:17408
	ds_read_b128 v[202:205], v164 offset:18432
	ds_read_b128 v[206:209], v164 offset:19456
	ds_read_b128 v[210:213], v164 offset:20480
	ds_read_b128 v[214:217], v164 offset:21504
	ds_read_b128 v[218:221], v164 offset:22528
	ds_read_b128 v[222:225], v164 offset:23552
	global_load_lds_dwordx4 v[226:227], off
	s_add_i32 m0, s64, 0x2000
	s_add_u32 s64, s26, 0x80000
	v_lshl_add_u64 v[228:229], s[26:27], 0, v[136:137]
	s_addc_u32 s65, s27, 0
	s_add_i32 s66, s56, s30
	global_load_lds_dwordx4 v[228:229], off
	v_lshl_add_u64 v[230:231], s[64:65], 0, v[132:133]
	s_mov_b32 m0, s66
	v_lshl_add_u64 v[232:233], s[28:29], 0, v[134:135]
	global_load_lds_dwordx4 v[230:231], off
	v_lshl_add_u64 v[230:231], s[64:65], 0, v[136:137]
	s_add_i32 m0, s66, 0x2000
	s_nop 0
	global_load_lds_dwordx4 v[230:231], off
	v_lshl_add_u64 v[230:231], s[28:29], 0, v[130:131]
	s_mov_b32 m0, s23
	s_nop 0
	global_load_lds_dwordx4 v[230:231], off
	s_mov_b32 m0, s25
	s_nop 0
	global_load_lds_dwordx4 v[232:233], off
	s_waitcnt vmcnt(8)
	s_waitcnt lgkmcnt(0)
	s_setprio 1
	s_barrier
	v_mfma_f32_16x16x32_bf16 v[62:65], v[146:149], v[194:197], v[62:65]
	v_mfma_f32_16x16x32_bf16 v[58:61], v[166:169], v[194:197], v[58:61]
	v_mfma_f32_16x16x32_bf16 v[46:49], v[146:149], v[202:205], v[46:49]
	v_mfma_f32_16x16x32_bf16 v[42:45], v[166:169], v[202:205], v[42:45]
	v_mfma_f32_16x16x32_bf16 v[30:33], v[146:149], v[210:213], v[30:33]
	v_mfma_f32_16x16x32_bf16 v[26:29], v[166:169], v[210:213], v[26:29]
	v_mfma_f32_16x16x32_bf16 v[14:17], v[146:149], v[218:221], v[14:17]
	v_mfma_f32_16x16x32_bf16 v[10:13], v[166:169], v[218:221], v[10:13]
	v_mfma_f32_16x16x32_bf16 v[62:65], v[150:153], v[198:201], v[62:65]
	v_mfma_f32_16x16x32_bf16 v[58:61], v[170:173], v[198:201], v[58:61]
	v_mfma_f32_16x16x32_bf16 v[46:49], v[150:153], v[206:209], v[46:49]
	v_mfma_f32_16x16x32_bf16 v[42:45], v[170:173], v[206:209], v[42:45]
	v_mfma_f32_16x16x32_bf16 v[30:33], v[150:153], v[214:217], v[30:33]
	v_mfma_f32_16x16x32_bf16 v[26:29], v[170:173], v[214:217], v[26:29]
	v_mfma_f32_16x16x32_bf16 v[14:17], v[150:153], v[222:225], v[14:17]
	v_mfma_f32_16x16x32_bf16 v[10:13], v[170:173], v[222:225], v[10:13]
	v_mfma_f32_16x16x32_bf16 v[54:57], v[174:177], v[194:197], v[54:57]
	v_mfma_f32_16x16x32_bf16 v[50:53], v[186:189], v[194:197], v[50:53]
	v_mfma_f32_16x16x32_bf16 v[38:41], v[174:177], v[202:205], v[38:41]
	v_mfma_f32_16x16x32_bf16 v[34:37], v[186:189], v[202:205], v[34:37]
	v_mfma_f32_16x16x32_bf16 v[22:25], v[174:177], v[210:213], v[22:25]
	v_mfma_f32_16x16x32_bf16 v[18:21], v[186:189], v[210:213], v[18:21]
	v_mfma_f32_16x16x32_bf16 v[6:9], v[174:177], v[218:221], v[6:9]
	v_mfma_f32_16x16x32_bf16 v[2:5], v[186:189], v[218:221], v[2:5]
	v_mfma_f32_16x16x32_bf16 v[54:57], v[182:185], v[198:201], v[54:57]
	v_mfma_f32_16x16x32_bf16 v[50:53], v[190:193], v[198:201], v[50:53]
	v_mfma_f32_16x16x32_bf16 v[38:41], v[182:185], v[206:209], v[38:41]
	v_mfma_f32_16x16x32_bf16 v[34:37], v[190:193], v[206:209], v[34:37]
	v_mfma_f32_16x16x32_bf16 v[22:25], v[182:185], v[214:217], v[22:25]
	v_mfma_f32_16x16x32_bf16 v[18:21], v[190:193], v[214:217], v[18:21]
	v_mfma_f32_16x16x32_bf16 v[6:9], v[182:185], v[222:225], v[6:9]
	v_mfma_f32_16x16x32_bf16 v[2:5], v[190:193], v[222:225], v[2:5]
	s_barrier
	s_setprio 0
	s_add_i32 s64, 0, 0x18000
	s_add_i32 s65, 0, 0x1c000
	v_add_u32_e32 v170, s64, v156
	v_add_u32_e32 v179, s65, v156
	ds_read_b128 v[146:149], v170
	ds_read_b128 v[150:153], v170 offset:1024
	ds_read_b128 v[166:169], v170 offset:2048
	ds_read_b128 v[170:173], v170 offset:3072
	ds_read_b128 v[174:177], v179
	ds_read_b128 v[182:185], v179 offset:1024
	ds_read_b128 v[186:189], v179 offset:2048
	ds_read_b128 v[190:193], v179 offset:3072
	s_add_u32 s28, s28, 0x80000
	s_addc_u32 s29, s29, 0
	s_mov_b32 m0, s31
	v_lshl_add_u64 v[234:235], s[28:29], 0, v[130:131]
	ds_read_b128 v[194:197], v164 offset:32768
	ds_read_b128 v[198:201], v164 offset:33792
	ds_read_b128 v[202:205], v164 offset:34816
	ds_read_b128 v[206:209], v164 offset:35840
	ds_read_b128 v[210:213], v164 offset:36864
	ds_read_b128 v[214:217], v164 offset:37888
	ds_read_b128 v[218:221], v164 offset:38912
	ds_read_b128 v[222:225], v164 offset:39936
	global_load_lds_dwordx4 v[234:235], off
	v_lshl_add_u64 v[234:235], s[28:29], 0, v[134:135]
	s_mov_b32 m0, s34
	s_nop 0
	global_load_lds_dwordx4 v[234:235], off
	s_waitcnt vmcnt(8)
	s_waitcnt lgkmcnt(0)
	s_setprio 1
	s_barrier
	v_mfma_f32_16x16x32_bf16 v[126:129], v[146:149], v[194:197], v[126:129]
	v_mfma_f32_16x16x32_bf16 v[122:125], v[166:169], v[194:197], v[122:125]
	v_mfma_f32_16x16x32_bf16 v[110:113], v[146:149], v[202:205], v[110:113]
	v_mfma_f32_16x16x32_bf16 v[106:109], v[166:169], v[202:205], v[106:109]
	v_mfma_f32_16x16x32_bf16 v[94:97], v[146:149], v[210:213], v[94:97]
	v_mfma_f32_16x16x32_bf16 v[90:93], v[166:169], v[210:213], v[90:93]
	v_mfma_f32_16x16x32_bf16 v[78:81], v[146:149], v[218:221], v[78:81]
	v_mfma_f32_16x16x32_bf16 v[74:77], v[166:169], v[218:221], v[74:77]
	v_mfma_f32_16x16x32_bf16 v[126:129], v[150:153], v[198:201], v[126:129]
	v_mfma_f32_16x16x32_bf16 v[122:125], v[170:173], v[198:201], v[122:125]
	v_mfma_f32_16x16x32_bf16 v[110:113], v[150:153], v[206:209], v[110:113]
	v_mfma_f32_16x16x32_bf16 v[106:109], v[170:173], v[206:209], v[106:109]
	v_mfma_f32_16x16x32_bf16 v[94:97], v[150:153], v[214:217], v[94:97]
	v_mfma_f32_16x16x32_bf16 v[90:93], v[170:173], v[214:217], v[90:93]
	v_mfma_f32_16x16x32_bf16 v[78:81], v[150:153], v[222:225], v[78:81]
	v_mfma_f32_16x16x32_bf16 v[74:77], v[170:173], v[222:225], v[74:77]
	v_mfma_f32_16x16x32_bf16 v[118:121], v[174:177], v[194:197], v[118:121]
	v_mfma_f32_16x16x32_bf16 v[114:117], v[186:189], v[194:197], v[114:117]
	v_mfma_f32_16x16x32_bf16 v[102:105], v[174:177], v[202:205], v[102:105]
	v_mfma_f32_16x16x32_bf16 v[98:101], v[186:189], v[202:205], v[98:101]
	v_mfma_f32_16x16x32_bf16 v[86:89], v[174:177], v[210:213], v[86:89]
	v_mfma_f32_16x16x32_bf16 v[82:85], v[186:189], v[210:213], v[82:85]
	v_mfma_f32_16x16x32_bf16 v[70:73], v[174:177], v[218:221], v[70:73]
	v_mfma_f32_16x16x32_bf16 v[66:69], v[186:189], v[218:221], v[66:69]
	v_mfma_f32_16x16x32_bf16 v[118:121], v[182:185], v[198:201], v[118:121]
	v_mfma_f32_16x16x32_bf16 v[114:117], v[190:193], v[198:201], v[114:117]
	v_mfma_f32_16x16x32_bf16 v[102:105], v[182:185], v[206:209], v[102:105]
	v_mfma_f32_16x16x32_bf16 v[98:101], v[190:193], v[206:209], v[98:101]
	v_mfma_f32_16x16x32_bf16 v[86:89], v[182:185], v[214:217], v[86:89]
	v_mfma_f32_16x16x32_bf16 v[82:85], v[190:193], v[214:217], v[82:85]
	v_mfma_f32_16x16x32_bf16 v[70:73], v[182:185], v[222:225], v[70:73]
	v_mfma_f32_16x16x32_bf16 v[66:69], v[190:193], v[222:225], v[66:69]
	s_barrier
	s_setprio 0
	s_add_i32 s28, s64, s30
	v_lshl_add_u64 v[226:227], v[226:227], 0, s[10:11]
	s_mov_b32 m0, s28
	ds_read_b128 v[194:197], v164 offset:49152
	ds_read_b128 v[198:201], v164 offset:50176
	ds_read_b128 v[202:205], v164 offset:51200
	ds_read_b128 v[206:209], v164 offset:52224
	ds_read_b128 v[210:213], v164 offset:53248
	ds_read_b128 v[214:217], v164 offset:54272
	ds_read_b128 v[218:221], v164 offset:55296
	ds_read_b128 v[222:225], v164 offset:56320
	global_load_lds_dwordx4 v[226:227], off
	s_add_i32 m0, s28, 0x2000
	s_add_u32 s26, s26, 0x80080
	v_lshl_add_u64 v[226:227], v[228:229], 0, s[10:11]
	s_addc_u32 s27, s27, 0
	s_add_i32 s28, s65, s30
	global_load_lds_dwordx4 v[226:227], off
	v_lshl_add_u64 v[226:227], s[26:27], 0, v[132:133]
	s_mov_b32 m0, s28
	s_nop 0
	global_load_lds_dwordx4 v[226:227], off
	v_lshl_add_u64 v[226:227], s[26:27], 0, v[136:137]
	s_add_i32 m0, s28, 0x2000
	s_nop 0
	global_load_lds_dwordx4 v[226:227], off
	v_lshl_add_u64 v[226:227], v[230:231], 0, s[10:11]
	s_mov_b32 m0, s36
	s_nop 0
	global_load_lds_dwordx4 v[226:227], off
	v_lshl_add_u64 v[226:227], v[232:233], 0, s[10:11]
	s_mov_b32 m0, s37
	s_nop 0
	global_load_lds_dwordx4 v[226:227], off
	s_waitcnt vmcnt(8)
	s_waitcnt lgkmcnt(0)
	s_setprio 1
	s_barrier
	v_mfma_f32_16x16x32_bf16 v[62:65], v[146:149], v[194:197], v[62:65]
	v_mfma_f32_16x16x32_bf16 v[58:61], v[166:169], v[194:197], v[58:61]
	v_mfma_f32_16x16x32_bf16 v[46:49], v[146:149], v[202:205], v[46:49]
	v_mfma_f32_16x16x32_bf16 v[42:45], v[166:169], v[202:205], v[42:45]
	v_mfma_f32_16x16x32_bf16 v[30:33], v[146:149], v[210:213], v[30:33]
	v_mfma_f32_16x16x32_bf16 v[26:29], v[166:169], v[210:213], v[26:29]
	v_mfma_f32_16x16x32_bf16 v[14:17], v[146:149], v[218:221], v[14:17]
	v_mfma_f32_16x16x32_bf16 v[10:13], v[166:169], v[218:221], v[10:13]
	v_mfma_f32_16x16x32_bf16 v[62:65], v[150:153], v[198:201], v[62:65]
	v_mfma_f32_16x16x32_bf16 v[58:61], v[170:173], v[198:201], v[58:61]
	v_mfma_f32_16x16x32_bf16 v[46:49], v[150:153], v[206:209], v[46:49]
	v_mfma_f32_16x16x32_bf16 v[42:45], v[170:173], v[206:209], v[42:45]
	v_mfma_f32_16x16x32_bf16 v[30:33], v[150:153], v[214:217], v[30:33]
	v_mfma_f32_16x16x32_bf16 v[26:29], v[170:173], v[214:217], v[26:29]
	v_mfma_f32_16x16x32_bf16 v[14:17], v[150:153], v[222:225], v[14:17]
	v_mfma_f32_16x16x32_bf16 v[10:13], v[170:173], v[222:225], v[10:13]
	v_mfma_f32_16x16x32_bf16 v[54:57], v[174:177], v[194:197], v[54:57]
	v_mfma_f32_16x16x32_bf16 v[50:53], v[186:189], v[194:197], v[50:53]
	v_mfma_f32_16x16x32_bf16 v[38:41], v[174:177], v[202:205], v[38:41]
	v_mfma_f32_16x16x32_bf16 v[34:37], v[186:189], v[202:205], v[34:37]
	v_mfma_f32_16x16x32_bf16 v[22:25], v[174:177], v[210:213], v[22:25]
	v_mfma_f32_16x16x32_bf16 v[18:21], v[186:189], v[210:213], v[18:21]
	v_mfma_f32_16x16x32_bf16 v[6:9], v[174:177], v[218:221], v[6:9]
	v_mfma_f32_16x16x32_bf16 v[2:5], v[186:189], v[218:221], v[2:5]
	v_mfma_f32_16x16x32_bf16 v[54:57], v[182:185], v[198:201], v[54:57]
	v_mfma_f32_16x16x32_bf16 v[50:53], v[190:193], v[198:201], v[50:53]
	v_mfma_f32_16x16x32_bf16 v[38:41], v[182:185], v[206:209], v[38:41]
	v_mfma_f32_16x16x32_bf16 v[34:37], v[190:193], v[206:209], v[34:37]
	v_mfma_f32_16x16x32_bf16 v[22:25], v[182:185], v[214:217], v[22:25]
	v_mfma_f32_16x16x32_bf16 v[18:21], v[190:193], v[214:217], v[18:21]
	v_mfma_f32_16x16x32_bf16 v[6:9], v[182:185], v[222:225], v[6:9]
	v_mfma_f32_16x16x32_bf16 v[2:5], v[190:193], v[222:225], v[2:5]
	s_barrier
	s_setprio 0
	s_add_i32 s63, s63, 2
	s_add_u32 s4, s4, 0x100
	s_addc_u32 s5, s5, 0
	s_add_u32 s60, s60, 0x100
	s_addc_u32 s62, s62, 0
	s_cmp_gt_u32 s63, 29
	s_cbranch_scc0 .LBB0_236
	s_and_b64 vcc, exec, s[12:13]
	s_cbranch_vccz .LBB0_239
	s_barrier

.LBB0_591:
	ds_read_b128 v[144:147], v150
	ds_read_b128 v[154:157], v150 offset:1024
	ds_read_b128 v[158:161], v150 offset:2048
	ds_read_b128 v[162:165], v150 offset:3072
	ds_read_b128 v[166:169], v151
	ds_read_b128 v[170:173], v151 offset:1024
	ds_read_b128 v[174:177], v151 offset:2048
	ds_read_b128 v[182:185], v151 offset:3072
	s_add_i32 s63, s22, 2
	s_add_u32 s23, s20, 0xfff80080
	s_addc_u32 s26, s21, -1
	s_cmp_eq_u32 s11, s22
	s_cselect_b32 s22, s18, s13
	s_cselect_b32 s27, s17, s26
	s_cselect_b32 s26, s16, s23
	s_cselect_b32 s23, s19, s15
	v_lshl_add_u64 v[218:219], s[20:21], 0, v[138:139]
	s_add_i32 m0, s3, 0xc000
	ds_read_b128 v[186:189], v152
	ds_read_b128 v[190:193], v152 offset:1024
	ds_read_b128 v[194:197], v152 offset:2048
	ds_read_b128 v[198:201], v152 offset:3072
	ds_read_b128 v[202:205], v152 offset:4096
	ds_read_b128 v[206:209], v152 offset:5120
	ds_read_b128 v[210:213], v152 offset:6144
	ds_read_b128 v[214:217], v152 offset:7168
	global_load_lds_dwordx4 v[218:219], off
	v_lshl_add_u64 v[218:219], s[20:21], 0, v[140:141]
	s_add_i32 m0, s3, 0xe000
	s_nop 0
	global_load_lds_dwordx4 v[218:219], off
	s_waitcnt vmcnt(8)
	s_waitcnt lgkmcnt(0)
	s_setprio 1
	s_barrier
	v_mfma_f32_16x16x32_bf16 v[126:129], v[144:147], v[186:189], v[126:129]
	v_mfma_f32_16x16x32_bf16 v[122:125], v[158:161], v[186:189], v[122:125]
	v_mfma_f32_16x16x32_bf16 v[118:121], v[144:147], v[194:197], v[118:121]
	v_mfma_f32_16x16x32_bf16 v[114:117], v[158:161], v[194:197], v[114:117]
	v_mfma_f32_16x16x32_bf16 v[106:109], v[144:147], v[202:205], v[106:109]
	v_mfma_f32_16x16x32_bf16 v[98:101], v[158:161], v[202:205], v[98:101]
	v_mfma_f32_16x16x32_bf16 v[90:93], v[144:147], v[210:213], v[90:93]
	v_mfma_f32_16x16x32_bf16 v[82:85], v[158:161], v[210:213], v[82:85]
	v_mfma_f32_16x16x32_bf16 v[126:129], v[154:157], v[190:193], v[126:129]
	v_mfma_f32_16x16x32_bf16 v[122:125], v[162:165], v[190:193], v[122:125]
	v_mfma_f32_16x16x32_bf16 v[118:121], v[154:157], v[198:201], v[118:121]
	v_mfma_f32_16x16x32_bf16 v[114:117], v[162:165], v[198:201], v[114:117]
	v_mfma_f32_16x16x32_bf16 v[106:109], v[154:157], v[206:209], v[106:109]
	v_mfma_f32_16x16x32_bf16 v[98:101], v[162:165], v[206:209], v[98:101]
	v_mfma_f32_16x16x32_bf16 v[90:93], v[154:157], v[214:217], v[90:93]
	v_mfma_f32_16x16x32_bf16 v[82:85], v[162:165], v[214:217], v[82:85]
	v_mfma_f32_16x16x32_bf16 v[110:113], v[166:169], v[186:189], v[110:113]
	v_mfma_f32_16x16x32_bf16 v[102:105], v[174:177], v[186:189], v[102:105]
	v_mfma_f32_16x16x32_bf16 v[94:97], v[166:169], v[194:197], v[94:97]
	v_mfma_f32_16x16x32_bf16 v[86:89], v[174:177], v[194:197], v[86:89]
	v_mfma_f32_16x16x32_bf16 v[78:81], v[166:169], v[202:205], v[78:81]
	v_mfma_f32_16x16x32_bf16 v[74:77], v[174:177], v[202:205], v[74:77]
	v_mfma_f32_16x16x32_bf16 v[70:73], v[166:169], v[210:213], v[70:73]
	v_mfma_f32_16x16x32_bf16 v[66:69], v[174:177], v[210:213], v[66:69]
	v_mfma_f32_16x16x32_bf16 v[110:113], v[170:173], v[190:193], v[110:113]
	v_mfma_f32_16x16x32_bf16 v[102:105], v[182:185], v[190:193], v[102:105]
	v_mfma_f32_16x16x32_bf16 v[94:97], v[170:173], v[198:201], v[94:97]
	v_mfma_f32_16x16x32_bf16 v[86:89], v[182:185], v[198:201], v[86:89]
	v_mfma_f32_16x16x32_bf16 v[78:81], v[170:173], v[206:209], v[78:81]
	v_mfma_f32_16x16x32_bf16 v[74:77], v[182:185], v[206:209], v[74:77]
	v_mfma_f32_16x16x32_bf16 v[70:73], v[170:173], v[214:217], v[70:73]
	v_mfma_f32_16x16x32_bf16 v[66:69], v[182:185], v[214:217], v[66:69]
	s_barrier
	s_setprio 0
	s_add_i32 s66, s56, s30
	v_lshl_add_u64 v[218:219], s[22:23], 0, v[132:133]
	s_mov_b32 m0, s66
	ds_read_b128 v[186:189], v152 offset:16384
	ds_read_b128 v[190:193], v152 offset:17408
	ds_read_b128 v[194:197], v152 offset:18432
	ds_read_b128 v[198:201], v152 offset:19456
	ds_read_b128 v[202:205], v152 offset:20480
	ds_read_b128 v[206:209], v152 offset:21504
	ds_read_b128 v[210:213], v152 offset:22528
	ds_read_b128 v[214:217], v152 offset:23552
	global_load_lds_dwordx4 v[218:219], off
	s_add_i32 m0, s66, 0x2000
	s_add_u32 s66, s22, 0x80000
	v_lshl_add_u64 v[220:221], s[22:23], 0, v[136:137]
	s_addc_u32 s67, s23, 0
	s_add_i32 s68, s57, s30
	global_load_lds_dwordx4 v[220:221], off
	v_lshl_add_u64 v[222:223], s[66:67], 0, v[132:133]
	s_mov_b32 m0, s68
	v_lshl_add_u64 v[224:225], s[26:27], 0, v[134:135]
	global_load_lds_dwordx4 v[222:223], off
	v_lshl_add_u64 v[222:223], s[66:67], 0, v[136:137]
	s_add_i32 m0, s68, 0x2000
	s_nop 0
	global_load_lds_dwordx4 v[222:223], off
	v_lshl_add_u64 v[222:223], s[26:27], 0, v[130:131]
	s_mov_b32 m0, s3
	s_nop 0
	global_load_lds_dwordx4 v[222:223], off
	s_mov_b32 m0, s34
	s_nop 0
	global_load_lds_dwordx4 v[224:225], off
	s_waitcnt vmcnt(8)
	s_waitcnt lgkmcnt(0)
	s_setprio 1
	s_barrier
	v_mfma_f32_16x16x32_bf16 v[62:65], v[144:147], v[186:189], v[62:65]
	v_mfma_f32_16x16x32_bf16 v[58:61], v[158:161], v[186:189], v[58:61]
	v_mfma_f32_16x16x32_bf16 v[54:57], v[144:147], v[194:197], v[54:57]
	v_mfma_f32_16x16x32_bf16 v[50:53], v[158:161], v[194:197], v[50:53]
	v_mfma_f32_16x16x32_bf16 v[38:41], v[144:147], v[202:205], v[38:41]
	v_mfma_f32_16x16x32_bf16 v[34:37], v[158:161], v[202:205], v[34:37]
	v_mfma_f32_16x16x32_bf16 v[22:25], v[144:147], v[210:213], v[22:25]
	v_mfma_f32_16x16x32_bf16 v[18:21], v[158:161], v[210:213], v[18:21]
	v_mfma_f32_16x16x32_bf16 v[62:65], v[154:157], v[190:193], v[62:65]
	v_mfma_f32_16x16x32_bf16 v[58:61], v[162:165], v[190:193], v[58:61]
	v_mfma_f32_16x16x32_bf16 v[54:57], v[154:157], v[198:201], v[54:57]
	v_mfma_f32_16x16x32_bf16 v[50:53], v[162:165], v[198:201], v[50:53]
	v_mfma_f32_16x16x32_bf16 v[38:41], v[154:157], v[206:209], v[38:41]
	v_mfma_f32_16x16x32_bf16 v[34:37], v[162:165], v[206:209], v[34:37]
	v_mfma_f32_16x16x32_bf16 v[22:25], v[154:157], v[214:217], v[22:25]
	v_mfma_f32_16x16x32_bf16 v[18:21], v[162:165], v[214:217], v[18:21]
	v_mfma_f32_16x16x32_bf16 v[46:49], v[166:169], v[186:189], v[46:49]
	v_mfma_f32_16x16x32_bf16 v[42:45], v[174:177], v[186:189], v[42:45]
	v_mfma_f32_16x16x32_bf16 v[30:33], v[166:169], v[194:197], v[30:33]
	v_mfma_f32_16x16x32_bf16 v[26:29], v[174:177], v[194:197], v[26:29]
	v_mfma_f32_16x16x32_bf16 v[14:17], v[166:169], v[202:205], v[14:17]
	v_mfma_f32_16x16x32_bf16 v[10:13], v[174:177], v[202:205], v[10:13]
	v_mfma_f32_16x16x32_bf16 v[6:9], v[166:169], v[210:213], v[6:9]
	v_mfma_f32_16x16x32_bf16 v[2:5], v[174:177], v[210:213], v[2:5]
	v_mfma_f32_16x16x32_bf16 v[46:49], v[170:173], v[190:193], v[46:49]
	v_mfma_f32_16x16x32_bf16 v[42:45], v[182:185], v[190:193], v[42:45]
	v_mfma_f32_16x16x32_bf16 v[30:33], v[170:173], v[198:201], v[30:33]
	v_mfma_f32_16x16x32_bf16 v[26:29], v[182:185], v[198:201], v[26:29]
	v_mfma_f32_16x16x32_bf16 v[14:17], v[170:173], v[206:209], v[14:17]
	v_mfma_f32_16x16x32_bf16 v[10:13], v[182:185], v[206:209], v[10:13]
	v_mfma_f32_16x16x32_bf16 v[6:9], v[170:173], v[214:217], v[6:9]
	v_mfma_f32_16x16x32_bf16 v[2:5], v[182:185], v[214:217], v[2:5]
	s_barrier
	s_setprio 0
	s_add_i32 s66, 0, 0x18000
	v_add_u32_e32 v153, s66, v148
	s_add_i32 s67, 0, 0x1c000
	ds_read_b128 v[144:147], v153
	ds_read_b128 v[154:157], v153 offset:1024
	ds_read_b128 v[158:161], v153 offset:2048
	ds_read_b128 v[162:165], v153 offset:3072
	v_add_u32_e32 v153, s67, v148
	ds_read_b128 v[166:169], v153
	ds_read_b128 v[170:173], v153 offset:1024
	ds_read_b128 v[174:177], v153 offset:2048
	ds_read_b128 v[182:185], v153 offset:3072
	s_add_u32 s26, s26, 0x80000
	s_addc_u32 s27, s27, 0
	s_mov_b32 m0, s35
	v_lshl_add_u64 v[226:227], s[26:27], 0, v[130:131]
	ds_read_b128 v[186:189], v152 offset:32768
	ds_read_b128 v[190:193], v152 offset:33792
	ds_read_b128 v[194:197], v152 offset:34816
	ds_read_b128 v[198:201], v152 offset:35840
	ds_read_b128 v[202:205], v152 offset:36864
	ds_read_b128 v[206:209], v152 offset:37888
	ds_read_b128 v[210:213], v152 offset:38912
	ds_read_b128 v[214:217], v152 offset:39936
	global_load_lds_dwordx4 v[226:227], off
	v_lshl_add_u64 v[226:227], s[26:27], 0, v[134:135]
	s_mov_b32 m0, s36
	s_nop 0
	global_load_lds_dwordx4 v[226:227], off
	s_waitcnt vmcnt(8)
	s_waitcnt lgkmcnt(0)
	s_setprio 1
	s_barrier
	v_mfma_f32_16x16x32_bf16 v[126:129], v[144:147], v[186:189], v[126:129]
	v_mfma_f32_16x16x32_bf16 v[122:125], v[158:161], v[186:189], v[122:125]
	v_mfma_f32_16x16x32_bf16 v[118:121], v[144:147], v[194:197], v[118:121]
	v_mfma_f32_16x16x32_bf16 v[114:117], v[158:161], v[194:197], v[114:117]
	v_mfma_f32_16x16x32_bf16 v[106:109], v[144:147], v[202:205], v[106:109]
	v_mfma_f32_16x16x32_bf16 v[98:101], v[158:161], v[202:205], v[98:101]
	v_mfma_f32_16x16x32_bf16 v[90:93], v[144:147], v[210:213], v[90:93]
	v_mfma_f32_16x16x32_bf16 v[82:85], v[158:161], v[210:213], v[82:85]
	v_mfma_f32_16x16x32_bf16 v[126:129], v[154:157], v[190:193], v[126:129]
	v_mfma_f32_16x16x32_bf16 v[122:125], v[162:165], v[190:193], v[122:125]
	v_mfma_f32_16x16x32_bf16 v[118:121], v[154:157], v[198:201], v[118:121]
	v_mfma_f32_16x16x32_bf16 v[114:117], v[162:165], v[198:201], v[114:117]
	v_mfma_f32_16x16x32_bf16 v[106:109], v[154:157], v[206:209], v[106:109]
	v_mfma_f32_16x16x32_bf16 v[98:101], v[162:165], v[206:209], v[98:101]
	v_mfma_f32_16x16x32_bf16 v[90:93], v[154:157], v[214:217], v[90:93]
	v_mfma_f32_16x16x32_bf16 v[82:85], v[162:165], v[214:217], v[82:85]
	v_mfma_f32_16x16x32_bf16 v[110:113], v[166:169], v[186:189], v[110:113]
	v_mfma_f32_16x16x32_bf16 v[102:105], v[174:177], v[186:189], v[102:105]
	v_mfma_f32_16x16x32_bf16 v[94:97], v[166:169], v[194:197], v[94:97]
	v_mfma_f32_16x16x32_bf16 v[86:89], v[174:177], v[194:197], v[86:89]
	v_mfma_f32_16x16x32_bf16 v[78:81], v[166:169], v[202:205], v[78:81]
	v_mfma_f32_16x16x32_bf16 v[74:77], v[174:177], v[202:205], v[74:77]
	v_mfma_f32_16x16x32_bf16 v[70:73], v[166:169], v[210:213], v[70:73]
	v_mfma_f32_16x16x32_bf16 v[66:69], v[174:177], v[210:213], v[66:69]
	v_mfma_f32_16x16x32_bf16 v[110:113], v[170:173], v[190:193], v[110:113]
	v_mfma_f32_16x16x32_bf16 v[102:105], v[182:185], v[190:193], v[102:105]
	v_mfma_f32_16x16x32_bf16 v[94:97], v[170:173], v[198:201], v[94:97]
	v_mfma_f32_16x16x32_bf16 v[86:89], v[182:185], v[198:201], v[86:89]
	v_mfma_f32_16x16x32_bf16 v[78:81], v[170:173], v[206:209], v[78:81]
	v_mfma_f32_16x16x32_bf16 v[74:77], v[182:185], v[206:209], v[74:77]
	v_mfma_f32_16x16x32_bf16 v[70:73], v[170:173], v[214:217], v[70:73]
	v_mfma_f32_16x16x32_bf16 v[66:69], v[182:185], v[214:217], v[66:69]
	s_barrier
	s_setprio 0
	s_add_i32 s26, s66, s30
	v_lshl_add_u64 v[218:219], v[218:219], 0, s[6:7]
	s_mov_b32 m0, s26
	ds_read_b128 v[186:189], v152 offset:49152
	ds_read_b128 v[190:193], v152 offset:50176
	ds_read_b128 v[194:197], v152 offset:51200
	ds_read_b128 v[198:201], v152 offset:52224
	ds_read_b128 v[202:205], v152 offset:53248
	ds_read_b128 v[206:209], v152 offset:54272
	ds_read_b128 v[210:213], v152 offset:55296
	ds_read_b128 v[214:217], v152 offset:56320
	global_load_lds_dwordx4 v[218:219], off
	s_add_i32 m0, s26, 0x2000
	s_add_u32 s22, s22, 0x80080
	v_lshl_add_u64 v[218:219], v[220:221], 0, s[6:7]
	s_addc_u32 s23, s23, 0
	s_add_i32 s26, s67, s30
	global_load_lds_dwordx4 v[218:219], off
	v_lshl_add_u64 v[218:219], s[22:23], 0, v[132:133]
	s_mov_b32 m0, s26
	s_nop 0
	global_load_lds_dwordx4 v[218:219], off
	v_lshl_add_u64 v[218:219], s[22:23], 0, v[136:137]
	s_add_i32 m0, s26, 0x2000
	s_nop 0
	global_load_lds_dwordx4 v[218:219], off
	v_lshl_add_u64 v[218:219], v[222:223], 0, s[6:7]
	s_mov_b32 m0, s52
	s_nop 0
	global_load_lds_dwordx4 v[218:219], off
	v_lshl_add_u64 v[218:219], v[224:225], 0, s[6:7]
	s_mov_b32 m0, s53
	s_nop 0
	global_load_lds_dwordx4 v[218:219], off
	s_waitcnt vmcnt(8)
	s_waitcnt lgkmcnt(0)
	s_setprio 1
	s_barrier
	v_mfma_f32_16x16x32_bf16 v[62:65], v[144:147], v[186:189], v[62:65]
	v_mfma_f32_16x16x32_bf16 v[58:61], v[158:161], v[186:189], v[58:61]
	v_mfma_f32_16x16x32_bf16 v[54:57], v[144:147], v[194:197], v[54:57]
	v_mfma_f32_16x16x32_bf16 v[50:53], v[158:161], v[194:197], v[50:53]
	v_mfma_f32_16x16x32_bf16 v[38:41], v[144:147], v[202:205], v[38:41]
	v_mfma_f32_16x16x32_bf16 v[34:37], v[158:161], v[202:205], v[34:37]
	v_mfma_f32_16x16x32_bf16 v[22:25], v[144:147], v[210:213], v[22:25]
	v_mfma_f32_16x16x32_bf16 v[18:21], v[158:161], v[210:213], v[18:21]
	v_mfma_f32_16x16x32_bf16 v[62:65], v[154:157], v[190:193], v[62:65]
	v_mfma_f32_16x16x32_bf16 v[58:61], v[162:165], v[190:193], v[58:61]
	v_mfma_f32_16x16x32_bf16 v[54:57], v[154:157], v[198:201], v[54:57]
	v_mfma_f32_16x16x32_bf16 v[50:53], v[162:165], v[198:201], v[50:53]
	v_mfma_f32_16x16x32_bf16 v[38:41], v[154:157], v[206:209], v[38:41]
	v_mfma_f32_16x16x32_bf16 v[34:37], v[162:165], v[206:209], v[34:37]
	v_mfma_f32_16x16x32_bf16 v[22:25], v[154:157], v[214:217], v[22:25]
	v_mfma_f32_16x16x32_bf16 v[18:21], v[162:165], v[214:217], v[18:21]
	v_mfma_f32_16x16x32_bf16 v[46:49], v[166:169], v[186:189], v[46:49]
	v_mfma_f32_16x16x32_bf16 v[42:45], v[174:177], v[186:189], v[42:45]
	v_mfma_f32_16x16x32_bf16 v[30:33], v[166:169], v[194:197], v[30:33]
	v_mfma_f32_16x16x32_bf16 v[26:29], v[174:177], v[194:197], v[26:29]
	v_mfma_f32_16x16x32_bf16 v[14:17], v[166:169], v[202:205], v[14:17]
	v_mfma_f32_16x16x32_bf16 v[10:13], v[174:177], v[202:205], v[10:13]
	v_mfma_f32_16x16x32_bf16 v[6:9], v[166:169], v[210:213], v[6:9]
	v_mfma_f32_16x16x32_bf16 v[2:5], v[174:177], v[210:213], v[2:5]
	v_mfma_f32_16x16x32_bf16 v[46:49], v[170:173], v[190:193], v[46:49]
	v_mfma_f32_16x16x32_bf16 v[42:45], v[182:185], v[190:193], v[42:45]
	v_mfma_f32_16x16x32_bf16 v[30:33], v[170:173], v[198:201], v[30:33]
	v_mfma_f32_16x16x32_bf16 v[26:29], v[182:185], v[198:201], v[26:29]
	v_mfma_f32_16x16x32_bf16 v[14:17], v[170:173], v[206:209], v[14:17]
	v_mfma_f32_16x16x32_bf16 v[10:13], v[182:185], v[206:209], v[10:13]
	v_mfma_f32_16x16x32_bf16 v[6:9], v[170:173], v[214:217], v[6:9]
	v_mfma_f32_16x16x32_bf16 v[2:5], v[182:185], v[214:217], v[2:5]
	s_barrier
	s_setprio 0
	s_add_u32 s20, s20, 0x100
	s_addc_u32 s21, s21, 0
	s_add_u32 s13, s13, 0x100
	s_addc_u32 s15, s15, 0
	s_cmp_ge_i32 s63, s62
	s_mov_b32 s22, s63
	s_cbranch_scc0 .LBB0_591
	s_and_b64 vcc, exec, s[8:9]
	s_cbranch_vccz .LBB0_594
	s_barrier

.LBB0_736:
	ds_read_b128 v[154:157], v151
	ds_read_b128 v[158:161], v151 offset:1024
	ds_read_b128 v[162:165], v151 offset:2048
	ds_read_b128 v[166:169], v151 offset:3072
	ds_read_b128 v[170:173], v152
	ds_read_b128 v[174:177], v152 offset:1024
	ds_read_b128 v[182:185], v152 offset:2048
	ds_read_b128 v[186:189], v152 offset:3072
	s_add_u32 s20, s18, 0xfff80080
	s_addc_u32 s21, s19, -1
	s_cmp_eq_u32 s63, 28
	s_cselect_b32 s23, s11, s21
	s_cselect_b32 s22, s58, s20
	s_cselect_b32 s21, s9, s62
	s_cselect_b32 s20, s59, s60
	v_lshl_add_u64 v[146:147], s[18:19], 0, v[138:139]
	s_add_i32 m0, s31, 0xc000
	ds_read_b128 v[190:193], v153
	ds_read_b128 v[194:197], v153 offset:1024
	ds_read_b128 v[198:201], v153 offset:2048
	ds_read_b128 v[202:205], v153 offset:3072
	ds_read_b128 v[206:209], v153 offset:4096
	ds_read_b128 v[210:213], v153 offset:5120
	ds_read_b128 v[214:217], v153 offset:6144
	ds_read_b128 v[218:221], v153 offset:7168
	global_load_lds_dwordx4 v[146:147], off
	v_lshl_add_u64 v[146:147], s[18:19], 0, v[140:141]
	s_add_i32 m0, s31, 0xe000
	s_nop 0
	global_load_lds_dwordx4 v[146:147], off
	s_waitcnt vmcnt(8)
	s_waitcnt lgkmcnt(0)
	s_setprio 1
	s_barrier
	v_mfma_f32_16x16x32_bf16 v[126:129], v[154:157], v[190:193], v[126:129]
	v_mfma_f32_16x16x32_bf16 v[118:121], v[162:165], v[190:193], v[118:121]
	v_mfma_f32_16x16x32_bf16 v[110:113], v[154:157], v[198:201], v[110:113]
	v_mfma_f32_16x16x32_bf16 v[102:105], v[162:165], v[198:201], v[102:105]
	v_mfma_f32_16x16x32_bf16 v[94:97], v[154:157], v[206:209], v[94:97]
	v_mfma_f32_16x16x32_bf16 v[86:89], v[162:165], v[206:209], v[86:89]
	v_mfma_f32_16x16x32_bf16 v[78:81], v[154:157], v[214:217], v[78:81]
	v_mfma_f32_16x16x32_bf16 v[70:73], v[162:165], v[214:217], v[70:73]
	v_mfma_f32_16x16x32_bf16 v[126:129], v[158:161], v[194:197], v[126:129]
	v_mfma_f32_16x16x32_bf16 v[118:121], v[166:169], v[194:197], v[118:121]
	v_mfma_f32_16x16x32_bf16 v[110:113], v[158:161], v[202:205], v[110:113]
	v_mfma_f32_16x16x32_bf16 v[102:105], v[166:169], v[202:205], v[102:105]
	v_mfma_f32_16x16x32_bf16 v[94:97], v[158:161], v[210:213], v[94:97]
	v_mfma_f32_16x16x32_bf16 v[86:89], v[166:169], v[210:213], v[86:89]
	v_mfma_f32_16x16x32_bf16 v[78:81], v[158:161], v[218:221], v[78:81]
	v_mfma_f32_16x16x32_bf16 v[70:73], v[166:169], v[218:221], v[70:73]
	v_mfma_f32_16x16x32_bf16 v[122:125], v[170:173], v[190:193], v[122:125]
	v_mfma_f32_16x16x32_bf16 v[114:117], v[182:185], v[190:193], v[114:117]
	v_mfma_f32_16x16x32_bf16 v[106:109], v[170:173], v[198:201], v[106:109]
	v_mfma_f32_16x16x32_bf16 v[98:101], v[182:185], v[198:201], v[98:101]
	v_mfma_f32_16x16x32_bf16 v[90:93], v[170:173], v[206:209], v[90:93]
	v_mfma_f32_16x16x32_bf16 v[82:85], v[182:185], v[206:209], v[82:85]
	v_mfma_f32_16x16x32_bf16 v[74:77], v[170:173], v[214:217], v[74:77]
	v_mfma_f32_16x16x32_bf16 v[66:69], v[182:185], v[214:217], v[66:69]
	v_mfma_f32_16x16x32_bf16 v[122:125], v[174:177], v[194:197], v[122:125]
	v_mfma_f32_16x16x32_bf16 v[114:117], v[186:189], v[194:197], v[114:117]
	v_mfma_f32_16x16x32_bf16 v[106:109], v[174:177], v[202:205], v[106:109]
	v_mfma_f32_16x16x32_bf16 v[98:101], v[186:189], v[202:205], v[98:101]
	v_mfma_f32_16x16x32_bf16 v[90:93], v[174:177], v[210:213], v[90:93]
	v_mfma_f32_16x16x32_bf16 v[82:85], v[186:189], v[210:213], v[82:85]
	v_mfma_f32_16x16x32_bf16 v[74:77], v[174:177], v[218:221], v[74:77]
	v_mfma_f32_16x16x32_bf16 v[66:69], v[186:189], v[218:221], v[66:69]
	s_barrier
	s_setprio 0
	s_add_i32 s66, s55, s28
	v_lshl_add_u64 v[146:147], s[20:21], 0, v[134:135]
	s_mov_b32 m0, s66
	ds_read_b128 v[190:193], v153 offset:16384
	ds_read_b128 v[194:197], v153 offset:17408
	ds_read_b128 v[198:201], v153 offset:18432
	ds_read_b128 v[202:205], v153 offset:19456
	ds_read_b128 v[206:209], v153 offset:20480
	ds_read_b128 v[210:213], v153 offset:21504
	ds_read_b128 v[214:217], v153 offset:22528
	ds_read_b128 v[218:221], v153 offset:23552
	global_load_lds_dwordx4 v[146:147], off
	s_add_i32 m0, s66, 0x2000
	s_add_u32 s66, s20, 0x80000
	v_lshl_add_u64 v[222:223], s[20:21], 0, v[130:131]
	s_addc_u32 s67, s21, 0
	s_add_i32 s68, s56, s28
	global_load_lds_dwordx4 v[222:223], off
	v_lshl_add_u64 v[224:225], s[66:67], 0, v[134:135]
	s_mov_b32 m0, s68
	v_lshl_add_u64 v[226:227], s[22:23], 0, v[132:133]
	global_load_lds_dwordx4 v[224:225], off
	v_lshl_add_u64 v[224:225], s[66:67], 0, v[130:131]
	s_add_i32 m0, s68, 0x2000
	s_nop 0
	global_load_lds_dwordx4 v[224:225], off
	v_lshl_add_u64 v[224:225], s[22:23], 0, v[136:137]
	s_mov_b32 m0, s31
	s_nop 0
	global_load_lds_dwordx4 v[224:225], off
	s_mov_b32 m0, s34
	s_nop 0
	global_load_lds_dwordx4 v[226:227], off
	s_waitcnt vmcnt(8)
	s_waitcnt lgkmcnt(0)
	s_setprio 1
	s_barrier
	v_mfma_f32_16x16x32_bf16 v[62:65], v[154:157], v[190:193], v[62:65]
	v_mfma_f32_16x16x32_bf16 v[54:57], v[162:165], v[190:193], v[54:57]
	v_mfma_f32_16x16x32_bf16 v[46:49], v[154:157], v[198:201], v[46:49]
	v_mfma_f32_16x16x32_bf16 v[38:41], v[162:165], v[198:201], v[38:41]
	v_mfma_f32_16x16x32_bf16 v[30:33], v[154:157], v[206:209], v[30:33]
	v_mfma_f32_16x16x32_bf16 v[22:25], v[162:165], v[206:209], v[22:25]
	v_mfma_f32_16x16x32_bf16 v[14:17], v[154:157], v[214:217], v[14:17]
	v_mfma_f32_16x16x32_bf16 v[6:9], v[162:165], v[214:217], v[6:9]
	v_mfma_f32_16x16x32_bf16 v[62:65], v[158:161], v[194:197], v[62:65]
	v_mfma_f32_16x16x32_bf16 v[54:57], v[166:169], v[194:197], v[54:57]
	v_mfma_f32_16x16x32_bf16 v[46:49], v[158:161], v[202:205], v[46:49]
	v_mfma_f32_16x16x32_bf16 v[38:41], v[166:169], v[202:205], v[38:41]
	v_mfma_f32_16x16x32_bf16 v[30:33], v[158:161], v[210:213], v[30:33]
	v_mfma_f32_16x16x32_bf16 v[22:25], v[166:169], v[210:213], v[22:25]
	v_mfma_f32_16x16x32_bf16 v[14:17], v[158:161], v[218:221], v[14:17]
	v_mfma_f32_16x16x32_bf16 v[6:9], v[166:169], v[218:221], v[6:9]
	v_mfma_f32_16x16x32_bf16 v[58:61], v[170:173], v[190:193], v[58:61]
	v_mfma_f32_16x16x32_bf16 v[50:53], v[182:185], v[190:193], v[50:53]
	v_mfma_f32_16x16x32_bf16 v[42:45], v[170:173], v[198:201], v[42:45]
	v_mfma_f32_16x16x32_bf16 v[34:37], v[182:185], v[198:201], v[34:37]
	v_mfma_f32_16x16x32_bf16 v[26:29], v[170:173], v[206:209], v[26:29]
	v_mfma_f32_16x16x32_bf16 v[18:21], v[182:185], v[206:209], v[18:21]
	v_mfma_f32_16x16x32_bf16 v[10:13], v[170:173], v[214:217], v[10:13]
	v_mfma_f32_16x16x32_bf16 v[2:5], v[182:185], v[214:217], v[2:5]
	v_mfma_f32_16x16x32_bf16 v[58:61], v[174:177], v[194:197], v[58:61]
	v_mfma_f32_16x16x32_bf16 v[50:53], v[186:189], v[194:197], v[50:53]
	v_mfma_f32_16x16x32_bf16 v[42:45], v[174:177], v[202:205], v[42:45]
	v_mfma_f32_16x16x32_bf16 v[34:37], v[186:189], v[202:205], v[34:37]
	v_mfma_f32_16x16x32_bf16 v[26:29], v[174:177], v[210:213], v[26:29]
	v_mfma_f32_16x16x32_bf16 v[18:21], v[186:189], v[210:213], v[18:21]
	v_mfma_f32_16x16x32_bf16 v[10:13], v[174:177], v[218:221], v[10:13]
	v_mfma_f32_16x16x32_bf16 v[2:5], v[186:189], v[218:221], v[2:5]
	s_barrier
	s_setprio 0
	s_add_i32 s66, 0, 0x18000
	s_add_i32 s67, 0, 0x1c000
	v_add_u32_e32 v166, s66, v149
	v_add_u32_e32 v179, s67, v149
	ds_read_b128 v[154:157], v166
	ds_read_b128 v[158:161], v166 offset:1024
	ds_read_b128 v[162:165], v166 offset:2048
	ds_read_b128 v[166:169], v166 offset:3072
	ds_read_b128 v[170:173], v179
	ds_read_b128 v[174:177], v179 offset:1024
	ds_read_b128 v[182:185], v179 offset:2048
	ds_read_b128 v[186:189], v179 offset:3072
	s_add_u32 s22, s22, 0x80000
	s_addc_u32 s23, s23, 0
	s_mov_b32 m0, s35
	v_lshl_add_u64 v[228:229], s[22:23], 0, v[136:137]
	ds_read_b128 v[190:193], v153 offset:32768
	ds_read_b128 v[194:197], v153 offset:33792
	ds_read_b128 v[198:201], v153 offset:34816
	ds_read_b128 v[202:205], v153 offset:35840
	ds_read_b128 v[206:209], v153 offset:36864
	ds_read_b128 v[210:213], v153 offset:37888
	ds_read_b128 v[214:217], v153 offset:38912
	ds_read_b128 v[218:221], v153 offset:39936
	global_load_lds_dwordx4 v[228:229], off
	v_lshl_add_u64 v[228:229], s[22:23], 0, v[132:133]
	s_mov_b32 m0, s36
	s_nop 0
	global_load_lds_dwordx4 v[228:229], off
	s_waitcnt vmcnt(8)
	s_waitcnt lgkmcnt(0)
	s_setprio 1
	s_barrier
	v_mfma_f32_16x16x32_bf16 v[126:129], v[154:157], v[190:193], v[126:129]
	v_mfma_f32_16x16x32_bf16 v[118:121], v[162:165], v[190:193], v[118:121]
	v_mfma_f32_16x16x32_bf16 v[110:113], v[154:157], v[198:201], v[110:113]
	v_mfma_f32_16x16x32_bf16 v[102:105], v[162:165], v[198:201], v[102:105]
	v_mfma_f32_16x16x32_bf16 v[94:97], v[154:157], v[206:209], v[94:97]
	v_mfma_f32_16x16x32_bf16 v[86:89], v[162:165], v[206:209], v[86:89]
	v_mfma_f32_16x16x32_bf16 v[78:81], v[154:157], v[214:217], v[78:81]
	v_mfma_f32_16x16x32_bf16 v[70:73], v[162:165], v[214:217], v[70:73]
	v_mfma_f32_16x16x32_bf16 v[126:129], v[158:161], v[194:197], v[126:129]
	v_mfma_f32_16x16x32_bf16 v[118:121], v[166:169], v[194:197], v[118:121]
	v_mfma_f32_16x16x32_bf16 v[110:113], v[158:161], v[202:205], v[110:113]
	v_mfma_f32_16x16x32_bf16 v[102:105], v[166:169], v[202:205], v[102:105]
	v_mfma_f32_16x16x32_bf16 v[94:97], v[158:161], v[210:213], v[94:97]
	v_mfma_f32_16x16x32_bf16 v[86:89], v[166:169], v[210:213], v[86:89]
	v_mfma_f32_16x16x32_bf16 v[78:81], v[158:161], v[218:221], v[78:81]
	v_mfma_f32_16x16x32_bf16 v[70:73], v[166:169], v[218:221], v[70:73]
	v_mfma_f32_16x16x32_bf16 v[122:125], v[170:173], v[190:193], v[122:125]
	v_mfma_f32_16x16x32_bf16 v[114:117], v[182:185], v[190:193], v[114:117]
	v_mfma_f32_16x16x32_bf16 v[106:109], v[170:173], v[198:201], v[106:109]
	v_mfma_f32_16x16x32_bf16 v[98:101], v[182:185], v[198:201], v[98:101]
	v_mfma_f32_16x16x32_bf16 v[90:93], v[170:173], v[206:209], v[90:93]
	v_mfma_f32_16x16x32_bf16 v[82:85], v[182:185], v[206:209], v[82:85]
	v_mfma_f32_16x16x32_bf16 v[74:77], v[170:173], v[214:217], v[74:77]
	v_mfma_f32_16x16x32_bf16 v[66:69], v[182:185], v[214:217], v[66:69]
	v_mfma_f32_16x16x32_bf16 v[122:125], v[174:177], v[194:197], v[122:125]
	v_mfma_f32_16x16x32_bf16 v[114:117], v[186:189], v[194:197], v[114:117]
	v_mfma_f32_16x16x32_bf16 v[106:109], v[174:177], v[202:205], v[106:109]
	v_mfma_f32_16x16x32_bf16 v[98:101], v[186:189], v[202:205], v[98:101]
	v_mfma_f32_16x16x32_bf16 v[90:93], v[174:177], v[210:213], v[90:93]
	v_mfma_f32_16x16x32_bf16 v[82:85], v[186:189], v[210:213], v[82:85]
	v_mfma_f32_16x16x32_bf16 v[74:77], v[174:177], v[218:221], v[74:77]
	v_mfma_f32_16x16x32_bf16 v[66:69], v[186:189], v[218:221], v[66:69]
	s_barrier
	s_setprio 0
	s_add_i32 s22, s66, s28
	v_lshl_add_u64 v[146:147], v[146:147], 0, s[4:5]
	s_mov_b32 m0, s22
	ds_read_b128 v[190:193], v153 offset:49152
	ds_read_b128 v[194:197], v153 offset:50176
	ds_read_b128 v[198:201], v153 offset:51200
	ds_read_b128 v[202:205], v153 offset:52224
	ds_read_b128 v[206:209], v153 offset:53248
	ds_read_b128 v[210:213], v153 offset:54272
	ds_read_b128 v[214:217], v153 offset:55296
	ds_read_b128 v[218:221], v153 offset:56320
	global_load_lds_dwordx4 v[146:147], off
	s_add_i32 m0, s22, 0x2000
	s_add_u32 s20, s20, 0x80080
	v_lshl_add_u64 v[146:147], v[222:223], 0, s[4:5]
	s_addc_u32 s21, s21, 0
	s_add_i32 s22, s67, s28
	global_load_lds_dwordx4 v[146:147], off
	v_lshl_add_u64 v[146:147], s[20:21], 0, v[134:135]
	s_mov_b32 m0, s22
	s_nop 0
	global_load_lds_dwordx4 v[146:147], off
	v_lshl_add_u64 v[146:147], s[20:21], 0, v[130:131]
	s_add_i32 m0, s22, 0x2000
	s_nop 0
	global_load_lds_dwordx4 v[146:147], off
	v_lshl_add_u64 v[146:147], v[224:225], 0, s[4:5]
	s_mov_b32 m0, s52
	s_nop 0
	global_load_lds_dwordx4 v[146:147], off
	v_lshl_add_u64 v[146:147], v[226:227], 0, s[4:5]
	s_mov_b32 m0, s53
	s_nop 0
	global_load_lds_dwordx4 v[146:147], off
	s_waitcnt vmcnt(8)
	s_waitcnt lgkmcnt(0)
	s_setprio 1
	s_barrier
	v_mfma_f32_16x16x32_bf16 v[62:65], v[154:157], v[190:193], v[62:65]
	v_mfma_f32_16x16x32_bf16 v[54:57], v[162:165], v[190:193], v[54:57]
	v_mfma_f32_16x16x32_bf16 v[46:49], v[154:157], v[198:201], v[46:49]
	v_mfma_f32_16x16x32_bf16 v[38:41], v[162:165], v[198:201], v[38:41]
	v_mfma_f32_16x16x32_bf16 v[30:33], v[154:157], v[206:209], v[30:33]
	v_mfma_f32_16x16x32_bf16 v[22:25], v[162:165], v[206:209], v[22:25]
	v_mfma_f32_16x16x32_bf16 v[14:17], v[154:157], v[214:217], v[14:17]
	v_mfma_f32_16x16x32_bf16 v[6:9], v[162:165], v[214:217], v[6:9]
	v_mfma_f32_16x16x32_bf16 v[62:65], v[158:161], v[194:197], v[62:65]
	v_mfma_f32_16x16x32_bf16 v[54:57], v[166:169], v[194:197], v[54:57]
	v_mfma_f32_16x16x32_bf16 v[46:49], v[158:161], v[202:205], v[46:49]
	v_mfma_f32_16x16x32_bf16 v[38:41], v[166:169], v[202:205], v[38:41]
	v_mfma_f32_16x16x32_bf16 v[30:33], v[158:161], v[210:213], v[30:33]
	v_mfma_f32_16x16x32_bf16 v[22:25], v[166:169], v[210:213], v[22:25]
	v_mfma_f32_16x16x32_bf16 v[14:17], v[158:161], v[218:221], v[14:17]
	v_mfma_f32_16x16x32_bf16 v[6:9], v[166:169], v[218:221], v[6:9]
	v_mfma_f32_16x16x32_bf16 v[58:61], v[170:173], v[190:193], v[58:61]
	v_mfma_f32_16x16x32_bf16 v[50:53], v[182:185], v[190:193], v[50:53]
	v_mfma_f32_16x16x32_bf16 v[42:45], v[170:173], v[198:201], v[42:45]
	v_mfma_f32_16x16x32_bf16 v[34:37], v[182:185], v[198:201], v[34:37]
	v_mfma_f32_16x16x32_bf16 v[26:29], v[170:173], v[206:209], v[26:29]
	v_mfma_f32_16x16x32_bf16 v[18:21], v[182:185], v[206:209], v[18:21]
	v_mfma_f32_16x16x32_bf16 v[10:13], v[170:173], v[214:217], v[10:13]
	v_mfma_f32_16x16x32_bf16 v[2:5], v[182:185], v[214:217], v[2:5]
	v_mfma_f32_16x16x32_bf16 v[58:61], v[174:177], v[194:197], v[58:61]
	v_mfma_f32_16x16x32_bf16 v[50:53], v[186:189], v[194:197], v[50:53]
	v_mfma_f32_16x16x32_bf16 v[42:45], v[174:177], v[202:205], v[42:45]
	v_mfma_f32_16x16x32_bf16 v[34:37], v[186:189], v[202:205], v[34:37]
	v_mfma_f32_16x16x32_bf16 v[26:29], v[174:177], v[210:213], v[26:29]
	v_mfma_f32_16x16x32_bf16 v[18:21], v[186:189], v[210:213], v[18:21]
	v_mfma_f32_16x16x32_bf16 v[10:13], v[174:177], v[218:221], v[10:13]
	v_mfma_f32_16x16x32_bf16 v[2:5], v[186:189], v[218:221], v[2:5]
	s_barrier
	s_setprio 0
	s_add_i32 s63, s63, 2
	s_add_u32 s18, s18, 0x100
	s_addc_u32 s19, s19, 0
	s_add_u32 s60, s60, 0x100
	s_addc_u32 s62, s62, 0
	s_cmp_gt_u32 s63, 29
	s_cbranch_scc0 .LBB0_736
	s_and_b64 vcc, exec, s[6:7]
	s_cbranch_vccz .LBB0_739
	s_barrier

.LBB0_854:
	ds_read_b128 v[144:147], v151
	ds_read_b128 v[154:157], v151 offset:1024
	ds_read_b128 v[158:161], v151 offset:2048
	ds_read_b128 v[162:165], v151 offset:3072
	ds_read_b128 v[166:169], v152
	ds_read_b128 v[170:173], v152 offset:1024
	ds_read_b128 v[174:177], v152 offset:2048
	ds_read_b128 v[182:185], v152 offset:3072
	s_add_i32 s63, s14, 2
	s_add_u32 s15, s12, 0xffea0080
	s_addc_u32 s16, s13, -1
	s_cmp_eq_u32 s59, s14
	s_cselect_b32 s14, s10, s60
	s_cselect_b32 s17, s9, s16
	s_cselect_b32 s16, s8, s15
	s_cselect_b32 s15, s11, s62
	v_lshl_add_u64 v[218:219], s[12:13], 0, v[138:139]
	s_add_i32 m0, s23, 0xc000
	ds_read_b128 v[186:189], v153
	ds_read_b128 v[190:193], v153 offset:1024
	ds_read_b128 v[194:197], v153 offset:2048
	ds_read_b128 v[198:201], v153 offset:3072
	ds_read_b128 v[202:205], v153 offset:4096
	ds_read_b128 v[206:209], v153 offset:5120
	ds_read_b128 v[210:213], v153 offset:6144
	ds_read_b128 v[214:217], v153 offset:7168
	global_load_lds_dwordx4 v[218:219], off
	v_lshl_add_u64 v[218:219], s[12:13], 0, v[140:141]
	s_add_i32 m0, s23, 0xe000
	s_nop 0
	global_load_lds_dwordx4 v[218:219], off
	s_waitcnt vmcnt(8)
	s_waitcnt lgkmcnt(0)
	s_setprio 1
	s_barrier
	v_mfma_f32_16x16x32_bf16 v[126:129], v[144:147], v[186:189], v[126:129]
	v_mfma_f32_16x16x32_bf16 v[122:125], v[158:161], v[186:189], v[122:125]
	v_mfma_f32_16x16x32_bf16 v[118:121], v[144:147], v[194:197], v[118:121]
	v_mfma_f32_16x16x32_bf16 v[114:117], v[158:161], v[194:197], v[114:117]
	v_mfma_f32_16x16x32_bf16 v[106:109], v[144:147], v[202:205], v[106:109]
	v_mfma_f32_16x16x32_bf16 v[98:101], v[158:161], v[202:205], v[98:101]
	v_mfma_f32_16x16x32_bf16 v[90:93], v[144:147], v[210:213], v[90:93]
	v_mfma_f32_16x16x32_bf16 v[82:85], v[158:161], v[210:213], v[82:85]
	v_mfma_f32_16x16x32_bf16 v[126:129], v[154:157], v[190:193], v[126:129]
	v_mfma_f32_16x16x32_bf16 v[122:125], v[162:165], v[190:193], v[122:125]
	v_mfma_f32_16x16x32_bf16 v[118:121], v[154:157], v[198:201], v[118:121]
	v_mfma_f32_16x16x32_bf16 v[114:117], v[162:165], v[198:201], v[114:117]
	v_mfma_f32_16x16x32_bf16 v[106:109], v[154:157], v[206:209], v[106:109]
	v_mfma_f32_16x16x32_bf16 v[98:101], v[162:165], v[206:209], v[98:101]
	v_mfma_f32_16x16x32_bf16 v[90:93], v[154:157], v[214:217], v[90:93]
	v_mfma_f32_16x16x32_bf16 v[82:85], v[162:165], v[214:217], v[82:85]
	v_mfma_f32_16x16x32_bf16 v[110:113], v[166:169], v[186:189], v[110:113]
	v_mfma_f32_16x16x32_bf16 v[102:105], v[174:177], v[186:189], v[102:105]
	v_mfma_f32_16x16x32_bf16 v[94:97], v[166:169], v[194:197], v[94:97]
	v_mfma_f32_16x16x32_bf16 v[86:89], v[174:177], v[194:197], v[86:89]
	v_mfma_f32_16x16x32_bf16 v[78:81], v[166:169], v[202:205], v[78:81]
	v_mfma_f32_16x16x32_bf16 v[74:77], v[174:177], v[202:205], v[74:77]
	v_mfma_f32_16x16x32_bf16 v[70:73], v[166:169], v[210:213], v[70:73]
	v_mfma_f32_16x16x32_bf16 v[66:69], v[174:177], v[210:213], v[66:69]
	v_mfma_f32_16x16x32_bf16 v[110:113], v[170:173], v[190:193], v[110:113]
	v_mfma_f32_16x16x32_bf16 v[102:105], v[182:185], v[190:193], v[102:105]
	v_mfma_f32_16x16x32_bf16 v[94:97], v[170:173], v[198:201], v[94:97]
	v_mfma_f32_16x16x32_bf16 v[86:89], v[182:185], v[198:201], v[86:89]
	v_mfma_f32_16x16x32_bf16 v[78:81], v[170:173], v[206:209], v[78:81]
	v_mfma_f32_16x16x32_bf16 v[74:77], v[182:185], v[206:209], v[74:77]
	v_mfma_f32_16x16x32_bf16 v[70:73], v[170:173], v[214:217], v[70:73]
	v_mfma_f32_16x16x32_bf16 v[66:69], v[182:185], v[214:217], v[66:69]
	s_barrier
	s_setprio 0
	s_add_i32 s66, s36, s20
	v_lshl_add_u64 v[218:219], s[14:15], 0, v[132:133]
	s_mov_b32 m0, s66
	ds_read_b128 v[186:189], v153 offset:16384
	ds_read_b128 v[190:193], v153 offset:17408
	ds_read_b128 v[194:197], v153 offset:18432
	ds_read_b128 v[198:201], v153 offset:19456
	ds_read_b128 v[202:205], v153 offset:20480
	ds_read_b128 v[206:209], v153 offset:21504
	ds_read_b128 v[210:213], v153 offset:22528
	ds_read_b128 v[214:217], v153 offset:23552
	global_load_lds_dwordx4 v[218:219], off
	s_add_i32 m0, s66, 0x2000
	s_add_u32 s66, s14, 0x160000
	v_lshl_add_u64 v[220:221], s[14:15], 0, v[136:137]
	s_addc_u32 s67, s15, 0
	s_add_i32 s68, s37, s20
	global_load_lds_dwordx4 v[220:221], off
	v_lshl_add_u64 v[222:223], s[66:67], 0, v[132:133]
	s_mov_b32 m0, s68
	v_lshl_add_u64 v[224:225], s[16:17], 0, v[134:135]
	global_load_lds_dwordx4 v[222:223], off
	v_lshl_add_u64 v[222:223], s[66:67], 0, v[136:137]
	s_add_i32 m0, s68, 0x2000
	s_nop 0
	global_load_lds_dwordx4 v[222:223], off
	v_lshl_add_u64 v[222:223], s[16:17], 0, v[130:131]
	s_mov_b32 m0, s23
	s_nop 0
	global_load_lds_dwordx4 v[222:223], off
	s_mov_b32 m0, s26
	s_nop 0
	global_load_lds_dwordx4 v[224:225], off
	s_waitcnt vmcnt(8)
	s_waitcnt lgkmcnt(0)
	s_setprio 1
	s_barrier
	v_mfma_f32_16x16x32_bf16 v[62:65], v[144:147], v[186:189], v[62:65]
	v_mfma_f32_16x16x32_bf16 v[58:61], v[158:161], v[186:189], v[58:61]
	v_mfma_f32_16x16x32_bf16 v[54:57], v[144:147], v[194:197], v[54:57]
	v_mfma_f32_16x16x32_bf16 v[50:53], v[158:161], v[194:197], v[50:53]
	v_mfma_f32_16x16x32_bf16 v[38:41], v[144:147], v[202:205], v[38:41]
	v_mfma_f32_16x16x32_bf16 v[34:37], v[158:161], v[202:205], v[34:37]
	v_mfma_f32_16x16x32_bf16 v[22:25], v[144:147], v[210:213], v[22:25]
	v_mfma_f32_16x16x32_bf16 v[18:21], v[158:161], v[210:213], v[18:21]
	v_mfma_f32_16x16x32_bf16 v[62:65], v[154:157], v[190:193], v[62:65]
	v_mfma_f32_16x16x32_bf16 v[58:61], v[162:165], v[190:193], v[58:61]
	v_mfma_f32_16x16x32_bf16 v[54:57], v[154:157], v[198:201], v[54:57]
	v_mfma_f32_16x16x32_bf16 v[50:53], v[162:165], v[198:201], v[50:53]
	v_mfma_f32_16x16x32_bf16 v[38:41], v[154:157], v[206:209], v[38:41]
	v_mfma_f32_16x16x32_bf16 v[34:37], v[162:165], v[206:209], v[34:37]
	v_mfma_f32_16x16x32_bf16 v[22:25], v[154:157], v[214:217], v[22:25]
	v_mfma_f32_16x16x32_bf16 v[18:21], v[162:165], v[214:217], v[18:21]
	v_mfma_f32_16x16x32_bf16 v[46:49], v[166:169], v[186:189], v[46:49]
	v_mfma_f32_16x16x32_bf16 v[42:45], v[174:177], v[186:189], v[42:45]
	v_mfma_f32_16x16x32_bf16 v[30:33], v[166:169], v[194:197], v[30:33]
	v_mfma_f32_16x16x32_bf16 v[26:29], v[174:177], v[194:197], v[26:29]
	v_mfma_f32_16x16x32_bf16 v[14:17], v[166:169], v[202:205], v[14:17]
	v_mfma_f32_16x16x32_bf16 v[10:13], v[174:177], v[202:205], v[10:13]
	v_mfma_f32_16x16x32_bf16 v[6:9], v[166:169], v[210:213], v[6:9]
	v_mfma_f32_16x16x32_bf16 v[2:5], v[174:177], v[210:213], v[2:5]
	v_mfma_f32_16x16x32_bf16 v[46:49], v[170:173], v[190:193], v[46:49]
	v_mfma_f32_16x16x32_bf16 v[42:45], v[182:185], v[190:193], v[42:45]
	v_mfma_f32_16x16x32_bf16 v[30:33], v[170:173], v[198:201], v[30:33]
	v_mfma_f32_16x16x32_bf16 v[26:29], v[182:185], v[198:201], v[26:29]
	v_mfma_f32_16x16x32_bf16 v[14:17], v[170:173], v[206:209], v[14:17]
	v_mfma_f32_16x16x32_bf16 v[10:13], v[182:185], v[206:209], v[10:13]
	v_mfma_f32_16x16x32_bf16 v[6:9], v[170:173], v[214:217], v[6:9]
	v_mfma_f32_16x16x32_bf16 v[2:5], v[182:185], v[214:217], v[2:5]
	s_barrier
	s_setprio 0
	s_add_i32 s66, 0, 0x18000
	s_add_i32 s67, 0, 0x1c000
	v_add_u32_e32 v162, s66, v149
	v_add_u32_e32 v179, s67, v149
	ds_read_b128 v[144:147], v162
	ds_read_b128 v[154:157], v162 offset:1024
	ds_read_b128 v[158:161], v162 offset:2048
	ds_read_b128 v[162:165], v162 offset:3072
	ds_read_b128 v[166:169], v179
	ds_read_b128 v[170:173], v179 offset:1024
	ds_read_b128 v[174:177], v179 offset:2048
	ds_read_b128 v[182:185], v179 offset:3072
	s_add_u32 s16, s16, 0x160000
	s_addc_u32 s17, s17, 0
	s_mov_b32 m0, s27
	v_lshl_add_u64 v[226:227], s[16:17], 0, v[130:131]
	ds_read_b128 v[186:189], v153 offset:32768
	ds_read_b128 v[190:193], v153 offset:33792
	ds_read_b128 v[194:197], v153 offset:34816
	ds_read_b128 v[198:201], v153 offset:35840
	ds_read_b128 v[202:205], v153 offset:36864
	ds_read_b128 v[206:209], v153 offset:37888
	ds_read_b128 v[210:213], v153 offset:38912
	ds_read_b128 v[214:217], v153 offset:39936
	global_load_lds_dwordx4 v[226:227], off
	v_lshl_add_u64 v[226:227], s[16:17], 0, v[134:135]
	s_mov_b32 m0, s28
	s_nop 0
	global_load_lds_dwordx4 v[226:227], off
	s_waitcnt vmcnt(8)
	s_waitcnt lgkmcnt(0)
	s_setprio 1
	s_barrier
	v_mfma_f32_16x16x32_bf16 v[126:129], v[144:147], v[186:189], v[126:129]
	v_mfma_f32_16x16x32_bf16 v[122:125], v[158:161], v[186:189], v[122:125]
	v_mfma_f32_16x16x32_bf16 v[118:121], v[144:147], v[194:197], v[118:121]
	v_mfma_f32_16x16x32_bf16 v[114:117], v[158:161], v[194:197], v[114:117]
	v_mfma_f32_16x16x32_bf16 v[106:109], v[144:147], v[202:205], v[106:109]
	v_mfma_f32_16x16x32_bf16 v[98:101], v[158:161], v[202:205], v[98:101]
	v_mfma_f32_16x16x32_bf16 v[90:93], v[144:147], v[210:213], v[90:93]
	v_mfma_f32_16x16x32_bf16 v[82:85], v[158:161], v[210:213], v[82:85]
	v_mfma_f32_16x16x32_bf16 v[126:129], v[154:157], v[190:193], v[126:129]
	v_mfma_f32_16x16x32_bf16 v[122:125], v[162:165], v[190:193], v[122:125]
	v_mfma_f32_16x16x32_bf16 v[118:121], v[154:157], v[198:201], v[118:121]
	v_mfma_f32_16x16x32_bf16 v[114:117], v[162:165], v[198:201], v[114:117]
	v_mfma_f32_16x16x32_bf16 v[106:109], v[154:157], v[206:209], v[106:109]
	v_mfma_f32_16x16x32_bf16 v[98:101], v[162:165], v[206:209], v[98:101]
	v_mfma_f32_16x16x32_bf16 v[90:93], v[154:157], v[214:217], v[90:93]
	v_mfma_f32_16x16x32_bf16 v[82:85], v[162:165], v[214:217], v[82:85]
	v_mfma_f32_16x16x32_bf16 v[110:113], v[166:169], v[186:189], v[110:113]
	v_mfma_f32_16x16x32_bf16 v[102:105], v[174:177], v[186:189], v[102:105]
	v_mfma_f32_16x16x32_bf16 v[94:97], v[166:169], v[194:197], v[94:97]
	v_mfma_f32_16x16x32_bf16 v[86:89], v[174:177], v[194:197], v[86:89]
	v_mfma_f32_16x16x32_bf16 v[78:81], v[166:169], v[202:205], v[78:81]
	v_mfma_f32_16x16x32_bf16 v[74:77], v[174:177], v[202:205], v[74:77]
	v_mfma_f32_16x16x32_bf16 v[70:73], v[166:169], v[210:213], v[70:73]
	v_mfma_f32_16x16x32_bf16 v[66:69], v[174:177], v[210:213], v[66:69]
	v_mfma_f32_16x16x32_bf16 v[110:113], v[170:173], v[190:193], v[110:113]
	v_mfma_f32_16x16x32_bf16 v[102:105], v[182:185], v[190:193], v[102:105]
	v_mfma_f32_16x16x32_bf16 v[94:97], v[170:173], v[198:201], v[94:97]
	v_mfma_f32_16x16x32_bf16 v[86:89], v[182:185], v[198:201], v[86:89]
	v_mfma_f32_16x16x32_bf16 v[78:81], v[170:173], v[206:209], v[78:81]
	v_mfma_f32_16x16x32_bf16 v[74:77], v[182:185], v[206:209], v[74:77]
	v_mfma_f32_16x16x32_bf16 v[70:73], v[170:173], v[214:217], v[70:73]
	v_mfma_f32_16x16x32_bf16 v[66:69], v[182:185], v[214:217], v[66:69]
	s_barrier
	s_setprio 0
	s_add_i32 s16, s66, s20
	v_lshl_add_u64 v[218:219], v[218:219], 0, s[4:5]
	s_mov_b32 m0, s16
	ds_read_b128 v[186:189], v153 offset:49152
	ds_read_b128 v[190:193], v153 offset:50176
	ds_read_b128 v[194:197], v153 offset:51200
	ds_read_b128 v[198:201], v153 offset:52224
	ds_read_b128 v[202:205], v153 offset:53248
	ds_read_b128 v[206:209], v153 offset:54272
	ds_read_b128 v[210:213], v153 offset:55296
	ds_read_b128 v[214:217], v153 offset:56320
	global_load_lds_dwordx4 v[218:219], off
	s_add_i32 m0, s16, 0x2000
	s_add_u32 s14, s14, 0x160080
	v_lshl_add_u64 v[218:219], v[220:221], 0, s[4:5]
	s_addc_u32 s15, s15, 0
	s_add_i32 s16, s67, s20
	global_load_lds_dwordx4 v[218:219], off
	v_lshl_add_u64 v[218:219], s[14:15], 0, v[132:133]
	s_mov_b32 m0, s16
	s_nop 0
	global_load_lds_dwordx4 v[218:219], off
	v_lshl_add_u64 v[218:219], s[14:15], 0, v[136:137]
	s_add_i32 m0, s16, 0x2000
	s_nop 0
	global_load_lds_dwordx4 v[218:219], off
	v_lshl_add_u64 v[218:219], v[222:223], 0, s[4:5]
	s_mov_b32 m0, s30
	s_nop 0
	global_load_lds_dwordx4 v[218:219], off
	v_lshl_add_u64 v[218:219], v[224:225], 0, s[4:5]
	s_mov_b32 m0, s31
	s_nop 0
	global_load_lds_dwordx4 v[218:219], off
	s_waitcnt vmcnt(8)
	s_waitcnt lgkmcnt(0)
	s_setprio 1
	s_barrier
	v_mfma_f32_16x16x32_bf16 v[62:65], v[144:147], v[186:189], v[62:65]
	v_mfma_f32_16x16x32_bf16 v[58:61], v[158:161], v[186:189], v[58:61]
	v_mfma_f32_16x16x32_bf16 v[54:57], v[144:147], v[194:197], v[54:57]
	v_mfma_f32_16x16x32_bf16 v[50:53], v[158:161], v[194:197], v[50:53]
	v_mfma_f32_16x16x32_bf16 v[38:41], v[144:147], v[202:205], v[38:41]
	v_mfma_f32_16x16x32_bf16 v[34:37], v[158:161], v[202:205], v[34:37]
	v_mfma_f32_16x16x32_bf16 v[22:25], v[144:147], v[210:213], v[22:25]
	v_mfma_f32_16x16x32_bf16 v[18:21], v[158:161], v[210:213], v[18:21]
	v_mfma_f32_16x16x32_bf16 v[62:65], v[154:157], v[190:193], v[62:65]
	v_mfma_f32_16x16x32_bf16 v[58:61], v[162:165], v[190:193], v[58:61]
	v_mfma_f32_16x16x32_bf16 v[54:57], v[154:157], v[198:201], v[54:57]
	v_mfma_f32_16x16x32_bf16 v[50:53], v[162:165], v[198:201], v[50:53]
	v_mfma_f32_16x16x32_bf16 v[38:41], v[154:157], v[206:209], v[38:41]
	v_mfma_f32_16x16x32_bf16 v[34:37], v[162:165], v[206:209], v[34:37]
	v_mfma_f32_16x16x32_bf16 v[22:25], v[154:157], v[214:217], v[22:25]
	v_mfma_f32_16x16x32_bf16 v[18:21], v[162:165], v[214:217], v[18:21]
	v_mfma_f32_16x16x32_bf16 v[46:49], v[166:169], v[186:189], v[46:49]
	v_mfma_f32_16x16x32_bf16 v[42:45], v[174:177], v[186:189], v[42:45]
	v_mfma_f32_16x16x32_bf16 v[30:33], v[166:169], v[194:197], v[30:33]
	v_mfma_f32_16x16x32_bf16 v[26:29], v[174:177], v[194:197], v[26:29]
	v_mfma_f32_16x16x32_bf16 v[14:17], v[166:169], v[202:205], v[14:17]
	v_mfma_f32_16x16x32_bf16 v[10:13], v[174:177], v[202:205], v[10:13]
	v_mfma_f32_16x16x32_bf16 v[6:9], v[166:169], v[210:213], v[6:9]
	v_mfma_f32_16x16x32_bf16 v[2:5], v[174:177], v[210:213], v[2:5]
	v_mfma_f32_16x16x32_bf16 v[46:49], v[170:173], v[190:193], v[46:49]
	v_mfma_f32_16x16x32_bf16 v[42:45], v[182:185], v[190:193], v[42:45]
	v_mfma_f32_16x16x32_bf16 v[30:33], v[170:173], v[198:201], v[30:33]
	v_mfma_f32_16x16x32_bf16 v[26:29], v[182:185], v[198:201], v[26:29]
	v_mfma_f32_16x16x32_bf16 v[14:17], v[170:173], v[206:209], v[14:17]
	v_mfma_f32_16x16x32_bf16 v[10:13], v[182:185], v[206:209], v[10:13]
	v_mfma_f32_16x16x32_bf16 v[6:9], v[170:173], v[214:217], v[6:9]
	v_mfma_f32_16x16x32_bf16 v[2:5], v[182:185], v[214:217], v[2:5]
	s_barrier
	s_setprio 0
	s_add_u32 s12, s12, 0x100
	s_addc_u32 s13, s13, 0
	s_add_u32 s60, s60, 0x100
	s_addc_u32 s62, s62, 0
	s_cmp_ge_i32 s63, s58
	s_mov_b32 s14, s63
	s_cbranch_scc0 .LBB0_854
	s_and_b64 vcc, exec, s[6:7]
	s_cbranch_vccz .LBB0_857
	s_barrier

.LBB0_1037:
	ds_read_b128 v[150:153], v170
	ds_read_b128 v[154:157], v170 offset:1024
	ds_read_b128 v[158:161], v170 offset:2048
	ds_read_b128 v[182:185], v170 offset:3072
	ds_read_b128 v[186:189], v171
	ds_read_b128 v[190:193], v171 offset:1024
	ds_read_b128 v[194:197], v171 offset:2048
	ds_read_b128 v[198:201], v171 offset:3072
	s_add_u32 s34, s4, 0xfff80080
	s_addc_u32 s35, s5, -1
	s_cmp_eq_u32 s69, 28
	s_cselect_b32 s37, s9, s35
	s_cselect_b32 s36, s14, s34
	s_cselect_b32 s35, s23, s68
	s_cselect_b32 s34, s27, s67
	v_lshl_add_u64 v[176:177], s[4:5], 0, v[142:143]
	s_add_i32 m0, s13, 0xc000
	ds_read_b128 v[202:205], v172
	ds_read_b128 v[206:209], v172 offset:1024
	ds_read_b128 v[210:213], v172 offset:2048
	ds_read_b128 v[214:217], v172 offset:3072
	ds_read_b128 v[218:221], v172 offset:4096
	ds_read_b128 v[222:225], v172 offset:5120
	ds_read_b128 v[226:229], v172 offset:6144
	ds_read_b128 v[230:233], v172 offset:7168
	global_load_lds_dwordx4 v[176:177], off
	v_lshl_add_u64 v[176:177], s[4:5], 0, v[144:145]
	s_add_i32 m0, s13, 0xe000
	s_nop 0
	global_load_lds_dwordx4 v[176:177], off
	s_waitcnt vmcnt(8)
	s_waitcnt lgkmcnt(0)
	s_setprio 1
	s_barrier
	v_mfma_f32_16x16x32_bf16 v[126:129], v[150:153], v[202:205], v[126:129]
	v_mfma_f32_16x16x32_bf16 v[122:125], v[158:161], v[202:205], v[122:125]
	v_mfma_f32_16x16x32_bf16 v[110:113], v[150:153], v[210:213], v[110:113]
	v_mfma_f32_16x16x32_bf16 v[106:109], v[158:161], v[210:213], v[106:109]
	v_mfma_f32_16x16x32_bf16 v[94:97], v[150:153], v[218:221], v[94:97]
	v_mfma_f32_16x16x32_bf16 v[90:93], v[158:161], v[218:221], v[90:93]
	v_mfma_f32_16x16x32_bf16 v[78:81], v[150:153], v[226:229], v[78:81]
	v_mfma_f32_16x16x32_bf16 v[74:77], v[158:161], v[226:229], v[74:77]
	v_mfma_f32_16x16x32_bf16 v[126:129], v[154:157], v[206:209], v[126:129]
	v_mfma_f32_16x16x32_bf16 v[122:125], v[182:185], v[206:209], v[122:125]
	v_mfma_f32_16x16x32_bf16 v[110:113], v[154:157], v[214:217], v[110:113]
	v_mfma_f32_16x16x32_bf16 v[106:109], v[182:185], v[214:217], v[106:109]
	v_mfma_f32_16x16x32_bf16 v[94:97], v[154:157], v[222:225], v[94:97]
	v_mfma_f32_16x16x32_bf16 v[90:93], v[182:185], v[222:225], v[90:93]
	v_mfma_f32_16x16x32_bf16 v[78:81], v[154:157], v[230:233], v[78:81]
	v_mfma_f32_16x16x32_bf16 v[74:77], v[182:185], v[230:233], v[74:77]
	v_mfma_f32_16x16x32_bf16 v[118:121], v[186:189], v[202:205], v[118:121]
	v_mfma_f32_16x16x32_bf16 v[114:117], v[194:197], v[202:205], v[114:117]
	v_mfma_f32_16x16x32_bf16 v[102:105], v[186:189], v[210:213], v[102:105]
	v_mfma_f32_16x16x32_bf16 v[98:101], v[194:197], v[210:213], v[98:101]
	v_mfma_f32_16x16x32_bf16 v[86:89], v[186:189], v[218:221], v[86:89]
	v_mfma_f32_16x16x32_bf16 v[82:85], v[194:197], v[218:221], v[82:85]
	v_mfma_f32_16x16x32_bf16 v[70:73], v[186:189], v[226:229], v[70:73]
	v_mfma_f32_16x16x32_bf16 v[66:69], v[194:197], v[226:229], v[66:69]
	v_mfma_f32_16x16x32_bf16 v[118:121], v[190:193], v[206:209], v[118:121]
	v_mfma_f32_16x16x32_bf16 v[114:117], v[198:201], v[206:209], v[114:117]
	v_mfma_f32_16x16x32_bf16 v[102:105], v[190:193], v[214:217], v[102:105]
	v_mfma_f32_16x16x32_bf16 v[98:101], v[198:201], v[214:217], v[98:101]
	v_mfma_f32_16x16x32_bf16 v[86:89], v[190:193], v[222:225], v[86:89]
	v_mfma_f32_16x16x32_bf16 v[82:85], v[198:201], v[222:225], v[82:85]
	v_mfma_f32_16x16x32_bf16 v[70:73], v[190:193], v[230:233], v[70:73]
	v_mfma_f32_16x16x32_bf16 v[66:69], v[198:201], v[230:233], v[66:69]
	s_barrier
	s_setprio 0
	s_add_i32 s70, s62, s52
	v_lshl_add_u64 v[176:177], s[34:35], 0, v[132:133]
	s_mov_b32 m0, s70
	ds_read_b128 v[202:205], v172 offset:16384
	ds_read_b128 v[206:209], v172 offset:17408
	ds_read_b128 v[210:213], v172 offset:18432
	ds_read_b128 v[214:217], v172 offset:19456
	ds_read_b128 v[218:221], v172 offset:20480
	ds_read_b128 v[222:225], v172 offset:21504
	ds_read_b128 v[226:229], v172 offset:22528
	ds_read_b128 v[230:233], v172 offset:23552
	global_load_lds_dwordx4 v[176:177], off
	s_add_i32 m0, s70, 0x2000
	s_add_u32 s70, s34, 0x80000
	v_lshl_add_u64 v[234:235], s[34:35], 0, v[136:137]
	s_addc_u32 s71, s35, 0
	s_add_i32 s72, s63, s52
	global_load_lds_dwordx4 v[234:235], off
	v_lshl_add_u64 v[236:237], s[70:71], 0, v[132:133]
	s_mov_b32 m0, s72
	v_lshl_add_u64 v[238:239], s[36:37], 0, v[134:135]
	global_load_lds_dwordx4 v[236:237], off
	v_lshl_add_u64 v[236:237], s[70:71], 0, v[136:137]
	s_add_i32 m0, s72, 0x2000
	s_nop 0
	global_load_lds_dwordx4 v[236:237], off
	v_lshl_add_u64 v[236:237], s[36:37], 0, v[130:131]
	s_mov_b32 m0, s13
	s_nop 0
	global_load_lds_dwordx4 v[236:237], off
	s_mov_b32 m0, s53
	s_nop 0
	global_load_lds_dwordx4 v[238:239], off
	s_waitcnt vmcnt(8)
	s_waitcnt lgkmcnt(0)
	s_setprio 1
	s_barrier
	v_mfma_f32_16x16x32_bf16 v[62:65], v[150:153], v[202:205], v[62:65]
	v_mfma_f32_16x16x32_bf16 v[58:61], v[158:161], v[202:205], v[58:61]
	v_mfma_f32_16x16x32_bf16 v[46:49], v[150:153], v[210:213], v[46:49]
	v_mfma_f32_16x16x32_bf16 v[42:45], v[158:161], v[210:213], v[42:45]
	v_mfma_f32_16x16x32_bf16 v[30:33], v[150:153], v[218:221], v[30:33]
	v_mfma_f32_16x16x32_bf16 v[26:29], v[158:161], v[218:221], v[26:29]
	v_mfma_f32_16x16x32_bf16 v[14:17], v[150:153], v[226:229], v[14:17]
	v_mfma_f32_16x16x32_bf16 v[10:13], v[158:161], v[226:229], v[10:13]
	v_mfma_f32_16x16x32_bf16 v[62:65], v[154:157], v[206:209], v[62:65]
	v_mfma_f32_16x16x32_bf16 v[58:61], v[182:185], v[206:209], v[58:61]
	v_mfma_f32_16x16x32_bf16 v[46:49], v[154:157], v[214:217], v[46:49]
	v_mfma_f32_16x16x32_bf16 v[42:45], v[182:185], v[214:217], v[42:45]
	v_mfma_f32_16x16x32_bf16 v[30:33], v[154:157], v[222:225], v[30:33]
	v_mfma_f32_16x16x32_bf16 v[26:29], v[182:185], v[222:225], v[26:29]
	v_mfma_f32_16x16x32_bf16 v[14:17], v[154:157], v[230:233], v[14:17]
	v_mfma_f32_16x16x32_bf16 v[10:13], v[182:185], v[230:233], v[10:13]
	v_mfma_f32_16x16x32_bf16 v[54:57], v[186:189], v[202:205], v[54:57]
	v_mfma_f32_16x16x32_bf16 v[50:53], v[194:197], v[202:205], v[50:53]
	v_mfma_f32_16x16x32_bf16 v[38:41], v[186:189], v[210:213], v[38:41]
	v_mfma_f32_16x16x32_bf16 v[34:37], v[194:197], v[210:213], v[34:37]
	v_mfma_f32_16x16x32_bf16 v[22:25], v[186:189], v[218:221], v[22:25]
	v_mfma_f32_16x16x32_bf16 v[18:21], v[194:197], v[218:221], v[18:21]
	v_mfma_f32_16x16x32_bf16 v[6:9], v[186:189], v[226:229], v[6:9]
	v_mfma_f32_16x16x32_bf16 v[2:5], v[194:197], v[226:229], v[2:5]
	v_mfma_f32_16x16x32_bf16 v[54:57], v[190:193], v[206:209], v[54:57]
	v_mfma_f32_16x16x32_bf16 v[50:53], v[198:201], v[206:209], v[50:53]
	v_mfma_f32_16x16x32_bf16 v[38:41], v[190:193], v[214:217], v[38:41]
	v_mfma_f32_16x16x32_bf16 v[34:37], v[198:201], v[214:217], v[34:37]
	v_mfma_f32_16x16x32_bf16 v[22:25], v[190:193], v[222:225], v[22:25]
	v_mfma_f32_16x16x32_bf16 v[18:21], v[198:201], v[222:225], v[18:21]
	v_mfma_f32_16x16x32_bf16 v[6:9], v[190:193], v[230:233], v[6:9]
	v_mfma_f32_16x16x32_bf16 v[2:5], v[198:201], v[230:233], v[2:5]
	s_barrier
	s_setprio 0
	s_add_i32 s70, 0, 0x18000
	v_add_u32_e32 v175, s70, v164
	s_add_i32 s71, 0, 0x1c000
	ds_read_b128 v[150:153], v175
	ds_read_b128 v[154:157], v175 offset:1024
	ds_read_b128 v[158:161], v175 offset:2048
	ds_read_b128 v[182:185], v175 offset:3072
	v_add_u32_e32 v175, s71, v164
	ds_read_b128 v[186:189], v175
	ds_read_b128 v[190:193], v175 offset:1024
	ds_read_b128 v[194:197], v175 offset:2048
	ds_read_b128 v[198:201], v175 offset:3072
	s_add_u32 s36, s36, 0x80000
	s_addc_u32 s37, s37, 0
	s_mov_b32 m0, s54
	v_lshl_add_u64 v[240:241], s[36:37], 0, v[130:131]
	ds_read_b128 v[202:205], v172 offset:32768
	ds_read_b128 v[206:209], v172 offset:33792
	ds_read_b128 v[210:213], v172 offset:34816
	ds_read_b128 v[214:217], v172 offset:35840
	ds_read_b128 v[218:221], v172 offset:36864
	ds_read_b128 v[222:225], v172 offset:37888
	ds_read_b128 v[226:229], v172 offset:38912
	ds_read_b128 v[230:233], v172 offset:39936
	global_load_lds_dwordx4 v[240:241], off
	v_lshl_add_u64 v[240:241], s[36:37], 0, v[134:135]
	s_mov_b32 m0, s55
	s_nop 0
	global_load_lds_dwordx4 v[240:241], off
	s_waitcnt vmcnt(8)
	s_waitcnt lgkmcnt(0)
	s_setprio 1
	s_barrier
	v_mfma_f32_16x16x32_bf16 v[126:129], v[150:153], v[202:205], v[126:129]
	v_mfma_f32_16x16x32_bf16 v[122:125], v[158:161], v[202:205], v[122:125]
	v_mfma_f32_16x16x32_bf16 v[110:113], v[150:153], v[210:213], v[110:113]
	v_mfma_f32_16x16x32_bf16 v[106:109], v[158:161], v[210:213], v[106:109]
	v_mfma_f32_16x16x32_bf16 v[94:97], v[150:153], v[218:221], v[94:97]
	v_mfma_f32_16x16x32_bf16 v[90:93], v[158:161], v[218:221], v[90:93]
	v_mfma_f32_16x16x32_bf16 v[78:81], v[150:153], v[226:229], v[78:81]
	v_mfma_f32_16x16x32_bf16 v[74:77], v[158:161], v[226:229], v[74:77]
	v_mfma_f32_16x16x32_bf16 v[126:129], v[154:157], v[206:209], v[126:129]
	v_mfma_f32_16x16x32_bf16 v[122:125], v[182:185], v[206:209], v[122:125]
	v_mfma_f32_16x16x32_bf16 v[110:113], v[154:157], v[214:217], v[110:113]
	v_mfma_f32_16x16x32_bf16 v[106:109], v[182:185], v[214:217], v[106:109]
	v_mfma_f32_16x16x32_bf16 v[94:97], v[154:157], v[222:225], v[94:97]
	v_mfma_f32_16x16x32_bf16 v[90:93], v[182:185], v[222:225], v[90:93]
	v_mfma_f32_16x16x32_bf16 v[78:81], v[154:157], v[230:233], v[78:81]
	v_mfma_f32_16x16x32_bf16 v[74:77], v[182:185], v[230:233], v[74:77]
	v_mfma_f32_16x16x32_bf16 v[118:121], v[186:189], v[202:205], v[118:121]
	v_mfma_f32_16x16x32_bf16 v[114:117], v[194:197], v[202:205], v[114:117]
	v_mfma_f32_16x16x32_bf16 v[102:105], v[186:189], v[210:213], v[102:105]
	v_mfma_f32_16x16x32_bf16 v[98:101], v[194:197], v[210:213], v[98:101]
	v_mfma_f32_16x16x32_bf16 v[86:89], v[186:189], v[218:221], v[86:89]
	v_mfma_f32_16x16x32_bf16 v[82:85], v[194:197], v[218:221], v[82:85]
	v_mfma_f32_16x16x32_bf16 v[70:73], v[186:189], v[226:229], v[70:73]
	v_mfma_f32_16x16x32_bf16 v[66:69], v[194:197], v[226:229], v[66:69]
	v_mfma_f32_16x16x32_bf16 v[118:121], v[190:193], v[206:209], v[118:121]
	v_mfma_f32_16x16x32_bf16 v[114:117], v[198:201], v[206:209], v[114:117]
	v_mfma_f32_16x16x32_bf16 v[102:105], v[190:193], v[214:217], v[102:105]
	v_mfma_f32_16x16x32_bf16 v[98:101], v[198:201], v[214:217], v[98:101]
	v_mfma_f32_16x16x32_bf16 v[86:89], v[190:193], v[222:225], v[86:89]
	v_mfma_f32_16x16x32_bf16 v[82:85], v[198:201], v[222:225], v[82:85]
	v_mfma_f32_16x16x32_bf16 v[70:73], v[190:193], v[230:233], v[70:73]
	v_mfma_f32_16x16x32_bf16 v[66:69], v[198:201], v[230:233], v[66:69]
	s_barrier
	s_setprio 0
	s_add_i32 s36, s70, s52
	v_lshl_add_u64 v[176:177], v[176:177], 0, s[16:17]
	s_mov_b32 m0, s36
	ds_read_b128 v[202:205], v172 offset:49152
	ds_read_b128 v[206:209], v172 offset:50176
	ds_read_b128 v[210:213], v172 offset:51200
	ds_read_b128 v[214:217], v172 offset:52224
	ds_read_b128 v[218:221], v172 offset:53248
	ds_read_b128 v[222:225], v172 offset:54272
	ds_read_b128 v[226:229], v172 offset:55296
	ds_read_b128 v[230:233], v172 offset:56320
	global_load_lds_dwordx4 v[176:177], off
	s_add_i32 m0, s36, 0x2000
	s_add_u32 s34, s34, 0x80080
	v_lshl_add_u64 v[176:177], v[234:235], 0, s[16:17]
	s_addc_u32 s35, s35, 0
	s_add_i32 s36, s71, s52
	global_load_lds_dwordx4 v[176:177], off
	v_lshl_add_u64 v[176:177], s[34:35], 0, v[132:133]
	s_mov_b32 m0, s36
	s_nop 0
	global_load_lds_dwordx4 v[176:177], off
	v_lshl_add_u64 v[176:177], s[34:35], 0, v[136:137]
	s_add_i32 m0, s36, 0x2000
	s_nop 0
	global_load_lds_dwordx4 v[176:177], off
	v_lshl_add_u64 v[176:177], v[236:237], 0, s[16:17]
	s_mov_b32 m0, s56
	s_nop 0
	global_load_lds_dwordx4 v[176:177], off
	v_lshl_add_u64 v[176:177], v[238:239], 0, s[16:17]
	s_mov_b32 m0, s57
	s_nop 0
	global_load_lds_dwordx4 v[176:177], off
	s_waitcnt vmcnt(8)
	s_waitcnt lgkmcnt(0)
	s_setprio 1
	s_barrier
	v_mfma_f32_16x16x32_bf16 v[62:65], v[150:153], v[202:205], v[62:65]
	v_mfma_f32_16x16x32_bf16 v[58:61], v[158:161], v[202:205], v[58:61]
	v_mfma_f32_16x16x32_bf16 v[46:49], v[150:153], v[210:213], v[46:49]
	v_mfma_f32_16x16x32_bf16 v[42:45], v[158:161], v[210:213], v[42:45]
	v_mfma_f32_16x16x32_bf16 v[30:33], v[150:153], v[218:221], v[30:33]
	v_mfma_f32_16x16x32_bf16 v[26:29], v[158:161], v[218:221], v[26:29]
	v_mfma_f32_16x16x32_bf16 v[14:17], v[150:153], v[226:229], v[14:17]
	v_mfma_f32_16x16x32_bf16 v[10:13], v[158:161], v[226:229], v[10:13]
	v_mfma_f32_16x16x32_bf16 v[62:65], v[154:157], v[206:209], v[62:65]
	v_mfma_f32_16x16x32_bf16 v[58:61], v[182:185], v[206:209], v[58:61]
	v_mfma_f32_16x16x32_bf16 v[46:49], v[154:157], v[214:217], v[46:49]
	v_mfma_f32_16x16x32_bf16 v[42:45], v[182:185], v[214:217], v[42:45]
	v_mfma_f32_16x16x32_bf16 v[30:33], v[154:157], v[222:225], v[30:33]
	v_mfma_f32_16x16x32_bf16 v[26:29], v[182:185], v[222:225], v[26:29]
	v_mfma_f32_16x16x32_bf16 v[14:17], v[154:157], v[230:233], v[14:17]
	v_mfma_f32_16x16x32_bf16 v[10:13], v[182:185], v[230:233], v[10:13]
	v_mfma_f32_16x16x32_bf16 v[54:57], v[186:189], v[202:205], v[54:57]
	v_mfma_f32_16x16x32_bf16 v[50:53], v[194:197], v[202:205], v[50:53]
	v_mfma_f32_16x16x32_bf16 v[38:41], v[186:189], v[210:213], v[38:41]
	v_mfma_f32_16x16x32_bf16 v[34:37], v[194:197], v[210:213], v[34:37]
	v_mfma_f32_16x16x32_bf16 v[22:25], v[186:189], v[218:221], v[22:25]
	v_mfma_f32_16x16x32_bf16 v[18:21], v[194:197], v[218:221], v[18:21]
	v_mfma_f32_16x16x32_bf16 v[6:9], v[186:189], v[226:229], v[6:9]
	v_mfma_f32_16x16x32_bf16 v[2:5], v[194:197], v[226:229], v[2:5]
	v_mfma_f32_16x16x32_bf16 v[54:57], v[190:193], v[206:209], v[54:57]
	v_mfma_f32_16x16x32_bf16 v[50:53], v[198:201], v[206:209], v[50:53]
	v_mfma_f32_16x16x32_bf16 v[38:41], v[190:193], v[214:217], v[38:41]
	v_mfma_f32_16x16x32_bf16 v[34:37], v[198:201], v[214:217], v[34:37]
	v_mfma_f32_16x16x32_bf16 v[22:25], v[190:193], v[222:225], v[22:25]
	v_mfma_f32_16x16x32_bf16 v[18:21], v[198:201], v[222:225], v[18:21]
	v_mfma_f32_16x16x32_bf16 v[6:9], v[190:193], v[230:233], v[6:9]
	v_mfma_f32_16x16x32_bf16 v[2:5], v[198:201], v[230:233], v[2:5]
	s_barrier
	s_setprio 0
	s_add_i32 s69, s69, 2
	s_add_u32 s4, s4, 0x100
	s_addc_u32 s5, s5, 0
	s_add_u32 s67, s67, 0x100
	s_addc_u32 s68, s68, 0
	s_cmp_gt_u32 s69, 29
	s_cbranch_scc0 .LBB0_1037
	s_and_b64 vcc, exec, s[18:19]
	s_cbranch_vccz .LBB0_1040
	s_barrier

.LBB0_1637:
	ds_read_b128 v[154:157], v150
	ds_read_b128 v[158:161], v150 offset:1024
	ds_read_b128 v[162:165], v150 offset:2048
	ds_read_b128 v[166:169], v150 offset:3072
	ds_read_b128 v[170:173], v151
	ds_read_b128 v[174:177], v151 offset:1024
	ds_read_b128 v[182:185], v151 offset:2048
	ds_read_b128 v[186:189], v151 offset:3072
	s_add_u32 s20, s18, 0xfff80080
	s_addc_u32 s21, s19, -1
	s_cmp_eq_u32 s63, 28
	s_cselect_b32 s23, s11, s21
	s_cselect_b32 s22, s58, s20
	s_cselect_b32 s21, s9, s62
	s_cselect_b32 s20, s59, s60
	v_lshl_add_u64 v[146:147], s[18:19], 0, v[138:139]
	s_add_i32 m0, s17, 0xc000
	ds_read_b128 v[190:193], v152
	ds_read_b128 v[194:197], v152 offset:1024
	ds_read_b128 v[198:201], v152 offset:2048
	ds_read_b128 v[202:205], v152 offset:3072
	ds_read_b128 v[206:209], v152 offset:4096
	ds_read_b128 v[210:213], v152 offset:5120
	ds_read_b128 v[214:217], v152 offset:6144
	ds_read_b128 v[218:221], v152 offset:7168
	global_load_lds_dwordx4 v[146:147], off
	v_lshl_add_u64 v[146:147], s[18:19], 0, v[140:141]
	s_add_i32 m0, s17, 0xe000
	s_nop 0
	global_load_lds_dwordx4 v[146:147], off
	s_waitcnt vmcnt(8)
	s_waitcnt lgkmcnt(0)
	s_setprio 1
	s_barrier
	v_mfma_f32_16x16x32_bf16 v[126:129], v[154:157], v[190:193], v[126:129]
	v_mfma_f32_16x16x32_bf16 v[122:125], v[162:165], v[190:193], v[122:125]
	v_mfma_f32_16x16x32_bf16 v[110:113], v[154:157], v[198:201], v[110:113]
	v_mfma_f32_16x16x32_bf16 v[106:109], v[162:165], v[198:201], v[106:109]
	v_mfma_f32_16x16x32_bf16 v[94:97], v[154:157], v[206:209], v[94:97]
	v_mfma_f32_16x16x32_bf16 v[90:93], v[162:165], v[206:209], v[90:93]
	v_mfma_f32_16x16x32_bf16 v[78:81], v[154:157], v[214:217], v[78:81]
	v_mfma_f32_16x16x32_bf16 v[74:77], v[162:165], v[214:217], v[74:77]
	v_mfma_f32_16x16x32_bf16 v[126:129], v[158:161], v[194:197], v[126:129]
	v_mfma_f32_16x16x32_bf16 v[122:125], v[166:169], v[194:197], v[122:125]
	v_mfma_f32_16x16x32_bf16 v[110:113], v[158:161], v[202:205], v[110:113]
	v_mfma_f32_16x16x32_bf16 v[106:109], v[166:169], v[202:205], v[106:109]
	v_mfma_f32_16x16x32_bf16 v[94:97], v[158:161], v[210:213], v[94:97]
	v_mfma_f32_16x16x32_bf16 v[90:93], v[166:169], v[210:213], v[90:93]
	v_mfma_f32_16x16x32_bf16 v[78:81], v[158:161], v[218:221], v[78:81]
	v_mfma_f32_16x16x32_bf16 v[74:77], v[166:169], v[218:221], v[74:77]
	v_mfma_f32_16x16x32_bf16 v[118:121], v[170:173], v[190:193], v[118:121]
	v_mfma_f32_16x16x32_bf16 v[114:117], v[182:185], v[190:193], v[114:117]
	v_mfma_f32_16x16x32_bf16 v[102:105], v[170:173], v[198:201], v[102:105]
	v_mfma_f32_16x16x32_bf16 v[98:101], v[182:185], v[198:201], v[98:101]
	v_mfma_f32_16x16x32_bf16 v[86:89], v[170:173], v[206:209], v[86:89]
	v_mfma_f32_16x16x32_bf16 v[82:85], v[182:185], v[206:209], v[82:85]
	v_mfma_f32_16x16x32_bf16 v[70:73], v[170:173], v[214:217], v[70:73]
	v_mfma_f32_16x16x32_bf16 v[66:69], v[182:185], v[214:217], v[66:69]
	v_mfma_f32_16x16x32_bf16 v[118:121], v[174:177], v[194:197], v[118:121]
	v_mfma_f32_16x16x32_bf16 v[114:117], v[186:189], v[194:197], v[114:117]
	v_mfma_f32_16x16x32_bf16 v[102:105], v[174:177], v[202:205], v[102:105]
	v_mfma_f32_16x16x32_bf16 v[98:101], v[186:189], v[202:205], v[98:101]
	v_mfma_f32_16x16x32_bf16 v[86:89], v[174:177], v[210:213], v[86:89]
	v_mfma_f32_16x16x32_bf16 v[82:85], v[186:189], v[210:213], v[82:85]
	v_mfma_f32_16x16x32_bf16 v[70:73], v[174:177], v[218:221], v[70:73]
	v_mfma_f32_16x16x32_bf16 v[66:69], v[186:189], v[218:221], v[66:69]
	s_barrier
	s_setprio 0
	s_add_i32 s66, s54, s28
	v_lshl_add_u64 v[146:147], s[20:21], 0, v[134:135]
	s_mov_b32 m0, s66
	ds_read_b128 v[190:193], v152 offset:16384
	ds_read_b128 v[194:197], v152 offset:17408
	ds_read_b128 v[198:201], v152 offset:18432
	ds_read_b128 v[202:205], v152 offset:19456
	ds_read_b128 v[206:209], v152 offset:20480
	ds_read_b128 v[210:213], v152 offset:21504
	ds_read_b128 v[214:217], v152 offset:22528
	ds_read_b128 v[218:221], v152 offset:23552
	global_load_lds_dwordx4 v[146:147], off
	s_add_i32 m0, s66, 0x2000
	s_add_u32 s66, s20, 0x80000
	v_lshl_add_u64 v[222:223], s[20:21], 0, v[130:131]
	s_addc_u32 s67, s21, 0
	s_add_i32 s68, s55, s28
	global_load_lds_dwordx4 v[222:223], off
	v_lshl_add_u64 v[224:225], s[66:67], 0, v[134:135]
	s_mov_b32 m0, s68
	v_lshl_add_u64 v[226:227], s[22:23], 0, v[132:133]
	global_load_lds_dwordx4 v[224:225], off
	v_lshl_add_u64 v[224:225], s[66:67], 0, v[130:131]
	s_add_i32 m0, s68, 0x2000
	s_nop 0
	global_load_lds_dwordx4 v[224:225], off
	v_lshl_add_u64 v[224:225], s[22:23], 0, v[136:137]
	s_mov_b32 m0, s17
	s_nop 0
	global_load_lds_dwordx4 v[224:225], off
	s_mov_b32 m0, s31
	s_nop 0
	global_load_lds_dwordx4 v[226:227], off
	s_waitcnt vmcnt(8)
	s_waitcnt lgkmcnt(0)
	s_setprio 1
	s_barrier
	v_mfma_f32_16x16x32_bf16 v[62:65], v[154:157], v[190:193], v[62:65]
	v_mfma_f32_16x16x32_bf16 v[58:61], v[162:165], v[190:193], v[58:61]
	v_mfma_f32_16x16x32_bf16 v[46:49], v[154:157], v[198:201], v[46:49]
	v_mfma_f32_16x16x32_bf16 v[42:45], v[162:165], v[198:201], v[42:45]
	v_mfma_f32_16x16x32_bf16 v[30:33], v[154:157], v[206:209], v[30:33]
	v_mfma_f32_16x16x32_bf16 v[26:29], v[162:165], v[206:209], v[26:29]
	v_mfma_f32_16x16x32_bf16 v[14:17], v[154:157], v[214:217], v[14:17]
	v_mfma_f32_16x16x32_bf16 v[10:13], v[162:165], v[214:217], v[10:13]
	v_mfma_f32_16x16x32_bf16 v[62:65], v[158:161], v[194:197], v[62:65]
	v_mfma_f32_16x16x32_bf16 v[58:61], v[166:169], v[194:197], v[58:61]
	v_mfma_f32_16x16x32_bf16 v[46:49], v[158:161], v[202:205], v[46:49]
	v_mfma_f32_16x16x32_bf16 v[42:45], v[166:169], v[202:205], v[42:45]
	v_mfma_f32_16x16x32_bf16 v[30:33], v[158:161], v[210:213], v[30:33]
	v_mfma_f32_16x16x32_bf16 v[26:29], v[166:169], v[210:213], v[26:29]
	v_mfma_f32_16x16x32_bf16 v[14:17], v[158:161], v[218:221], v[14:17]
	v_mfma_f32_16x16x32_bf16 v[10:13], v[166:169], v[218:221], v[10:13]
	v_mfma_f32_16x16x32_bf16 v[54:57], v[170:173], v[190:193], v[54:57]
	v_mfma_f32_16x16x32_bf16 v[50:53], v[182:185], v[190:193], v[50:53]
	v_mfma_f32_16x16x32_bf16 v[38:41], v[170:173], v[198:201], v[38:41]
	v_mfma_f32_16x16x32_bf16 v[34:37], v[182:185], v[198:201], v[34:37]
	v_mfma_f32_16x16x32_bf16 v[22:25], v[170:173], v[206:209], v[22:25]
	v_mfma_f32_16x16x32_bf16 v[18:21], v[182:185], v[206:209], v[18:21]
	v_mfma_f32_16x16x32_bf16 v[6:9], v[170:173], v[214:217], v[6:9]
	v_mfma_f32_16x16x32_bf16 v[2:5], v[182:185], v[214:217], v[2:5]
	v_mfma_f32_16x16x32_bf16 v[54:57], v[174:177], v[194:197], v[54:57]
	v_mfma_f32_16x16x32_bf16 v[50:53], v[186:189], v[194:197], v[50:53]
	v_mfma_f32_16x16x32_bf16 v[38:41], v[174:177], v[202:205], v[38:41]
	v_mfma_f32_16x16x32_bf16 v[34:37], v[186:189], v[202:205], v[34:37]
	v_mfma_f32_16x16x32_bf16 v[22:25], v[174:177], v[210:213], v[22:25]
	v_mfma_f32_16x16x32_bf16 v[18:21], v[186:189], v[210:213], v[18:21]
	v_mfma_f32_16x16x32_bf16 v[6:9], v[174:177], v[218:221], v[6:9]
	v_mfma_f32_16x16x32_bf16 v[2:5], v[186:189], v[218:221], v[2:5]
	s_barrier
	s_setprio 0
	s_add_i32 s66, 0, 0x18000
	v_add_u32_e32 v153, s66, v148
	s_add_i32 s67, 0, 0x1c000
	ds_read_b128 v[154:157], v153
	ds_read_b128 v[158:161], v153 offset:1024
	ds_read_b128 v[162:165], v153 offset:2048
	ds_read_b128 v[166:169], v153 offset:3072
	v_add_u32_e32 v153, s67, v148
	ds_read_b128 v[170:173], v153
	ds_read_b128 v[174:177], v153 offset:1024
	ds_read_b128 v[182:185], v153 offset:2048
	ds_read_b128 v[186:189], v153 offset:3072
	s_add_u32 s22, s22, 0x80000
	s_addc_u32 s23, s23, 0
	s_mov_b32 m0, s34
	v_lshl_add_u64 v[228:229], s[22:23], 0, v[136:137]
	ds_read_b128 v[190:193], v152 offset:32768
	ds_read_b128 v[194:197], v152 offset:33792
	ds_read_b128 v[198:201], v152 offset:34816
	ds_read_b128 v[202:205], v152 offset:35840
	ds_read_b128 v[206:209], v152 offset:36864
	ds_read_b128 v[210:213], v152 offset:37888
	ds_read_b128 v[214:217], v152 offset:38912
	ds_read_b128 v[218:221], v152 offset:39936
	global_load_lds_dwordx4 v[228:229], off
	v_lshl_add_u64 v[228:229], s[22:23], 0, v[132:133]
	s_mov_b32 m0, s35
	s_nop 0
	global_load_lds_dwordx4 v[228:229], off
	s_waitcnt vmcnt(8)
	s_waitcnt lgkmcnt(0)
	s_setprio 1
	s_barrier
	v_mfma_f32_16x16x32_bf16 v[126:129], v[154:157], v[190:193], v[126:129]
	v_mfma_f32_16x16x32_bf16 v[122:125], v[162:165], v[190:193], v[122:125]
	v_mfma_f32_16x16x32_bf16 v[110:113], v[154:157], v[198:201], v[110:113]
	v_mfma_f32_16x16x32_bf16 v[106:109], v[162:165], v[198:201], v[106:109]
	v_mfma_f32_16x16x32_bf16 v[94:97], v[154:157], v[206:209], v[94:97]
	v_mfma_f32_16x16x32_bf16 v[90:93], v[162:165], v[206:209], v[90:93]
	v_mfma_f32_16x16x32_bf16 v[78:81], v[154:157], v[214:217], v[78:81]
	v_mfma_f32_16x16x32_bf16 v[74:77], v[162:165], v[214:217], v[74:77]
	v_mfma_f32_16x16x32_bf16 v[126:129], v[158:161], v[194:197], v[126:129]
	v_mfma_f32_16x16x32_bf16 v[122:125], v[166:169], v[194:197], v[122:125]
	v_mfma_f32_16x16x32_bf16 v[110:113], v[158:161], v[202:205], v[110:113]
	v_mfma_f32_16x16x32_bf16 v[106:109], v[166:169], v[202:205], v[106:109]
	v_mfma_f32_16x16x32_bf16 v[94:97], v[158:161], v[210:213], v[94:97]
	v_mfma_f32_16x16x32_bf16 v[90:93], v[166:169], v[210:213], v[90:93]
	v_mfma_f32_16x16x32_bf16 v[78:81], v[158:161], v[218:221], v[78:81]
	v_mfma_f32_16x16x32_bf16 v[74:77], v[166:169], v[218:221], v[74:77]
	v_mfma_f32_16x16x32_bf16 v[118:121], v[170:173], v[190:193], v[118:121]
	v_mfma_f32_16x16x32_bf16 v[114:117], v[182:185], v[190:193], v[114:117]
	v_mfma_f32_16x16x32_bf16 v[102:105], v[170:173], v[198:201], v[102:105]
	v_mfma_f32_16x16x32_bf16 v[98:101], v[182:185], v[198:201], v[98:101]
	v_mfma_f32_16x16x32_bf16 v[86:89], v[170:173], v[206:209], v[86:89]
	v_mfma_f32_16x16x32_bf16 v[82:85], v[182:185], v[206:209], v[82:85]
	v_mfma_f32_16x16x32_bf16 v[70:73], v[170:173], v[214:217], v[70:73]
	v_mfma_f32_16x16x32_bf16 v[66:69], v[182:185], v[214:217], v[66:69]
	v_mfma_f32_16x16x32_bf16 v[118:121], v[174:177], v[194:197], v[118:121]
	v_mfma_f32_16x16x32_bf16 v[114:117], v[186:189], v[194:197], v[114:117]
	v_mfma_f32_16x16x32_bf16 v[102:105], v[174:177], v[202:205], v[102:105]
	v_mfma_f32_16x16x32_bf16 v[98:101], v[186:189], v[202:205], v[98:101]
	v_mfma_f32_16x16x32_bf16 v[86:89], v[174:177], v[210:213], v[86:89]
	v_mfma_f32_16x16x32_bf16 v[82:85], v[186:189], v[210:213], v[82:85]
	v_mfma_f32_16x16x32_bf16 v[70:73], v[174:177], v[218:221], v[70:73]
	v_mfma_f32_16x16x32_bf16 v[66:69], v[186:189], v[218:221], v[66:69]
	s_barrier
	s_setprio 0
	s_add_i32 s22, s66, s28
	v_lshl_add_u64 v[146:147], v[146:147], 0, s[4:5]
	s_mov_b32 m0, s22
	ds_read_b128 v[190:193], v152 offset:49152
	ds_read_b128 v[194:197], v152 offset:50176
	ds_read_b128 v[198:201], v152 offset:51200
	ds_read_b128 v[202:205], v152 offset:52224
	ds_read_b128 v[206:209], v152 offset:53248
	ds_read_b128 v[210:213], v152 offset:54272
	ds_read_b128 v[214:217], v152 offset:55296
	ds_read_b128 v[218:221], v152 offset:56320
	global_load_lds_dwordx4 v[146:147], off
	s_add_i32 m0, s22, 0x2000
	s_add_u32 s20, s20, 0x80080
	v_lshl_add_u64 v[146:147], v[222:223], 0, s[4:5]
	s_addc_u32 s21, s21, 0
	s_add_i32 s22, s67, s28
	global_load_lds_dwordx4 v[146:147], off
	v_lshl_add_u64 v[146:147], s[20:21], 0, v[134:135]
	s_mov_b32 m0, s22
	s_nop 0
	global_load_lds_dwordx4 v[146:147], off
	v_lshl_add_u64 v[146:147], s[20:21], 0, v[130:131]
	s_add_i32 m0, s22, 0x2000
	s_nop 0
	global_load_lds_dwordx4 v[146:147], off
	v_lshl_add_u64 v[146:147], v[224:225], 0, s[4:5]
	s_mov_b32 m0, s37
	s_nop 0
	global_load_lds_dwordx4 v[146:147], off
	v_lshl_add_u64 v[146:147], v[226:227], 0, s[4:5]
	s_mov_b32 m0, s52
	s_nop 0
	global_load_lds_dwordx4 v[146:147], off
	s_waitcnt vmcnt(8)
	s_waitcnt lgkmcnt(0)
	s_setprio 1
	s_barrier
	v_mfma_f32_16x16x32_bf16 v[62:65], v[154:157], v[190:193], v[62:65]
	v_mfma_f32_16x16x32_bf16 v[58:61], v[162:165], v[190:193], v[58:61]
	v_mfma_f32_16x16x32_bf16 v[46:49], v[154:157], v[198:201], v[46:49]
	v_mfma_f32_16x16x32_bf16 v[42:45], v[162:165], v[198:201], v[42:45]
	v_mfma_f32_16x16x32_bf16 v[30:33], v[154:157], v[206:209], v[30:33]
	v_mfma_f32_16x16x32_bf16 v[26:29], v[162:165], v[206:209], v[26:29]
	v_mfma_f32_16x16x32_bf16 v[14:17], v[154:157], v[214:217], v[14:17]
	v_mfma_f32_16x16x32_bf16 v[10:13], v[162:165], v[214:217], v[10:13]
	v_mfma_f32_16x16x32_bf16 v[62:65], v[158:161], v[194:197], v[62:65]
	v_mfma_f32_16x16x32_bf16 v[58:61], v[166:169], v[194:197], v[58:61]
	v_mfma_f32_16x16x32_bf16 v[46:49], v[158:161], v[202:205], v[46:49]
	v_mfma_f32_16x16x32_bf16 v[42:45], v[166:169], v[202:205], v[42:45]
	v_mfma_f32_16x16x32_bf16 v[30:33], v[158:161], v[210:213], v[30:33]
	v_mfma_f32_16x16x32_bf16 v[26:29], v[166:169], v[210:213], v[26:29]
	v_mfma_f32_16x16x32_bf16 v[14:17], v[158:161], v[218:221], v[14:17]
	v_mfma_f32_16x16x32_bf16 v[10:13], v[166:169], v[218:221], v[10:13]
	v_mfma_f32_16x16x32_bf16 v[54:57], v[170:173], v[190:193], v[54:57]
	v_mfma_f32_16x16x32_bf16 v[50:53], v[182:185], v[190:193], v[50:53]
	v_mfma_f32_16x16x32_bf16 v[38:41], v[170:173], v[198:201], v[38:41]
	v_mfma_f32_16x16x32_bf16 v[34:37], v[182:185], v[198:201], v[34:37]
	v_mfma_f32_16x16x32_bf16 v[22:25], v[170:173], v[206:209], v[22:25]
	v_mfma_f32_16x16x32_bf16 v[18:21], v[182:185], v[206:209], v[18:21]
	v_mfma_f32_16x16x32_bf16 v[6:9], v[170:173], v[214:217], v[6:9]
	v_mfma_f32_16x16x32_bf16 v[2:5], v[182:185], v[214:217], v[2:5]
	v_mfma_f32_16x16x32_bf16 v[54:57], v[174:177], v[194:197], v[54:57]
	v_mfma_f32_16x16x32_bf16 v[50:53], v[186:189], v[194:197], v[50:53]
	v_mfma_f32_16x16x32_bf16 v[38:41], v[174:177], v[202:205], v[38:41]
	v_mfma_f32_16x16x32_bf16 v[34:37], v[186:189], v[202:205], v[34:37]
	v_mfma_f32_16x16x32_bf16 v[22:25], v[174:177], v[210:213], v[22:25]
	v_mfma_f32_16x16x32_bf16 v[18:21], v[186:189], v[210:213], v[18:21]
	v_mfma_f32_16x16x32_bf16 v[6:9], v[174:177], v[218:221], v[6:9]
	v_mfma_f32_16x16x32_bf16 v[2:5], v[186:189], v[218:221], v[2:5]
	s_barrier
	s_setprio 0
	s_add_i32 s63, s63, 2
	s_add_u32 s18, s18, 0x100
	s_addc_u32 s19, s19, 0
	s_add_u32 s60, s60, 0x100
	s_addc_u32 s62, s62, 0
	s_cmp_gt_u32 s63, 29
	s_cbranch_scc0 .LBB0_1637
	s_and_b64 vcc, exec, s[6:7]
	s_cbranch_vccz .LBB0_1640
	s_barrier

.LBB0_1913:
	ds_read_b128 v[148:151], v172
	ds_read_b128 v[152:155], v172 offset:1024
	ds_read_b128 v[156:159], v172 offset:2048
	ds_read_b128 v[160:163], v172 offset:3072
	ds_read_b128 v[182:185], v173
	ds_read_b128 v[186:189], v173 offset:1024
	ds_read_b128 v[190:193], v173 offset:2048
	ds_read_b128 v[194:197], v173 offset:3072
	s_add_u32 s54, s52, 0xfff80080
	s_addc_u32 s55, s53, -1
	s_cmp_eq_u32 s82, 28
	s_cselect_b32 s57, s9, s55
	s_cselect_b32 s56, s31, s54
	s_cselect_b32 s55, s29, s79
	s_cselect_b32 s54, s77, s78
	v_lshl_add_u64 v[176:177], s[52:53], 0, v[140:141]
	s_add_i32 m0, s59, 0xc000
	ds_read_b128 v[198:201], v174
	ds_read_b128 v[202:205], v174 offset:1024
	ds_read_b128 v[206:209], v174 offset:2048
	ds_read_b128 v[210:213], v174 offset:3072
	ds_read_b128 v[214:217], v174 offset:4096
	ds_read_b128 v[218:221], v174 offset:5120
	ds_read_b128 v[222:225], v174 offset:6144
	ds_read_b128 v[226:229], v174 offset:7168
	global_load_lds_dwordx4 v[176:177], off
	v_lshl_add_u64 v[176:177], s[52:53], 0, v[142:143]
	s_add_i32 m0, s59, 0xe000
	s_nop 0
	global_load_lds_dwordx4 v[176:177], off
	s_waitcnt vmcnt(8)
	s_waitcnt lgkmcnt(0)
	s_setprio 1
	s_barrier
	v_mfma_f32_16x16x32_bf16 v[126:129], v[148:151], v[198:201], v[126:129]
	v_mfma_f32_16x16x32_bf16 v[122:125], v[156:159], v[198:201], v[122:125]
	v_mfma_f32_16x16x32_bf16 v[110:113], v[148:151], v[206:209], v[110:113]
	v_mfma_f32_16x16x32_bf16 v[106:109], v[156:159], v[206:209], v[106:109]
	v_mfma_f32_16x16x32_bf16 v[94:97], v[148:151], v[214:217], v[94:97]
	v_mfma_f32_16x16x32_bf16 v[90:93], v[156:159], v[214:217], v[90:93]
	v_mfma_f32_16x16x32_bf16 v[78:81], v[148:151], v[222:225], v[78:81]
	v_mfma_f32_16x16x32_bf16 v[74:77], v[156:159], v[222:225], v[74:77]
	v_mfma_f32_16x16x32_bf16 v[126:129], v[152:155], v[202:205], v[126:129]
	v_mfma_f32_16x16x32_bf16 v[122:125], v[160:163], v[202:205], v[122:125]
	v_mfma_f32_16x16x32_bf16 v[110:113], v[152:155], v[210:213], v[110:113]
	v_mfma_f32_16x16x32_bf16 v[106:109], v[160:163], v[210:213], v[106:109]
	v_mfma_f32_16x16x32_bf16 v[94:97], v[152:155], v[218:221], v[94:97]
	v_mfma_f32_16x16x32_bf16 v[90:93], v[160:163], v[218:221], v[90:93]
	v_mfma_f32_16x16x32_bf16 v[78:81], v[152:155], v[226:229], v[78:81]
	v_mfma_f32_16x16x32_bf16 v[74:77], v[160:163], v[226:229], v[74:77]
	v_mfma_f32_16x16x32_bf16 v[118:121], v[182:185], v[198:201], v[118:121]
	v_mfma_f32_16x16x32_bf16 v[114:117], v[190:193], v[198:201], v[114:117]
	v_mfma_f32_16x16x32_bf16 v[102:105], v[182:185], v[206:209], v[102:105]
	v_mfma_f32_16x16x32_bf16 v[98:101], v[190:193], v[206:209], v[98:101]
	v_mfma_f32_16x16x32_bf16 v[86:89], v[182:185], v[214:217], v[86:89]
	v_mfma_f32_16x16x32_bf16 v[82:85], v[190:193], v[214:217], v[82:85]
	v_mfma_f32_16x16x32_bf16 v[70:73], v[182:185], v[222:225], v[70:73]
	v_mfma_f32_16x16x32_bf16 v[66:69], v[190:193], v[222:225], v[66:69]
	v_mfma_f32_16x16x32_bf16 v[118:121], v[186:189], v[202:205], v[118:121]
	v_mfma_f32_16x16x32_bf16 v[114:117], v[194:197], v[202:205], v[114:117]
	v_mfma_f32_16x16x32_bf16 v[102:105], v[186:189], v[210:213], v[102:105]
	v_mfma_f32_16x16x32_bf16 v[98:101], v[194:197], v[210:213], v[98:101]
	v_mfma_f32_16x16x32_bf16 v[86:89], v[186:189], v[218:221], v[86:89]
	v_mfma_f32_16x16x32_bf16 v[82:85], v[194:197], v[218:221], v[82:85]
	v_mfma_f32_16x16x32_bf16 v[70:73], v[186:189], v[226:229], v[70:73]
	v_mfma_f32_16x16x32_bf16 v[66:69], v[194:197], v[226:229], v[66:69]
	s_barrier
	s_setprio 0
	s_add_i32 s83, s72, s58
	v_lshl_add_u64 v[176:177], s[54:55], 0, v[132:133]
	s_mov_b32 m0, s83
	ds_read_b128 v[198:201], v174 offset:16384
	ds_read_b128 v[202:205], v174 offset:17408
	ds_read_b128 v[206:209], v174 offset:18432
	ds_read_b128 v[210:213], v174 offset:19456
	ds_read_b128 v[214:217], v174 offset:20480
	ds_read_b128 v[218:221], v174 offset:21504
	ds_read_b128 v[222:225], v174 offset:22528
	ds_read_b128 v[226:229], v174 offset:23552
	global_load_lds_dwordx4 v[176:177], off
	s_add_i32 m0, s83, 0x2000
	s_add_u32 s88, s54, 0x80000
	v_lshl_add_u64 v[230:231], s[54:55], 0, v[136:137]
	s_addc_u32 s89, s55, 0
	s_add_i32 s83, s73, s58
	global_load_lds_dwordx4 v[230:231], off
	v_lshl_add_u64 v[232:233], s[88:89], 0, v[132:133]
	s_mov_b32 m0, s83
	v_lshl_add_u64 v[234:235], s[56:57], 0, v[134:135]
	global_load_lds_dwordx4 v[232:233], off
	v_lshl_add_u64 v[232:233], s[88:89], 0, v[136:137]
	s_add_i32 m0, s83, 0x2000
	s_nop 0
	global_load_lds_dwordx4 v[232:233], off
	v_lshl_add_u64 v[232:233], s[56:57], 0, v[130:131]
	s_mov_b32 m0, s59
	s_nop 0
	global_load_lds_dwordx4 v[232:233], off
	s_mov_b32 m0, s60
	s_nop 0
	global_load_lds_dwordx4 v[234:235], off
	s_waitcnt vmcnt(8)
	s_waitcnt lgkmcnt(0)
	s_setprio 1
	s_barrier
	v_mfma_f32_16x16x32_bf16 v[62:65], v[148:151], v[198:201], v[62:65]
	v_mfma_f32_16x16x32_bf16 v[58:61], v[156:159], v[198:201], v[58:61]
	v_mfma_f32_16x16x32_bf16 v[46:49], v[148:151], v[206:209], v[46:49]
	v_mfma_f32_16x16x32_bf16 v[42:45], v[156:159], v[206:209], v[42:45]
	v_mfma_f32_16x16x32_bf16 v[30:33], v[148:151], v[214:217], v[30:33]
	v_mfma_f32_16x16x32_bf16 v[26:29], v[156:159], v[214:217], v[26:29]
	v_mfma_f32_16x16x32_bf16 v[14:17], v[148:151], v[222:225], v[14:17]
	v_mfma_f32_16x16x32_bf16 v[10:13], v[156:159], v[222:225], v[10:13]
	v_mfma_f32_16x16x32_bf16 v[62:65], v[152:155], v[202:205], v[62:65]
	v_mfma_f32_16x16x32_bf16 v[58:61], v[160:163], v[202:205], v[58:61]
	v_mfma_f32_16x16x32_bf16 v[46:49], v[152:155], v[210:213], v[46:49]
	v_mfma_f32_16x16x32_bf16 v[42:45], v[160:163], v[210:213], v[42:45]
	v_mfma_f32_16x16x32_bf16 v[30:33], v[152:155], v[218:221], v[30:33]
	v_mfma_f32_16x16x32_bf16 v[26:29], v[160:163], v[218:221], v[26:29]
	v_mfma_f32_16x16x32_bf16 v[14:17], v[152:155], v[226:229], v[14:17]
	v_mfma_f32_16x16x32_bf16 v[10:13], v[160:163], v[226:229], v[10:13]
	v_mfma_f32_16x16x32_bf16 v[54:57], v[182:185], v[198:201], v[54:57]
	v_mfma_f32_16x16x32_bf16 v[50:53], v[190:193], v[198:201], v[50:53]
	v_mfma_f32_16x16x32_bf16 v[38:41], v[182:185], v[206:209], v[38:41]
	v_mfma_f32_16x16x32_bf16 v[34:37], v[190:193], v[206:209], v[34:37]
	v_mfma_f32_16x16x32_bf16 v[22:25], v[182:185], v[214:217], v[22:25]
	v_mfma_f32_16x16x32_bf16 v[18:21], v[190:193], v[214:217], v[18:21]
	v_mfma_f32_16x16x32_bf16 v[6:9], v[182:185], v[222:225], v[6:9]
	v_mfma_f32_16x16x32_bf16 v[2:5], v[190:193], v[222:225], v[2:5]
	v_mfma_f32_16x16x32_bf16 v[54:57], v[186:189], v[202:205], v[54:57]
	v_mfma_f32_16x16x32_bf16 v[50:53], v[194:197], v[202:205], v[50:53]
	v_mfma_f32_16x16x32_bf16 v[38:41], v[186:189], v[210:213], v[38:41]
	v_mfma_f32_16x16x32_bf16 v[34:37], v[194:197], v[210:213], v[34:37]
	v_mfma_f32_16x16x32_bf16 v[22:25], v[186:189], v[218:221], v[22:25]
	v_mfma_f32_16x16x32_bf16 v[18:21], v[194:197], v[218:221], v[18:21]
	v_mfma_f32_16x16x32_bf16 v[6:9], v[186:189], v[226:229], v[6:9]
	v_mfma_f32_16x16x32_bf16 v[2:5], v[194:197], v[226:229], v[2:5]
	s_barrier
	s_setprio 0
	s_add_i32 s83, 0, 0x18000
	s_add_i32 s88, 0, 0x1c000
	v_add_u32_e32 v160, s83, v166
	v_add_u32_e32 v179, s88, v166
	ds_read_b128 v[148:151], v160
	ds_read_b128 v[152:155], v160 offset:1024
	ds_read_b128 v[156:159], v160 offset:2048
	ds_read_b128 v[160:163], v160 offset:3072
	ds_read_b128 v[182:185], v179
	ds_read_b128 v[186:189], v179 offset:1024
	ds_read_b128 v[190:193], v179 offset:2048
	ds_read_b128 v[194:197], v179 offset:3072
	s_add_u32 s56, s56, 0x80000
	s_addc_u32 s57, s57, 0
	s_mov_b32 m0, s62
	v_lshl_add_u64 v[236:237], s[56:57], 0, v[130:131]
	ds_read_b128 v[198:201], v174 offset:32768
	ds_read_b128 v[202:205], v174 offset:33792
	ds_read_b128 v[206:209], v174 offset:34816
	ds_read_b128 v[210:213], v174 offset:35840
	ds_read_b128 v[214:217], v174 offset:36864
	ds_read_b128 v[218:221], v174 offset:37888
	ds_read_b128 v[222:225], v174 offset:38912
	ds_read_b128 v[226:229], v174 offset:39936
	global_load_lds_dwordx4 v[236:237], off
	v_lshl_add_u64 v[236:237], s[56:57], 0, v[134:135]
	s_mov_b32 m0, s63
	s_nop 0
	global_load_lds_dwordx4 v[236:237], off
	s_waitcnt vmcnt(8)
	s_waitcnt lgkmcnt(0)
	s_setprio 1
	s_barrier
	v_mfma_f32_16x16x32_bf16 v[126:129], v[148:151], v[198:201], v[126:129]
	v_mfma_f32_16x16x32_bf16 v[122:125], v[156:159], v[198:201], v[122:125]
	v_mfma_f32_16x16x32_bf16 v[110:113], v[148:151], v[206:209], v[110:113]
	v_mfma_f32_16x16x32_bf16 v[106:109], v[156:159], v[206:209], v[106:109]
	v_mfma_f32_16x16x32_bf16 v[94:97], v[148:151], v[214:217], v[94:97]
	v_mfma_f32_16x16x32_bf16 v[90:93], v[156:159], v[214:217], v[90:93]
	v_mfma_f32_16x16x32_bf16 v[78:81], v[148:151], v[222:225], v[78:81]
	v_mfma_f32_16x16x32_bf16 v[74:77], v[156:159], v[222:225], v[74:77]
	v_mfma_f32_16x16x32_bf16 v[126:129], v[152:155], v[202:205], v[126:129]
	v_mfma_f32_16x16x32_bf16 v[122:125], v[160:163], v[202:205], v[122:125]
	v_mfma_f32_16x16x32_bf16 v[110:113], v[152:155], v[210:213], v[110:113]
	v_mfma_f32_16x16x32_bf16 v[106:109], v[160:163], v[210:213], v[106:109]
	v_mfma_f32_16x16x32_bf16 v[94:97], v[152:155], v[218:221], v[94:97]
	v_mfma_f32_16x16x32_bf16 v[90:93], v[160:163], v[218:221], v[90:93]
	v_mfma_f32_16x16x32_bf16 v[78:81], v[152:155], v[226:229], v[78:81]
	v_mfma_f32_16x16x32_bf16 v[74:77], v[160:163], v[226:229], v[74:77]
	v_mfma_f32_16x16x32_bf16 v[118:121], v[182:185], v[198:201], v[118:121]
	v_mfma_f32_16x16x32_bf16 v[114:117], v[190:193], v[198:201], v[114:117]
	v_mfma_f32_16x16x32_bf16 v[102:105], v[182:185], v[206:209], v[102:105]
	v_mfma_f32_16x16x32_bf16 v[98:101], v[190:193], v[206:209], v[98:101]
	v_mfma_f32_16x16x32_bf16 v[86:89], v[182:185], v[214:217], v[86:89]
	v_mfma_f32_16x16x32_bf16 v[82:85], v[190:193], v[214:217], v[82:85]
	v_mfma_f32_16x16x32_bf16 v[70:73], v[182:185], v[222:225], v[70:73]
	v_mfma_f32_16x16x32_bf16 v[66:69], v[190:193], v[222:225], v[66:69]
	v_mfma_f32_16x16x32_bf16 v[118:121], v[186:189], v[202:205], v[118:121]
	v_mfma_f32_16x16x32_bf16 v[114:117], v[194:197], v[202:205], v[114:117]
	v_mfma_f32_16x16x32_bf16 v[102:105], v[186:189], v[210:213], v[102:105]
	v_mfma_f32_16x16x32_bf16 v[98:101], v[194:197], v[210:213], v[98:101]
	v_mfma_f32_16x16x32_bf16 v[86:89], v[186:189], v[218:221], v[86:89]
	v_mfma_f32_16x16x32_bf16 v[82:85], v[194:197], v[218:221], v[82:85]
	v_mfma_f32_16x16x32_bf16 v[70:73], v[186:189], v[226:229], v[70:73]
	v_mfma_f32_16x16x32_bf16 v[66:69], v[194:197], v[226:229], v[66:69]
	s_barrier
	s_setprio 0
	s_add_i32 s56, s83, s58
	v_lshl_add_u64 v[176:177], v[176:177], 0, s[20:21]
	s_mov_b32 m0, s56
	ds_read_b128 v[198:201], v174 offset:49152
	ds_read_b128 v[202:205], v174 offset:50176
	ds_read_b128 v[206:209], v174 offset:51200
	ds_read_b128 v[210:213], v174 offset:52224
	ds_read_b128 v[214:217], v174 offset:53248
	ds_read_b128 v[218:221], v174 offset:54272
	ds_read_b128 v[222:225], v174 offset:55296
	ds_read_b128 v[226:229], v174 offset:56320
	global_load_lds_dwordx4 v[176:177], off
	s_add_i32 m0, s56, 0x2000
	s_add_u32 s54, s54, 0x80080
	v_lshl_add_u64 v[176:177], v[230:231], 0, s[20:21]
	s_addc_u32 s55, s55, 0
	s_add_i32 s56, s88, s58
	global_load_lds_dwordx4 v[176:177], off
	v_lshl_add_u64 v[176:177], s[54:55], 0, v[132:133]
	s_mov_b32 m0, s56
	s_nop 0
	global_load_lds_dwordx4 v[176:177], off
	v_lshl_add_u64 v[176:177], s[54:55], 0, v[136:137]
	s_add_i32 m0, s56, 0x2000
	s_nop 0
	global_load_lds_dwordx4 v[176:177], off
	v_lshl_add_u64 v[176:177], v[232:233], 0, s[20:21]
	s_mov_b32 m0, s67
	s_nop 0
	global_load_lds_dwordx4 v[176:177], off
	v_lshl_add_u64 v[176:177], v[234:235], 0, s[20:21]
	s_mov_b32 m0, s68
	s_nop 0
	global_load_lds_dwordx4 v[176:177], off
	s_waitcnt vmcnt(8)
	s_waitcnt lgkmcnt(0)
	s_setprio 1
	s_barrier
	v_mfma_f32_16x16x32_bf16 v[62:65], v[148:151], v[198:201], v[62:65]
	v_mfma_f32_16x16x32_bf16 v[58:61], v[156:159], v[198:201], v[58:61]
	v_mfma_f32_16x16x32_bf16 v[46:49], v[148:151], v[206:209], v[46:49]
	v_mfma_f32_16x16x32_bf16 v[42:45], v[156:159], v[206:209], v[42:45]
	v_mfma_f32_16x16x32_bf16 v[30:33], v[148:151], v[214:217], v[30:33]
	v_mfma_f32_16x16x32_bf16 v[26:29], v[156:159], v[214:217], v[26:29]
	v_mfma_f32_16x16x32_bf16 v[14:17], v[148:151], v[222:225], v[14:17]
	v_mfma_f32_16x16x32_bf16 v[10:13], v[156:159], v[222:225], v[10:13]
	v_mfma_f32_16x16x32_bf16 v[62:65], v[152:155], v[202:205], v[62:65]
	v_mfma_f32_16x16x32_bf16 v[58:61], v[160:163], v[202:205], v[58:61]
	v_mfma_f32_16x16x32_bf16 v[46:49], v[152:155], v[210:213], v[46:49]
	v_mfma_f32_16x16x32_bf16 v[42:45], v[160:163], v[210:213], v[42:45]
	v_mfma_f32_16x16x32_bf16 v[30:33], v[152:155], v[218:221], v[30:33]
	v_mfma_f32_16x16x32_bf16 v[26:29], v[160:163], v[218:221], v[26:29]
	v_mfma_f32_16x16x32_bf16 v[14:17], v[152:155], v[226:229], v[14:17]
	v_mfma_f32_16x16x32_bf16 v[10:13], v[160:163], v[226:229], v[10:13]
	v_mfma_f32_16x16x32_bf16 v[54:57], v[182:185], v[198:201], v[54:57]
	v_mfma_f32_16x16x32_bf16 v[50:53], v[190:193], v[198:201], v[50:53]
	v_mfma_f32_16x16x32_bf16 v[38:41], v[182:185], v[206:209], v[38:41]
	v_mfma_f32_16x16x32_bf16 v[34:37], v[190:193], v[206:209], v[34:37]
	v_mfma_f32_16x16x32_bf16 v[22:25], v[182:185], v[214:217], v[22:25]
	v_mfma_f32_16x16x32_bf16 v[18:21], v[190:193], v[214:217], v[18:21]
	v_mfma_f32_16x16x32_bf16 v[6:9], v[182:185], v[222:225], v[6:9]
	v_mfma_f32_16x16x32_bf16 v[2:5], v[190:193], v[222:225], v[2:5]
	v_mfma_f32_16x16x32_bf16 v[54:57], v[186:189], v[202:205], v[54:57]
	v_mfma_f32_16x16x32_bf16 v[50:53], v[194:197], v[202:205], v[50:53]
	v_mfma_f32_16x16x32_bf16 v[38:41], v[186:189], v[210:213], v[38:41]
	v_mfma_f32_16x16x32_bf16 v[34:37], v[194:197], v[210:213], v[34:37]
	v_mfma_f32_16x16x32_bf16 v[22:25], v[186:189], v[218:221], v[22:25]
	v_mfma_f32_16x16x32_bf16 v[18:21], v[194:197], v[218:221], v[18:21]
	v_mfma_f32_16x16x32_bf16 v[6:9], v[186:189], v[226:229], v[6:9]
	v_mfma_f32_16x16x32_bf16 v[2:5], v[194:197], v[226:229], v[2:5]
	s_barrier
	s_setprio 0
	s_add_i32 s82, s82, 2
	s_add_u32 s52, s52, 0x100
	s_addc_u32 s53, s53, 0
	s_add_u32 s78, s78, 0x100
	s_addc_u32 s79, s79, 0
	s_cmp_gt_u32 s82, 29
	s_cbranch_scc0 .LBB0_1913
	s_and_b64 vcc, exec, s[22:23]
	s_cbranch_vccz .LBB0_1916
	s_barrier

.LBB0_2098:
	ds_read_b128 v[146:149], v168
	ds_read_b128 v[150:153], v168 offset:1024
	ds_read_b128 v[172:175], v168 offset:2048
	ds_read_b128 v[182:185], v168 offset:3072
	ds_read_b128 v[186:189], v169
	ds_read_b128 v[190:193], v169 offset:1024
	ds_read_b128 v[194:197], v169 offset:2048
	ds_read_b128 v[198:201], v169 offset:3072
	s_add_u32 s28, s26, 0xfffc0080
	s_addc_u32 s29, s27, -1
	s_cmp_eq_u32 s72, 4
	s_cselect_b32 s31, s3, s29
	s_cselect_b32 s30, s5, s28
	s_cselect_b32 s29, s17, s71
	s_cselect_b32 s28, s19, s70
	v_lshl_add_u64 v[176:177], s[26:27], 0, v[138:139]
	s_add_i32 m0, s53, 0xc000
	ds_read_b128 v[202:205], v170
	ds_read_b128 v[206:209], v170 offset:1024
	ds_read_b128 v[210:213], v170 offset:2048
	ds_read_b128 v[214:217], v170 offset:3072
	ds_read_b128 v[218:221], v170 offset:4096
	ds_read_b128 v[222:225], v170 offset:5120
	ds_read_b128 v[226:229], v170 offset:6144
	ds_read_b128 v[230:233], v170 offset:7168
	global_load_lds_dwordx4 v[176:177], off
	v_lshl_add_u64 v[176:177], s[26:27], 0, v[140:141]
	s_add_i32 m0, s53, 0xe000
	s_nop 0
	global_load_lds_dwordx4 v[176:177], off
	s_waitcnt vmcnt(8)
	s_waitcnt lgkmcnt(0)
	s_setprio 1
	s_barrier
	v_mfma_f32_16x16x32_bf16 v[126:129], v[146:149], v[202:205], v[126:129]
	v_mfma_f32_16x16x32_bf16 v[122:125], v[172:175], v[202:205], v[122:125]
	v_mfma_f32_16x16x32_bf16 v[110:113], v[146:149], v[210:213], v[110:113]
	v_mfma_f32_16x16x32_bf16 v[106:109], v[172:175], v[210:213], v[106:109]
	v_mfma_f32_16x16x32_bf16 v[94:97], v[146:149], v[218:221], v[94:97]
	v_mfma_f32_16x16x32_bf16 v[90:93], v[172:175], v[218:221], v[90:93]
	v_mfma_f32_16x16x32_bf16 v[78:81], v[146:149], v[226:229], v[78:81]
	v_mfma_f32_16x16x32_bf16 v[74:77], v[172:175], v[226:229], v[74:77]
	v_mfma_f32_16x16x32_bf16 v[126:129], v[150:153], v[206:209], v[126:129]
	v_mfma_f32_16x16x32_bf16 v[122:125], v[182:185], v[206:209], v[122:125]
	v_mfma_f32_16x16x32_bf16 v[110:113], v[150:153], v[214:217], v[110:113]
	v_mfma_f32_16x16x32_bf16 v[106:109], v[182:185], v[214:217], v[106:109]
	v_mfma_f32_16x16x32_bf16 v[94:97], v[150:153], v[222:225], v[94:97]
	v_mfma_f32_16x16x32_bf16 v[90:93], v[182:185], v[222:225], v[90:93]
	v_mfma_f32_16x16x32_bf16 v[78:81], v[150:153], v[230:233], v[78:81]
	v_mfma_f32_16x16x32_bf16 v[74:77], v[182:185], v[230:233], v[74:77]
	v_mfma_f32_16x16x32_bf16 v[118:121], v[186:189], v[202:205], v[118:121]
	v_mfma_f32_16x16x32_bf16 v[114:117], v[194:197], v[202:205], v[114:117]
	v_mfma_f32_16x16x32_bf16 v[102:105], v[186:189], v[210:213], v[102:105]
	v_mfma_f32_16x16x32_bf16 v[98:101], v[194:197], v[210:213], v[98:101]
	v_mfma_f32_16x16x32_bf16 v[86:89], v[186:189], v[218:221], v[86:89]
	v_mfma_f32_16x16x32_bf16 v[82:85], v[194:197], v[218:221], v[82:85]
	v_mfma_f32_16x16x32_bf16 v[70:73], v[186:189], v[226:229], v[70:73]
	v_mfma_f32_16x16x32_bf16 v[66:69], v[194:197], v[226:229], v[66:69]
	v_mfma_f32_16x16x32_bf16 v[118:121], v[190:193], v[206:209], v[118:121]
	v_mfma_f32_16x16x32_bf16 v[114:117], v[198:201], v[206:209], v[114:117]
	v_mfma_f32_16x16x32_bf16 v[102:105], v[190:193], v[214:217], v[102:105]
	v_mfma_f32_16x16x32_bf16 v[98:101], v[198:201], v[214:217], v[98:101]
	v_mfma_f32_16x16x32_bf16 v[86:89], v[190:193], v[222:225], v[86:89]
	v_mfma_f32_16x16x32_bf16 v[82:85], v[198:201], v[222:225], v[82:85]
	v_mfma_f32_16x16x32_bf16 v[70:73], v[190:193], v[230:233], v[70:73]
	v_mfma_f32_16x16x32_bf16 v[66:69], v[198:201], v[230:233], v[66:69]
	s_barrier
	s_setprio 0
	s_add_i32 s73, s67, s52
	v_lshl_add_u64 v[176:177], s[28:29], 0, v[132:133]
	s_mov_b32 m0, s73
	ds_read_b128 v[202:205], v170 offset:16384
	ds_read_b128 v[206:209], v170 offset:17408
	ds_read_b128 v[210:213], v170 offset:18432
	ds_read_b128 v[214:217], v170 offset:19456
	ds_read_b128 v[218:221], v170 offset:20480
	ds_read_b128 v[222:225], v170 offset:21504
	ds_read_b128 v[226:229], v170 offset:22528
	ds_read_b128 v[230:233], v170 offset:23552
	global_load_lds_dwordx4 v[176:177], off
	s_add_i32 m0, s73, 0x2000
	s_add_u32 s76, s28, 0x20000
	v_lshl_add_u64 v[234:235], s[28:29], 0, v[136:137]
	s_addc_u32 s77, s29, 0
	s_add_i32 s73, s68, s52
	global_load_lds_dwordx4 v[234:235], off
	v_lshl_add_u64 v[236:237], s[76:77], 0, v[132:133]
	s_mov_b32 m0, s73
	v_lshl_add_u64 v[238:239], s[30:31], 0, v[134:135]
	global_load_lds_dwordx4 v[236:237], off
	v_lshl_add_u64 v[236:237], s[76:77], 0, v[136:137]
	s_add_i32 m0, s73, 0x2000
	s_nop 0
	global_load_lds_dwordx4 v[236:237], off
	v_lshl_add_u64 v[236:237], s[30:31], 0, v[130:131]
	s_mov_b32 m0, s53
	s_nop 0
	global_load_lds_dwordx4 v[236:237], off
	s_mov_b32 m0, s54
	s_nop 0
	global_load_lds_dwordx4 v[238:239], off
	s_waitcnt vmcnt(8)
	s_waitcnt lgkmcnt(0)
	s_setprio 1
	s_barrier
	v_mfma_f32_16x16x32_bf16 v[62:65], v[146:149], v[202:205], v[62:65]
	v_mfma_f32_16x16x32_bf16 v[58:61], v[172:175], v[202:205], v[58:61]
	v_mfma_f32_16x16x32_bf16 v[46:49], v[146:149], v[210:213], v[46:49]
	v_mfma_f32_16x16x32_bf16 v[42:45], v[172:175], v[210:213], v[42:45]
	v_mfma_f32_16x16x32_bf16 v[30:33], v[146:149], v[218:221], v[30:33]
	v_mfma_f32_16x16x32_bf16 v[26:29], v[172:175], v[218:221], v[26:29]
	v_mfma_f32_16x16x32_bf16 v[14:17], v[146:149], v[226:229], v[14:17]
	v_mfma_f32_16x16x32_bf16 v[10:13], v[172:175], v[226:229], v[10:13]
	v_mfma_f32_16x16x32_bf16 v[62:65], v[150:153], v[206:209], v[62:65]
	v_mfma_f32_16x16x32_bf16 v[58:61], v[182:185], v[206:209], v[58:61]
	v_mfma_f32_16x16x32_bf16 v[46:49], v[150:153], v[214:217], v[46:49]
	v_mfma_f32_16x16x32_bf16 v[42:45], v[182:185], v[214:217], v[42:45]
	v_mfma_f32_16x16x32_bf16 v[30:33], v[150:153], v[222:225], v[30:33]
	v_mfma_f32_16x16x32_bf16 v[26:29], v[182:185], v[222:225], v[26:29]
	v_mfma_f32_16x16x32_bf16 v[14:17], v[150:153], v[230:233], v[14:17]
	v_mfma_f32_16x16x32_bf16 v[10:13], v[182:185], v[230:233], v[10:13]
	v_mfma_f32_16x16x32_bf16 v[54:57], v[186:189], v[202:205], v[54:57]
	v_mfma_f32_16x16x32_bf16 v[50:53], v[194:197], v[202:205], v[50:53]
	v_mfma_f32_16x16x32_bf16 v[38:41], v[186:189], v[210:213], v[38:41]
	v_mfma_f32_16x16x32_bf16 v[34:37], v[194:197], v[210:213], v[34:37]
	v_mfma_f32_16x16x32_bf16 v[22:25], v[186:189], v[218:221], v[22:25]
	v_mfma_f32_16x16x32_bf16 v[18:21], v[194:197], v[218:221], v[18:21]
	v_mfma_f32_16x16x32_bf16 v[6:9], v[186:189], v[226:229], v[6:9]
	v_mfma_f32_16x16x32_bf16 v[2:5], v[194:197], v[226:229], v[2:5]
	v_mfma_f32_16x16x32_bf16 v[54:57], v[190:193], v[206:209], v[54:57]
	v_mfma_f32_16x16x32_bf16 v[50:53], v[198:201], v[206:209], v[50:53]
	v_mfma_f32_16x16x32_bf16 v[38:41], v[190:193], v[214:217], v[38:41]
	v_mfma_f32_16x16x32_bf16 v[34:37], v[198:201], v[214:217], v[34:37]
	v_mfma_f32_16x16x32_bf16 v[22:25], v[190:193], v[222:225], v[22:25]
	v_mfma_f32_16x16x32_bf16 v[18:21], v[198:201], v[222:225], v[18:21]
	v_mfma_f32_16x16x32_bf16 v[6:9], v[190:193], v[230:233], v[6:9]
	v_mfma_f32_16x16x32_bf16 v[2:5], v[198:201], v[230:233], v[2:5]
	s_barrier
	s_setprio 0
	s_add_i32 s73, 0, 0x18000
	v_add_u32_e32 v179, s73, v162
	s_add_i32 s76, 0, 0x1c000
	ds_read_b128 v[146:149], v179
	ds_read_b128 v[150:153], v179 offset:1024
	ds_read_b128 v[172:175], v179 offset:2048
	ds_read_b128 v[182:185], v179 offset:3072
	v_add_u32_e32 v179, s76, v162
	ds_read_b128 v[186:189], v179
	ds_read_b128 v[190:193], v179 offset:1024
	ds_read_b128 v[194:197], v179 offset:2048
	ds_read_b128 v[198:201], v179 offset:3072
	s_add_u32 s30, s30, 0x40000
	s_addc_u32 s31, s31, 0
	s_mov_b32 m0, s55
	v_lshl_add_u64 v[240:241], s[30:31], 0, v[130:131]
	ds_read_b128 v[202:205], v170 offset:32768
	ds_read_b128 v[206:209], v170 offset:33792
	ds_read_b128 v[210:213], v170 offset:34816
	ds_read_b128 v[214:217], v170 offset:35840
	ds_read_b128 v[218:221], v170 offset:36864
	ds_read_b128 v[222:225], v170 offset:37888
	ds_read_b128 v[226:229], v170 offset:38912
	ds_read_b128 v[230:233], v170 offset:39936
	global_load_lds_dwordx4 v[240:241], off
	v_lshl_add_u64 v[240:241], s[30:31], 0, v[134:135]
	s_mov_b32 m0, s56
	s_nop 0
	global_load_lds_dwordx4 v[240:241], off
	s_waitcnt vmcnt(8)
	s_waitcnt lgkmcnt(0)
	s_setprio 1
	s_barrier
	v_mfma_f32_16x16x32_bf16 v[126:129], v[146:149], v[202:205], v[126:129]
	v_mfma_f32_16x16x32_bf16 v[122:125], v[172:175], v[202:205], v[122:125]
	v_mfma_f32_16x16x32_bf16 v[110:113], v[146:149], v[210:213], v[110:113]
	v_mfma_f32_16x16x32_bf16 v[106:109], v[172:175], v[210:213], v[106:109]
	v_mfma_f32_16x16x32_bf16 v[94:97], v[146:149], v[218:221], v[94:97]
	v_mfma_f32_16x16x32_bf16 v[90:93], v[172:175], v[218:221], v[90:93]
	v_mfma_f32_16x16x32_bf16 v[78:81], v[146:149], v[226:229], v[78:81]
	v_mfma_f32_16x16x32_bf16 v[74:77], v[172:175], v[226:229], v[74:77]
	v_mfma_f32_16x16x32_bf16 v[126:129], v[150:153], v[206:209], v[126:129]
	v_mfma_f32_16x16x32_bf16 v[122:125], v[182:185], v[206:209], v[122:125]
	v_mfma_f32_16x16x32_bf16 v[110:113], v[150:153], v[214:217], v[110:113]
	v_mfma_f32_16x16x32_bf16 v[106:109], v[182:185], v[214:217], v[106:109]
	v_mfma_f32_16x16x32_bf16 v[94:97], v[150:153], v[222:225], v[94:97]
	v_mfma_f32_16x16x32_bf16 v[90:93], v[182:185], v[222:225], v[90:93]
	v_mfma_f32_16x16x32_bf16 v[78:81], v[150:153], v[230:233], v[78:81]
	v_mfma_f32_16x16x32_bf16 v[74:77], v[182:185], v[230:233], v[74:77]
	v_mfma_f32_16x16x32_bf16 v[118:121], v[186:189], v[202:205], v[118:121]
	v_mfma_f32_16x16x32_bf16 v[114:117], v[194:197], v[202:205], v[114:117]
	v_mfma_f32_16x16x32_bf16 v[102:105], v[186:189], v[210:213], v[102:105]
	v_mfma_f32_16x16x32_bf16 v[98:101], v[194:197], v[210:213], v[98:101]
	v_mfma_f32_16x16x32_bf16 v[86:89], v[186:189], v[218:221], v[86:89]
	v_mfma_f32_16x16x32_bf16 v[82:85], v[194:197], v[218:221], v[82:85]
	v_mfma_f32_16x16x32_bf16 v[70:73], v[186:189], v[226:229], v[70:73]
	v_mfma_f32_16x16x32_bf16 v[66:69], v[194:197], v[226:229], v[66:69]
	v_mfma_f32_16x16x32_bf16 v[118:121], v[190:193], v[206:209], v[118:121]
	v_mfma_f32_16x16x32_bf16 v[114:117], v[198:201], v[206:209], v[114:117]
	v_mfma_f32_16x16x32_bf16 v[102:105], v[190:193], v[214:217], v[102:105]
	v_mfma_f32_16x16x32_bf16 v[98:101], v[198:201], v[214:217], v[98:101]
	v_mfma_f32_16x16x32_bf16 v[86:89], v[190:193], v[222:225], v[86:89]
	v_mfma_f32_16x16x32_bf16 v[82:85], v[198:201], v[222:225], v[82:85]
	v_mfma_f32_16x16x32_bf16 v[70:73], v[190:193], v[230:233], v[70:73]
	v_mfma_f32_16x16x32_bf16 v[66:69], v[198:201], v[230:233], v[66:69]
	s_barrier
	s_setprio 0
	s_add_i32 s30, s73, s52
	v_lshl_add_u64 v[176:177], v[176:177], 0, s[12:13]
	s_mov_b32 m0, s30
	ds_read_b128 v[202:205], v170 offset:49152
	ds_read_b128 v[206:209], v170 offset:50176
	ds_read_b128 v[210:213], v170 offset:51200
	ds_read_b128 v[214:217], v170 offset:52224
	ds_read_b128 v[218:221], v170 offset:53248
	ds_read_b128 v[222:225], v170 offset:54272
	ds_read_b128 v[226:229], v170 offset:55296
	ds_read_b128 v[230:233], v170 offset:56320
	global_load_lds_dwordx4 v[176:177], off
	s_add_i32 m0, s30, 0x2000
	s_add_u32 s28, s28, 0x20080
	v_lshl_add_u64 v[176:177], v[234:235], 0, s[12:13]
	s_addc_u32 s29, s29, 0
	s_add_i32 s30, s76, s52
	global_load_lds_dwordx4 v[176:177], off
	v_lshl_add_u64 v[176:177], s[28:29], 0, v[132:133]
	s_mov_b32 m0, s30
	s_nop 0
	global_load_lds_dwordx4 v[176:177], off
	v_lshl_add_u64 v[176:177], s[28:29], 0, v[136:137]
	s_add_i32 m0, s30, 0x2000
	s_nop 0
	global_load_lds_dwordx4 v[176:177], off
	v_lshl_add_u64 v[176:177], v[236:237], 0, s[12:13]
	s_mov_b32 m0, s59
	s_nop 0
	global_load_lds_dwordx4 v[176:177], off
	v_lshl_add_u64 v[176:177], v[238:239], 0, s[12:13]
	s_mov_b32 m0, s60
	s_nop 0
	global_load_lds_dwordx4 v[176:177], off
	s_waitcnt vmcnt(8)
	s_waitcnt lgkmcnt(0)
	s_setprio 1
	s_barrier
	v_mfma_f32_16x16x32_bf16 v[62:65], v[146:149], v[202:205], v[62:65]
	v_mfma_f32_16x16x32_bf16 v[58:61], v[172:175], v[202:205], v[58:61]
	v_mfma_f32_16x16x32_bf16 v[46:49], v[146:149], v[210:213], v[46:49]
	v_mfma_f32_16x16x32_bf16 v[42:45], v[172:175], v[210:213], v[42:45]
	v_mfma_f32_16x16x32_bf16 v[30:33], v[146:149], v[218:221], v[30:33]
	v_mfma_f32_16x16x32_bf16 v[26:29], v[172:175], v[218:221], v[26:29]
	v_mfma_f32_16x16x32_bf16 v[14:17], v[146:149], v[226:229], v[14:17]
	v_mfma_f32_16x16x32_bf16 v[10:13], v[172:175], v[226:229], v[10:13]
	v_mfma_f32_16x16x32_bf16 v[62:65], v[150:153], v[206:209], v[62:65]
	v_mfma_f32_16x16x32_bf16 v[58:61], v[182:185], v[206:209], v[58:61]
	v_mfma_f32_16x16x32_bf16 v[46:49], v[150:153], v[214:217], v[46:49]
	v_mfma_f32_16x16x32_bf16 v[42:45], v[182:185], v[214:217], v[42:45]
	v_mfma_f32_16x16x32_bf16 v[30:33], v[150:153], v[222:225], v[30:33]
	v_mfma_f32_16x16x32_bf16 v[26:29], v[182:185], v[222:225], v[26:29]
	v_mfma_f32_16x16x32_bf16 v[14:17], v[150:153], v[230:233], v[14:17]
	v_mfma_f32_16x16x32_bf16 v[10:13], v[182:185], v[230:233], v[10:13]
	v_mfma_f32_16x16x32_bf16 v[54:57], v[186:189], v[202:205], v[54:57]
	v_mfma_f32_16x16x32_bf16 v[50:53], v[194:197], v[202:205], v[50:53]
	v_mfma_f32_16x16x32_bf16 v[38:41], v[186:189], v[210:213], v[38:41]
	v_mfma_f32_16x16x32_bf16 v[34:37], v[194:197], v[210:213], v[34:37]
	v_mfma_f32_16x16x32_bf16 v[22:25], v[186:189], v[218:221], v[22:25]
	v_mfma_f32_16x16x32_bf16 v[18:21], v[194:197], v[218:221], v[18:21]
	v_mfma_f32_16x16x32_bf16 v[6:9], v[186:189], v[226:229], v[6:9]
	v_mfma_f32_16x16x32_bf16 v[2:5], v[194:197], v[226:229], v[2:5]
	v_mfma_f32_16x16x32_bf16 v[54:57], v[190:193], v[206:209], v[54:57]
	v_mfma_f32_16x16x32_bf16 v[50:53], v[198:201], v[206:209], v[50:53]
	v_mfma_f32_16x16x32_bf16 v[38:41], v[190:193], v[214:217], v[38:41]
	v_mfma_f32_16x16x32_bf16 v[34:37], v[198:201], v[214:217], v[34:37]
	v_mfma_f32_16x16x32_bf16 v[22:25], v[190:193], v[222:225], v[22:25]
	v_mfma_f32_16x16x32_bf16 v[18:21], v[198:201], v[222:225], v[18:21]
	v_mfma_f32_16x16x32_bf16 v[6:9], v[190:193], v[230:233], v[6:9]
	v_mfma_f32_16x16x32_bf16 v[2:5], v[198:201], v[230:233], v[2:5]
	s_barrier
	s_setprio 0
	s_add_i32 s72, s72, 2
	s_add_u32 s26, s26, 0x100
	s_addc_u32 s27, s27, 0
	s_add_u32 s70, s70, 0x100
	s_addc_u32 s71, s71, 0
	s_cmp_gt_u32 s72, 5
	s_cbranch_scc0 .LBB0_2098
	s_and_b64 vcc, exec, s[14:15]
	s_cbranch_vccz .LBB0_2101
	s_barrier

.LBB0_2146:
	ds_read_b128 v[146:149], v1
	ds_read_b128 v[156:159], v1 offset:1024
	ds_read_b128 v[160:163], v1 offset:2048
	ds_read_b128 v[164:167], v1 offset:3072
	ds_read_b128 v[168:171], v153
	ds_read_b128 v[172:175], v153 offset:1024
	ds_read_b128 v[182:185], v153 offset:2048
	ds_read_b128 v[186:189], v153 offset:3072
	s_add_u32 s26, s22, 0xfffc0080
	s_addc_u32 s27, s23, -1
	s_cmp_eq_u32 s71, 4
	s_cselect_b32 s29, s15, s27
	s_cselect_b32 s28, s67, s26
	s_cselect_b32 s27, s13, s70
	s_cselect_b32 s26, s68, s69
	v_lshl_add_u64 v[176:177], s[22:23], 0, v[138:139]
	s_add_i32 m0, s21, 0xc000
	ds_read_b128 v[190:193], v154
	ds_read_b128 v[194:197], v154 offset:1024
	ds_read_b128 v[198:201], v154 offset:2048
	ds_read_b128 v[202:205], v154 offset:3072
	ds_read_b128 v[206:209], v154 offset:4096
	ds_read_b128 v[210:213], v154 offset:5120
	ds_read_b128 v[214:217], v154 offset:6144
	ds_read_b128 v[218:221], v154 offset:7168
	global_load_lds_dwordx4 v[176:177], off
	v_lshl_add_u64 v[176:177], s[22:23], 0, v[140:141]
	s_add_i32 m0, s21, 0xe000
	s_nop 0
	global_load_lds_dwordx4 v[176:177], off
	s_waitcnt vmcnt(8)
	s_waitcnt lgkmcnt(0)
	s_setprio 1
	s_barrier
	v_mfma_f32_16x16x32_bf16 v[126:129], v[146:149], v[190:193], v[126:129]
	v_mfma_f32_16x16x32_bf16 v[122:125], v[160:163], v[190:193], v[122:125]
	v_mfma_f32_16x16x32_bf16 v[110:113], v[146:149], v[198:201], v[110:113]
	v_mfma_f32_16x16x32_bf16 v[106:109], v[160:163], v[198:201], v[106:109]
	v_mfma_f32_16x16x32_bf16 v[94:97], v[146:149], v[206:209], v[94:97]
	v_mfma_f32_16x16x32_bf16 v[90:93], v[160:163], v[206:209], v[90:93]
	v_mfma_f32_16x16x32_bf16 v[78:81], v[146:149], v[214:217], v[78:81]
	v_mfma_f32_16x16x32_bf16 v[74:77], v[160:163], v[214:217], v[74:77]
	v_mfma_f32_16x16x32_bf16 v[126:129], v[156:159], v[194:197], v[126:129]
	v_mfma_f32_16x16x32_bf16 v[122:125], v[164:167], v[194:197], v[122:125]
	v_mfma_f32_16x16x32_bf16 v[110:113], v[156:159], v[202:205], v[110:113]
	v_mfma_f32_16x16x32_bf16 v[106:109], v[164:167], v[202:205], v[106:109]
	v_mfma_f32_16x16x32_bf16 v[94:97], v[156:159], v[210:213], v[94:97]
	v_mfma_f32_16x16x32_bf16 v[90:93], v[164:167], v[210:213], v[90:93]
	v_mfma_f32_16x16x32_bf16 v[78:81], v[156:159], v[218:221], v[78:81]
	v_mfma_f32_16x16x32_bf16 v[74:77], v[164:167], v[218:221], v[74:77]
	v_mfma_f32_16x16x32_bf16 v[118:121], v[168:171], v[190:193], v[118:121]
	v_mfma_f32_16x16x32_bf16 v[114:117], v[182:185], v[190:193], v[114:117]
	v_mfma_f32_16x16x32_bf16 v[102:105], v[168:171], v[198:201], v[102:105]
	v_mfma_f32_16x16x32_bf16 v[98:101], v[182:185], v[198:201], v[98:101]
	v_mfma_f32_16x16x32_bf16 v[86:89], v[168:171], v[206:209], v[86:89]
	v_mfma_f32_16x16x32_bf16 v[82:85], v[182:185], v[206:209], v[82:85]
	v_mfma_f32_16x16x32_bf16 v[70:73], v[168:171], v[214:217], v[70:73]
	v_mfma_f32_16x16x32_bf16 v[66:69], v[182:185], v[214:217], v[66:69]
	v_mfma_f32_16x16x32_bf16 v[118:121], v[172:175], v[194:197], v[118:121]
	v_mfma_f32_16x16x32_bf16 v[114:117], v[186:189], v[194:197], v[114:117]
	v_mfma_f32_16x16x32_bf16 v[102:105], v[172:175], v[202:205], v[102:105]
	v_mfma_f32_16x16x32_bf16 v[98:101], v[186:189], v[202:205], v[98:101]
	v_mfma_f32_16x16x32_bf16 v[86:89], v[172:175], v[210:213], v[86:89]
	v_mfma_f32_16x16x32_bf16 v[82:85], v[186:189], v[210:213], v[82:85]
	v_mfma_f32_16x16x32_bf16 v[70:73], v[172:175], v[218:221], v[70:73]
	v_mfma_f32_16x16x32_bf16 v[66:69], v[186:189], v[218:221], v[66:69]
	s_barrier
	s_setprio 0
	s_add_i32 s72, s62, s37
	v_lshl_add_u64 v[176:177], s[26:27], 0, v[132:133]
	s_mov_b32 m0, s72
	ds_read_b128 v[190:193], v154 offset:16384
	ds_read_b128 v[194:197], v154 offset:17408
	ds_read_b128 v[198:201], v154 offset:18432
	ds_read_b128 v[202:205], v154 offset:19456
	ds_read_b128 v[206:209], v154 offset:20480
	ds_read_b128 v[210:213], v154 offset:21504
	ds_read_b128 v[214:217], v154 offset:22528
	ds_read_b128 v[218:221], v154 offset:23552
	global_load_lds_dwordx4 v[176:177], off
	s_add_i32 m0, s72, 0x2000
	s_add_u32 s72, s26, 0x20000
	v_lshl_add_u64 v[222:223], s[26:27], 0, v[136:137]
	s_addc_u32 s73, s27, 0
	s_add_i32 s76, s63, s37
	global_load_lds_dwordx4 v[222:223], off
	v_lshl_add_u64 v[224:225], s[72:73], 0, v[132:133]
	s_mov_b32 m0, s76
	v_lshl_add_u64 v[226:227], s[28:29], 0, v[134:135]
	global_load_lds_dwordx4 v[224:225], off
	v_lshl_add_u64 v[224:225], s[72:73], 0, v[136:137]
	s_add_i32 m0, s76, 0x2000
	s_nop 0
	global_load_lds_dwordx4 v[224:225], off
	v_lshl_add_u64 v[224:225], s[28:29], 0, v[130:131]
	s_mov_b32 m0, s21
	s_nop 0
	global_load_lds_dwordx4 v[224:225], off
	s_mov_b32 m0, s54
	s_nop 0
	global_load_lds_dwordx4 v[226:227], off
	s_waitcnt vmcnt(8)
	s_waitcnt lgkmcnt(0)
	s_setprio 1
	s_barrier
	v_mfma_f32_16x16x32_bf16 v[62:65], v[146:149], v[190:193], v[62:65]
	v_mfma_f32_16x16x32_bf16 v[58:61], v[160:163], v[190:193], v[58:61]
	v_mfma_f32_16x16x32_bf16 v[46:49], v[146:149], v[198:201], v[46:49]
	v_mfma_f32_16x16x32_bf16 v[42:45], v[160:163], v[198:201], v[42:45]
	v_mfma_f32_16x16x32_bf16 v[30:33], v[146:149], v[206:209], v[30:33]
	v_mfma_f32_16x16x32_bf16 v[26:29], v[160:163], v[206:209], v[26:29]
	v_mfma_f32_16x16x32_bf16 v[14:17], v[146:149], v[214:217], v[14:17]
	v_mfma_f32_16x16x32_bf16 v[10:13], v[160:163], v[214:217], v[10:13]
	v_mfma_f32_16x16x32_bf16 v[62:65], v[156:159], v[194:197], v[62:65]
	v_mfma_f32_16x16x32_bf16 v[58:61], v[164:167], v[194:197], v[58:61]
	v_mfma_f32_16x16x32_bf16 v[46:49], v[156:159], v[202:205], v[46:49]
	v_mfma_f32_16x16x32_bf16 v[42:45], v[164:167], v[202:205], v[42:45]
	v_mfma_f32_16x16x32_bf16 v[30:33], v[156:159], v[210:213], v[30:33]
	v_mfma_f32_16x16x32_bf16 v[26:29], v[164:167], v[210:213], v[26:29]
	v_mfma_f32_16x16x32_bf16 v[14:17], v[156:159], v[218:221], v[14:17]
	v_mfma_f32_16x16x32_bf16 v[10:13], v[164:167], v[218:221], v[10:13]
	v_mfma_f32_16x16x32_bf16 v[54:57], v[168:171], v[190:193], v[54:57]
	v_mfma_f32_16x16x32_bf16 v[50:53], v[182:185], v[190:193], v[50:53]
	v_mfma_f32_16x16x32_bf16 v[38:41], v[168:171], v[198:201], v[38:41]
	v_mfma_f32_16x16x32_bf16 v[34:37], v[182:185], v[198:201], v[34:37]
	v_mfma_f32_16x16x32_bf16 v[22:25], v[168:171], v[206:209], v[22:25]
	v_mfma_f32_16x16x32_bf16 v[18:21], v[182:185], v[206:209], v[18:21]
	v_mfma_f32_16x16x32_bf16 v[6:9], v[168:171], v[214:217], v[6:9]
	v_mfma_f32_16x16x32_bf16 v[2:5], v[182:185], v[214:217], v[2:5]
	v_mfma_f32_16x16x32_bf16 v[54:57], v[172:175], v[194:197], v[54:57]
	v_mfma_f32_16x16x32_bf16 v[50:53], v[186:189], v[194:197], v[50:53]
	v_mfma_f32_16x16x32_bf16 v[38:41], v[172:175], v[202:205], v[38:41]
	v_mfma_f32_16x16x32_bf16 v[34:37], v[186:189], v[202:205], v[34:37]
	v_mfma_f32_16x16x32_bf16 v[22:25], v[172:175], v[210:213], v[22:25]
	v_mfma_f32_16x16x32_bf16 v[18:21], v[186:189], v[210:213], v[18:21]
	v_mfma_f32_16x16x32_bf16 v[6:9], v[172:175], v[218:221], v[6:9]
	v_mfma_f32_16x16x32_bf16 v[2:5], v[186:189], v[218:221], v[2:5]
	s_barrier
	s_setprio 0
	s_add_i32 s72, 0, 0x18000
	s_add_i32 s73, 0, 0x1c000
	v_add_u32_e32 v164, s72, v151
	v_add_u32_e32 v179, s73, v151
	ds_read_b128 v[146:149], v164
	ds_read_b128 v[156:159], v164 offset:1024
	ds_read_b128 v[160:163], v164 offset:2048
	ds_read_b128 v[164:167], v164 offset:3072
	ds_read_b128 v[168:171], v179
	ds_read_b128 v[172:175], v179 offset:1024
	ds_read_b128 v[182:185], v179 offset:2048
	ds_read_b128 v[186:189], v179 offset:3072
	s_add_u32 s28, s28, 0x40000
	s_addc_u32 s29, s29, 0
	s_mov_b32 m0, s55
	v_lshl_add_u64 v[228:229], s[28:29], 0, v[130:131]
	ds_read_b128 v[190:193], v154 offset:32768
	ds_read_b128 v[194:197], v154 offset:33792
	ds_read_b128 v[198:201], v154 offset:34816
	ds_read_b128 v[202:205], v154 offset:35840
	ds_read_b128 v[206:209], v154 offset:36864
	ds_read_b128 v[210:213], v154 offset:37888
	ds_read_b128 v[214:217], v154 offset:38912
	ds_read_b128 v[218:221], v154 offset:39936
	global_load_lds_dwordx4 v[228:229], off
	v_lshl_add_u64 v[228:229], s[28:29], 0, v[134:135]
	s_mov_b32 m0, s56
	s_nop 0
	global_load_lds_dwordx4 v[228:229], off
	s_waitcnt vmcnt(8)
	s_waitcnt lgkmcnt(0)
	s_setprio 1
	s_barrier
	v_mfma_f32_16x16x32_bf16 v[126:129], v[146:149], v[190:193], v[126:129]
	v_mfma_f32_16x16x32_bf16 v[122:125], v[160:163], v[190:193], v[122:125]
	v_mfma_f32_16x16x32_bf16 v[110:113], v[146:149], v[198:201], v[110:113]
	v_mfma_f32_16x16x32_bf16 v[106:109], v[160:163], v[198:201], v[106:109]
	v_mfma_f32_16x16x32_bf16 v[94:97], v[146:149], v[206:209], v[94:97]
	v_mfma_f32_16x16x32_bf16 v[90:93], v[160:163], v[206:209], v[90:93]
	v_mfma_f32_16x16x32_bf16 v[78:81], v[146:149], v[214:217], v[78:81]
	v_mfma_f32_16x16x32_bf16 v[74:77], v[160:163], v[214:217], v[74:77]
	v_mfma_f32_16x16x32_bf16 v[126:129], v[156:159], v[194:197], v[126:129]
	v_mfma_f32_16x16x32_bf16 v[122:125], v[164:167], v[194:197], v[122:125]
	v_mfma_f32_16x16x32_bf16 v[110:113], v[156:159], v[202:205], v[110:113]
	v_mfma_f32_16x16x32_bf16 v[106:109], v[164:167], v[202:205], v[106:109]
	v_mfma_f32_16x16x32_bf16 v[94:97], v[156:159], v[210:213], v[94:97]
	v_mfma_f32_16x16x32_bf16 v[90:93], v[164:167], v[210:213], v[90:93]
	v_mfma_f32_16x16x32_bf16 v[78:81], v[156:159], v[218:221], v[78:81]
	v_mfma_f32_16x16x32_bf16 v[74:77], v[164:167], v[218:221], v[74:77]
	v_mfma_f32_16x16x32_bf16 v[118:121], v[168:171], v[190:193], v[118:121]
	v_mfma_f32_16x16x32_bf16 v[114:117], v[182:185], v[190:193], v[114:117]
	v_mfma_f32_16x16x32_bf16 v[102:105], v[168:171], v[198:201], v[102:105]
	v_mfma_f32_16x16x32_bf16 v[98:101], v[182:185], v[198:201], v[98:101]
	v_mfma_f32_16x16x32_bf16 v[86:89], v[168:171], v[206:209], v[86:89]
	v_mfma_f32_16x16x32_bf16 v[82:85], v[182:185], v[206:209], v[82:85]
	v_mfma_f32_16x16x32_bf16 v[70:73], v[168:171], v[214:217], v[70:73]
	v_mfma_f32_16x16x32_bf16 v[66:69], v[182:185], v[214:217], v[66:69]
	v_mfma_f32_16x16x32_bf16 v[118:121], v[172:175], v[194:197], v[118:121]
	v_mfma_f32_16x16x32_bf16 v[114:117], v[186:189], v[194:197], v[114:117]
	v_mfma_f32_16x16x32_bf16 v[102:105], v[172:175], v[202:205], v[102:105]
	v_mfma_f32_16x16x32_bf16 v[98:101], v[186:189], v[202:205], v[98:101]
	v_mfma_f32_16x16x32_bf16 v[86:89], v[172:175], v[210:213], v[86:89]
	v_mfma_f32_16x16x32_bf16 v[82:85], v[186:189], v[210:213], v[82:85]
	v_mfma_f32_16x16x32_bf16 v[70:73], v[172:175], v[218:221], v[70:73]
	v_mfma_f32_16x16x32_bf16 v[66:69], v[186:189], v[218:221], v[66:69]
	s_barrier
	s_setprio 0
	s_add_i32 s28, s72, s37
	v_lshl_add_u64 v[176:177], v[176:177], 0, s[6:7]
	s_mov_b32 m0, s28
	ds_read_b128 v[190:193], v154 offset:49152
	ds_read_b128 v[194:197], v154 offset:50176
	ds_read_b128 v[198:201], v154 offset:51200
	ds_read_b128 v[202:205], v154 offset:52224
	ds_read_b128 v[206:209], v154 offset:53248
	ds_read_b128 v[210:213], v154 offset:54272
	ds_read_b128 v[214:217], v154 offset:55296
	ds_read_b128 v[218:221], v154 offset:56320
	global_load_lds_dwordx4 v[176:177], off
	s_add_i32 m0, s28, 0x2000
	s_add_u32 s26, s26, 0x20080
	v_lshl_add_u64 v[176:177], v[222:223], 0, s[6:7]
	s_addc_u32 s27, s27, 0
	s_add_i32 s28, s73, s37
	global_load_lds_dwordx4 v[176:177], off
	v_lshl_add_u64 v[176:177], s[26:27], 0, v[132:133]
	s_mov_b32 m0, s28
	s_nop 0
	global_load_lds_dwordx4 v[176:177], off
	v_lshl_add_u64 v[176:177], s[26:27], 0, v[136:137]
	s_add_i32 m0, s28, 0x2000
	s_nop 0
	global_load_lds_dwordx4 v[176:177], off
	v_lshl_add_u64 v[176:177], v[224:225], 0, s[6:7]
	s_mov_b32 m0, s58
	s_nop 0
	global_load_lds_dwordx4 v[176:177], off
	v_lshl_add_u64 v[176:177], v[226:227], 0, s[6:7]
	s_mov_b32 m0, s59
	s_nop 0
	global_load_lds_dwordx4 v[176:177], off
	s_waitcnt vmcnt(8)
	s_waitcnt lgkmcnt(0)
	s_setprio 1
	s_barrier
	v_mfma_f32_16x16x32_bf16 v[62:65], v[146:149], v[190:193], v[62:65]
	v_mfma_f32_16x16x32_bf16 v[58:61], v[160:163], v[190:193], v[58:61]
	v_mfma_f32_16x16x32_bf16 v[46:49], v[146:149], v[198:201], v[46:49]
	v_mfma_f32_16x16x32_bf16 v[42:45], v[160:163], v[198:201], v[42:45]
	v_mfma_f32_16x16x32_bf16 v[30:33], v[146:149], v[206:209], v[30:33]
	v_mfma_f32_16x16x32_bf16 v[26:29], v[160:163], v[206:209], v[26:29]
	v_mfma_f32_16x16x32_bf16 v[14:17], v[146:149], v[214:217], v[14:17]
	v_mfma_f32_16x16x32_bf16 v[10:13], v[160:163], v[214:217], v[10:13]
	v_mfma_f32_16x16x32_bf16 v[62:65], v[156:159], v[194:197], v[62:65]
	v_mfma_f32_16x16x32_bf16 v[58:61], v[164:167], v[194:197], v[58:61]
	v_mfma_f32_16x16x32_bf16 v[46:49], v[156:159], v[202:205], v[46:49]
	v_mfma_f32_16x16x32_bf16 v[42:45], v[164:167], v[202:205], v[42:45]
	v_mfma_f32_16x16x32_bf16 v[30:33], v[156:159], v[210:213], v[30:33]
	v_mfma_f32_16x16x32_bf16 v[26:29], v[164:167], v[210:213], v[26:29]
	v_mfma_f32_16x16x32_bf16 v[14:17], v[156:159], v[218:221], v[14:17]
	v_mfma_f32_16x16x32_bf16 v[10:13], v[164:167], v[218:221], v[10:13]
	v_mfma_f32_16x16x32_bf16 v[54:57], v[168:171], v[190:193], v[54:57]
	v_mfma_f32_16x16x32_bf16 v[50:53], v[182:185], v[190:193], v[50:53]
	v_mfma_f32_16x16x32_bf16 v[38:41], v[168:171], v[198:201], v[38:41]
	v_mfma_f32_16x16x32_bf16 v[34:37], v[182:185], v[198:201], v[34:37]
	v_mfma_f32_16x16x32_bf16 v[22:25], v[168:171], v[206:209], v[22:25]
	v_mfma_f32_16x16x32_bf16 v[18:21], v[182:185], v[206:209], v[18:21]
	v_mfma_f32_16x16x32_bf16 v[6:9], v[168:171], v[214:217], v[6:9]
	v_mfma_f32_16x16x32_bf16 v[2:5], v[182:185], v[214:217], v[2:5]
	v_mfma_f32_16x16x32_bf16 v[54:57], v[172:175], v[194:197], v[54:57]
	v_mfma_f32_16x16x32_bf16 v[50:53], v[186:189], v[194:197], v[50:53]
	v_mfma_f32_16x16x32_bf16 v[38:41], v[172:175], v[202:205], v[38:41]
	v_mfma_f32_16x16x32_bf16 v[34:37], v[186:189], v[202:205], v[34:37]
	v_mfma_f32_16x16x32_bf16 v[22:25], v[172:175], v[210:213], v[22:25]
	v_mfma_f32_16x16x32_bf16 v[18:21], v[186:189], v[210:213], v[18:21]
	v_mfma_f32_16x16x32_bf16 v[6:9], v[172:175], v[218:221], v[6:9]
	v_mfma_f32_16x16x32_bf16 v[2:5], v[186:189], v[218:221], v[2:5]
	s_barrier
	s_setprio 0
	s_add_i32 s71, s71, 2
	s_add_u32 s22, s22, 0x100
	s_addc_u32 s23, s23, 0
	s_add_u32 s69, s69, 0x100
	s_addc_u32 s70, s70, 0
	s_cmp_gt_u32 s71, 5
	s_cbranch_scc0 .LBB0_2146
	s_and_b64 vcc, exec, s[10:11]
	s_cbranch_vccz .LBB0_2149
	s_barrier

.LBB0_2322:
	ds_read_b128 v[144:147], v150
	ds_read_b128 v[154:157], v150 offset:1024
	ds_read_b128 v[158:161], v150 offset:2048
	ds_read_b128 v[162:165], v150 offset:3072
	ds_read_b128 v[166:169], v151
	ds_read_b128 v[170:173], v151 offset:1024
	ds_read_b128 v[174:177], v151 offset:2048
	ds_read_b128 v[182:185], v151 offset:3072
	s_add_i32 s72, s30, 2
	s_add_u32 s31, s28, 0xfff80080
	s_addc_u32 s34, s29, -1
	s_cmp_eq_u32 s17, s30
	s_cselect_b32 s30, s26, s19
	s_cselect_b32 s35, s23, s34
	s_cselect_b32 s34, s22, s31
	s_cselect_b32 s31, s27, s21
	v_lshl_add_u64 v[218:219], s[28:29], 0, v[138:139]
	s_add_i32 m0, s3, 0xc000
	ds_read_b128 v[186:189], v152
	ds_read_b128 v[190:193], v152 offset:1024
	ds_read_b128 v[194:197], v152 offset:2048
	ds_read_b128 v[198:201], v152 offset:3072
	ds_read_b128 v[202:205], v152 offset:4096
	ds_read_b128 v[206:209], v152 offset:5120
	ds_read_b128 v[210:213], v152 offset:6144
	ds_read_b128 v[214:217], v152 offset:7168
	global_load_lds_dwordx4 v[218:219], off
	v_lshl_add_u64 v[218:219], s[28:29], 0, v[140:141]
	s_add_i32 m0, s3, 0xe000
	s_nop 0
	global_load_lds_dwordx4 v[218:219], off
	s_waitcnt vmcnt(8)
	s_waitcnt lgkmcnt(0)
	s_setprio 1
	s_barrier
	v_mfma_f32_16x16x32_bf16 v[126:129], v[144:147], v[186:189], v[126:129]
	v_mfma_f32_16x16x32_bf16 v[122:125], v[158:161], v[186:189], v[122:125]
	v_mfma_f32_16x16x32_bf16 v[118:121], v[144:147], v[194:197], v[118:121]
	v_mfma_f32_16x16x32_bf16 v[114:117], v[158:161], v[194:197], v[114:117]
	v_mfma_f32_16x16x32_bf16 v[106:109], v[144:147], v[202:205], v[106:109]
	v_mfma_f32_16x16x32_bf16 v[98:101], v[158:161], v[202:205], v[98:101]
	v_mfma_f32_16x16x32_bf16 v[90:93], v[144:147], v[210:213], v[90:93]
	v_mfma_f32_16x16x32_bf16 v[82:85], v[158:161], v[210:213], v[82:85]
	v_mfma_f32_16x16x32_bf16 v[126:129], v[154:157], v[190:193], v[126:129]
	v_mfma_f32_16x16x32_bf16 v[122:125], v[162:165], v[190:193], v[122:125]
	v_mfma_f32_16x16x32_bf16 v[118:121], v[154:157], v[198:201], v[118:121]
	v_mfma_f32_16x16x32_bf16 v[114:117], v[162:165], v[198:201], v[114:117]
	v_mfma_f32_16x16x32_bf16 v[106:109], v[154:157], v[206:209], v[106:109]
	v_mfma_f32_16x16x32_bf16 v[98:101], v[162:165], v[206:209], v[98:101]
	v_mfma_f32_16x16x32_bf16 v[90:93], v[154:157], v[214:217], v[90:93]
	v_mfma_f32_16x16x32_bf16 v[82:85], v[162:165], v[214:217], v[82:85]
	v_mfma_f32_16x16x32_bf16 v[110:113], v[166:169], v[186:189], v[110:113]
	v_mfma_f32_16x16x32_bf16 v[102:105], v[174:177], v[186:189], v[102:105]
	v_mfma_f32_16x16x32_bf16 v[94:97], v[166:169], v[194:197], v[94:97]
	v_mfma_f32_16x16x32_bf16 v[86:89], v[174:177], v[194:197], v[86:89]
	v_mfma_f32_16x16x32_bf16 v[78:81], v[166:169], v[202:205], v[78:81]
	v_mfma_f32_16x16x32_bf16 v[74:77], v[174:177], v[202:205], v[74:77]
	v_mfma_f32_16x16x32_bf16 v[70:73], v[166:169], v[210:213], v[70:73]
	v_mfma_f32_16x16x32_bf16 v[66:69], v[174:177], v[210:213], v[66:69]
	v_mfma_f32_16x16x32_bf16 v[110:113], v[170:173], v[190:193], v[110:113]
	v_mfma_f32_16x16x32_bf16 v[102:105], v[182:185], v[190:193], v[102:105]
	v_mfma_f32_16x16x32_bf16 v[94:97], v[170:173], v[198:201], v[94:97]
	v_mfma_f32_16x16x32_bf16 v[86:89], v[182:185], v[198:201], v[86:89]
	v_mfma_f32_16x16x32_bf16 v[78:81], v[170:173], v[206:209], v[78:81]
	v_mfma_f32_16x16x32_bf16 v[74:77], v[182:185], v[206:209], v[74:77]
	v_mfma_f32_16x16x32_bf16 v[70:73], v[170:173], v[214:217], v[70:73]
	v_mfma_f32_16x16x32_bf16 v[66:69], v[182:185], v[214:217], v[66:69]
	s_barrier
	s_setprio 0
	s_add_i32 s73, s63, s52
	v_lshl_add_u64 v[218:219], s[30:31], 0, v[132:133]
	s_mov_b32 m0, s73
	ds_read_b128 v[186:189], v152 offset:16384
	ds_read_b128 v[190:193], v152 offset:17408
	ds_read_b128 v[194:197], v152 offset:18432
	ds_read_b128 v[198:201], v152 offset:19456
	ds_read_b128 v[202:205], v152 offset:20480
	ds_read_b128 v[206:209], v152 offset:21504
	ds_read_b128 v[210:213], v152 offset:22528
	ds_read_b128 v[214:217], v152 offset:23552
	global_load_lds_dwordx4 v[218:219], off
	s_add_i32 m0, s73, 0x2000
	s_add_u32 s76, s30, 0x80000
	v_lshl_add_u64 v[220:221], s[30:31], 0, v[136:137]
	s_addc_u32 s77, s31, 0
	s_add_i32 s73, s66, s52
	global_load_lds_dwordx4 v[220:221], off
	v_lshl_add_u64 v[222:223], s[76:77], 0, v[132:133]
	s_mov_b32 m0, s73
	v_lshl_add_u64 v[224:225], s[34:35], 0, v[134:135]
	global_load_lds_dwordx4 v[222:223], off
	v_lshl_add_u64 v[222:223], s[76:77], 0, v[136:137]
	s_add_i32 m0, s73, 0x2000
	s_nop 0
	global_load_lds_dwordx4 v[222:223], off
	v_lshl_add_u64 v[222:223], s[34:35], 0, v[130:131]
	s_mov_b32 m0, s3
	s_nop 0
	global_load_lds_dwordx4 v[222:223], off
	s_mov_b32 m0, s54
	s_nop 0
	global_load_lds_dwordx4 v[224:225], off
	s_waitcnt vmcnt(8)
	s_waitcnt lgkmcnt(0)
	s_setprio 1
	s_barrier
	v_mfma_f32_16x16x32_bf16 v[62:65], v[144:147], v[186:189], v[62:65]
	v_mfma_f32_16x16x32_bf16 v[58:61], v[158:161], v[186:189], v[58:61]
	v_mfma_f32_16x16x32_bf16 v[54:57], v[144:147], v[194:197], v[54:57]
	v_mfma_f32_16x16x32_bf16 v[50:53], v[158:161], v[194:197], v[50:53]
	v_mfma_f32_16x16x32_bf16 v[42:45], v[144:147], v[202:205], v[42:45]
	v_mfma_f32_16x16x32_bf16 v[34:37], v[158:161], v[202:205], v[34:37]
	v_mfma_f32_16x16x32_bf16 v[26:29], v[144:147], v[210:213], v[26:29]
	v_mfma_f32_16x16x32_bf16 v[18:21], v[158:161], v[210:213], v[18:21]
	v_mfma_f32_16x16x32_bf16 v[62:65], v[154:157], v[190:193], v[62:65]
	v_mfma_f32_16x16x32_bf16 v[58:61], v[162:165], v[190:193], v[58:61]
	v_mfma_f32_16x16x32_bf16 v[54:57], v[154:157], v[198:201], v[54:57]
	v_mfma_f32_16x16x32_bf16 v[50:53], v[162:165], v[198:201], v[50:53]
	v_mfma_f32_16x16x32_bf16 v[42:45], v[154:157], v[206:209], v[42:45]
	v_mfma_f32_16x16x32_bf16 v[34:37], v[162:165], v[206:209], v[34:37]
	v_mfma_f32_16x16x32_bf16 v[26:29], v[154:157], v[214:217], v[26:29]
	v_mfma_f32_16x16x32_bf16 v[18:21], v[162:165], v[214:217], v[18:21]
	v_mfma_f32_16x16x32_bf16 v[46:49], v[166:169], v[186:189], v[46:49]
	v_mfma_f32_16x16x32_bf16 v[38:41], v[174:177], v[186:189], v[38:41]
	v_mfma_f32_16x16x32_bf16 v[30:33], v[166:169], v[194:197], v[30:33]
	v_mfma_f32_16x16x32_bf16 v[22:25], v[174:177], v[194:197], v[22:25]
	v_mfma_f32_16x16x32_bf16 v[14:17], v[166:169], v[202:205], v[14:17]
	v_mfma_f32_16x16x32_bf16 v[10:13], v[174:177], v[202:205], v[10:13]
	v_mfma_f32_16x16x32_bf16 v[6:9], v[166:169], v[210:213], v[6:9]
	v_mfma_f32_16x16x32_bf16 v[2:5], v[174:177], v[210:213], v[2:5]
	v_mfma_f32_16x16x32_bf16 v[46:49], v[170:173], v[190:193], v[46:49]
	v_mfma_f32_16x16x32_bf16 v[38:41], v[182:185], v[190:193], v[38:41]
	v_mfma_f32_16x16x32_bf16 v[30:33], v[170:173], v[198:201], v[30:33]
	v_mfma_f32_16x16x32_bf16 v[22:25], v[182:185], v[198:201], v[22:25]
	v_mfma_f32_16x16x32_bf16 v[14:17], v[170:173], v[206:209], v[14:17]
	v_mfma_f32_16x16x32_bf16 v[10:13], v[182:185], v[206:209], v[10:13]
	v_mfma_f32_16x16x32_bf16 v[6:9], v[170:173], v[214:217], v[6:9]
	v_mfma_f32_16x16x32_bf16 v[2:5], v[182:185], v[214:217], v[2:5]
	s_barrier
	s_setprio 0
	s_add_i32 s73, 0, 0x18000
	v_add_u32_e32 v153, s73, v148
	s_add_i32 s76, 0, 0x1c000
	ds_read_b128 v[144:147], v153
	ds_read_b128 v[154:157], v153 offset:1024
	ds_read_b128 v[158:161], v153 offset:2048
	ds_read_b128 v[162:165], v153 offset:3072
	v_add_u32_e32 v153, s76, v148
	ds_read_b128 v[166:169], v153
	ds_read_b128 v[170:173], v153 offset:1024
	ds_read_b128 v[174:177], v153 offset:2048
	ds_read_b128 v[182:185], v153 offset:3072
	s_add_u32 s34, s34, 0x80000
	s_addc_u32 s35, s35, 0
	s_mov_b32 m0, s55
	v_lshl_add_u64 v[226:227], s[34:35], 0, v[130:131]
	ds_read_b128 v[186:189], v152 offset:32768
	ds_read_b128 v[190:193], v152 offset:33792
	ds_read_b128 v[194:197], v152 offset:34816
	ds_read_b128 v[198:201], v152 offset:35840
	ds_read_b128 v[202:205], v152 offset:36864
	ds_read_b128 v[206:209], v152 offset:37888
	ds_read_b128 v[210:213], v152 offset:38912
	ds_read_b128 v[214:217], v152 offset:39936
	global_load_lds_dwordx4 v[226:227], off
	v_lshl_add_u64 v[226:227], s[34:35], 0, v[134:135]
	s_mov_b32 m0, s56
	s_nop 0
	global_load_lds_dwordx4 v[226:227], off
	s_waitcnt vmcnt(8)
	s_waitcnt lgkmcnt(0)
	s_setprio 1
	s_barrier
	v_mfma_f32_16x16x32_bf16 v[126:129], v[144:147], v[186:189], v[126:129]
	v_mfma_f32_16x16x32_bf16 v[122:125], v[158:161], v[186:189], v[122:125]
	v_mfma_f32_16x16x32_bf16 v[118:121], v[144:147], v[194:197], v[118:121]
	v_mfma_f32_16x16x32_bf16 v[114:117], v[158:161], v[194:197], v[114:117]
	v_mfma_f32_16x16x32_bf16 v[106:109], v[144:147], v[202:205], v[106:109]
	v_mfma_f32_16x16x32_bf16 v[98:101], v[158:161], v[202:205], v[98:101]
	v_mfma_f32_16x16x32_bf16 v[90:93], v[144:147], v[210:213], v[90:93]
	v_mfma_f32_16x16x32_bf16 v[82:85], v[158:161], v[210:213], v[82:85]
	v_mfma_f32_16x16x32_bf16 v[126:129], v[154:157], v[190:193], v[126:129]
	v_mfma_f32_16x16x32_bf16 v[122:125], v[162:165], v[190:193], v[122:125]
	v_mfma_f32_16x16x32_bf16 v[118:121], v[154:157], v[198:201], v[118:121]
	v_mfma_f32_16x16x32_bf16 v[114:117], v[162:165], v[198:201], v[114:117]
	v_mfma_f32_16x16x32_bf16 v[106:109], v[154:157], v[206:209], v[106:109]
	v_mfma_f32_16x16x32_bf16 v[98:101], v[162:165], v[206:209], v[98:101]
	v_mfma_f32_16x16x32_bf16 v[90:93], v[154:157], v[214:217], v[90:93]
	v_mfma_f32_16x16x32_bf16 v[82:85], v[162:165], v[214:217], v[82:85]
	v_mfma_f32_16x16x32_bf16 v[110:113], v[166:169], v[186:189], v[110:113]
	v_mfma_f32_16x16x32_bf16 v[102:105], v[174:177], v[186:189], v[102:105]
	v_mfma_f32_16x16x32_bf16 v[94:97], v[166:169], v[194:197], v[94:97]
	v_mfma_f32_16x16x32_bf16 v[86:89], v[174:177], v[194:197], v[86:89]
	v_mfma_f32_16x16x32_bf16 v[78:81], v[166:169], v[202:205], v[78:81]
	v_mfma_f32_16x16x32_bf16 v[74:77], v[174:177], v[202:205], v[74:77]
	v_mfma_f32_16x16x32_bf16 v[70:73], v[166:169], v[210:213], v[70:73]
	v_mfma_f32_16x16x32_bf16 v[66:69], v[174:177], v[210:213], v[66:69]
	v_mfma_f32_16x16x32_bf16 v[110:113], v[170:173], v[190:193], v[110:113]
	v_mfma_f32_16x16x32_bf16 v[102:105], v[182:185], v[190:193], v[102:105]
	v_mfma_f32_16x16x32_bf16 v[94:97], v[170:173], v[198:201], v[94:97]
	v_mfma_f32_16x16x32_bf16 v[86:89], v[182:185], v[198:201], v[86:89]
	v_mfma_f32_16x16x32_bf16 v[78:81], v[170:173], v[206:209], v[78:81]
	v_mfma_f32_16x16x32_bf16 v[74:77], v[182:185], v[206:209], v[74:77]
	v_mfma_f32_16x16x32_bf16 v[70:73], v[170:173], v[214:217], v[70:73]
	v_mfma_f32_16x16x32_bf16 v[66:69], v[182:185], v[214:217], v[66:69]
	s_barrier
	s_setprio 0
	s_add_i32 s34, s73, s52
	v_lshl_add_u64 v[218:219], v[218:219], 0, s[6:7]
	s_mov_b32 m0, s34
	ds_read_b128 v[186:189], v152 offset:49152
	ds_read_b128 v[190:193], v152 offset:50176
	ds_read_b128 v[194:197], v152 offset:51200
	ds_read_b128 v[198:201], v152 offset:52224
	ds_read_b128 v[202:205], v152 offset:53248
	ds_read_b128 v[206:209], v152 offset:54272
	ds_read_b128 v[210:213], v152 offset:55296
	ds_read_b128 v[214:217], v152 offset:56320
	global_load_lds_dwordx4 v[218:219], off
	s_add_i32 m0, s34, 0x2000
	s_add_u32 s30, s30, 0x80080
	v_lshl_add_u64 v[218:219], v[220:221], 0, s[6:7]
	s_addc_u32 s31, s31, 0
	s_add_i32 s34, s76, s52
	global_load_lds_dwordx4 v[218:219], off
	v_lshl_add_u64 v[218:219], s[30:31], 0, v[132:133]
	s_mov_b32 m0, s34
	s_nop 0
	global_load_lds_dwordx4 v[218:219], off
	v_lshl_add_u64 v[218:219], s[30:31], 0, v[136:137]
	s_add_i32 m0, s34, 0x2000
	s_nop 0
	global_load_lds_dwordx4 v[218:219], off
	v_lshl_add_u64 v[218:219], v[222:223], 0, s[6:7]
	s_mov_b32 m0, s58
	s_nop 0
	global_load_lds_dwordx4 v[218:219], off
	v_lshl_add_u64 v[218:219], v[224:225], 0, s[6:7]
	s_mov_b32 m0, s59
	s_nop 0
	global_load_lds_dwordx4 v[218:219], off
	s_waitcnt vmcnt(8)
	s_waitcnt lgkmcnt(0)
	s_setprio 1
	s_barrier
	v_mfma_f32_16x16x32_bf16 v[62:65], v[144:147], v[186:189], v[62:65]
	v_mfma_f32_16x16x32_bf16 v[58:61], v[158:161], v[186:189], v[58:61]
	v_mfma_f32_16x16x32_bf16 v[54:57], v[144:147], v[194:197], v[54:57]
	v_mfma_f32_16x16x32_bf16 v[50:53], v[158:161], v[194:197], v[50:53]
	v_mfma_f32_16x16x32_bf16 v[42:45], v[144:147], v[202:205], v[42:45]
	v_mfma_f32_16x16x32_bf16 v[34:37], v[158:161], v[202:205], v[34:37]
	v_mfma_f32_16x16x32_bf16 v[26:29], v[144:147], v[210:213], v[26:29]
	v_mfma_f32_16x16x32_bf16 v[18:21], v[158:161], v[210:213], v[18:21]
	v_mfma_f32_16x16x32_bf16 v[62:65], v[154:157], v[190:193], v[62:65]
	v_mfma_f32_16x16x32_bf16 v[58:61], v[162:165], v[190:193], v[58:61]
	v_mfma_f32_16x16x32_bf16 v[54:57], v[154:157], v[198:201], v[54:57]
	v_mfma_f32_16x16x32_bf16 v[50:53], v[162:165], v[198:201], v[50:53]
	v_mfma_f32_16x16x32_bf16 v[42:45], v[154:157], v[206:209], v[42:45]
	v_mfma_f32_16x16x32_bf16 v[34:37], v[162:165], v[206:209], v[34:37]
	v_mfma_f32_16x16x32_bf16 v[26:29], v[154:157], v[214:217], v[26:29]
	v_mfma_f32_16x16x32_bf16 v[18:21], v[162:165], v[214:217], v[18:21]
	v_mfma_f32_16x16x32_bf16 v[46:49], v[166:169], v[186:189], v[46:49]
	v_mfma_f32_16x16x32_bf16 v[38:41], v[174:177], v[186:189], v[38:41]
	v_mfma_f32_16x16x32_bf16 v[30:33], v[166:169], v[194:197], v[30:33]
	v_mfma_f32_16x16x32_bf16 v[22:25], v[174:177], v[194:197], v[22:25]
	v_mfma_f32_16x16x32_bf16 v[14:17], v[166:169], v[202:205], v[14:17]
	v_mfma_f32_16x16x32_bf16 v[10:13], v[174:177], v[202:205], v[10:13]
	v_mfma_f32_16x16x32_bf16 v[6:9], v[166:169], v[210:213], v[6:9]
	v_mfma_f32_16x16x32_bf16 v[2:5], v[174:177], v[210:213], v[2:5]
	v_mfma_f32_16x16x32_bf16 v[46:49], v[170:173], v[190:193], v[46:49]
	v_mfma_f32_16x16x32_bf16 v[38:41], v[182:185], v[190:193], v[38:41]
	v_mfma_f32_16x16x32_bf16 v[30:33], v[170:173], v[198:201], v[30:33]
	v_mfma_f32_16x16x32_bf16 v[22:25], v[182:185], v[198:201], v[22:25]
	v_mfma_f32_16x16x32_bf16 v[14:17], v[170:173], v[206:209], v[14:17]
	v_mfma_f32_16x16x32_bf16 v[10:13], v[182:185], v[206:209], v[10:13]
	v_mfma_f32_16x16x32_bf16 v[6:9], v[170:173], v[214:217], v[6:9]
	v_mfma_f32_16x16x32_bf16 v[2:5], v[182:185], v[214:217], v[2:5]
	s_barrier
	s_setprio 0
	s_add_u32 s28, s28, 0x100
	s_addc_u32 s29, s29, 0
	s_add_u32 s19, s19, 0x100
	s_addc_u32 s21, s21, 0
	s_cmp_ge_i32 s72, s71
	s_mov_b32 s30, s72
	s_cbranch_scc0 .LBB0_2322
	s_and_b64 vcc, exec, s[8:9]
	s_cbranch_vccz .LBB0_2325
	s_barrier

.LBB0_2565:
	ds_read_b128 v[144:147], v151
	ds_read_b128 v[154:157], v151 offset:1024
	ds_read_b128 v[158:161], v151 offset:2048
	ds_read_b128 v[162:165], v151 offset:3072
	ds_read_b128 v[166:169], v152
	ds_read_b128 v[170:173], v152 offset:1024
	ds_read_b128 v[174:177], v152 offset:2048
	ds_read_b128 v[182:185], v152 offset:3072
	s_add_i32 s71, s22, 2
	s_add_u32 s23, s20, 0xffea0080
	s_addc_u32 s26, s21, -1
	s_cmp_eq_u32 s68, s22
	s_cselect_b32 s22, s18, s69
	s_cselect_b32 s27, s17, s26
	s_cselect_b32 s26, s16, s23
	s_cselect_b32 s23, s19, s70
	v_lshl_add_u64 v[218:219], s[20:21], 0, v[138:139]
	s_add_i32 m0, s35, 0xc000
	ds_read_b128 v[186:189], v153
	ds_read_b128 v[190:193], v153 offset:1024
	ds_read_b128 v[194:197], v153 offset:2048
	ds_read_b128 v[198:201], v153 offset:3072
	ds_read_b128 v[202:205], v153 offset:4096
	ds_read_b128 v[206:209], v153 offset:5120
	ds_read_b128 v[210:213], v153 offset:6144
	ds_read_b128 v[214:217], v153 offset:7168
	global_load_lds_dwordx4 v[218:219], off
	v_lshl_add_u64 v[218:219], s[20:21], 0, v[140:141]
	s_add_i32 m0, s35, 0xe000
	s_nop 0
	global_load_lds_dwordx4 v[218:219], off
	s_waitcnt vmcnt(8)
	s_waitcnt lgkmcnt(0)
	s_setprio 1
	s_barrier
	v_mfma_f32_16x16x32_bf16 v[126:129], v[144:147], v[186:189], v[126:129]
	v_mfma_f32_16x16x32_bf16 v[122:125], v[158:161], v[186:189], v[122:125]
	v_mfma_f32_16x16x32_bf16 v[118:121], v[144:147], v[194:197], v[118:121]
	v_mfma_f32_16x16x32_bf16 v[114:117], v[158:161], v[194:197], v[114:117]
	v_mfma_f32_16x16x32_bf16 v[106:109], v[144:147], v[202:205], v[106:109]
	v_mfma_f32_16x16x32_bf16 v[98:101], v[158:161], v[202:205], v[98:101]
	v_mfma_f32_16x16x32_bf16 v[90:93], v[144:147], v[210:213], v[90:93]
	v_mfma_f32_16x16x32_bf16 v[82:85], v[158:161], v[210:213], v[82:85]
	v_mfma_f32_16x16x32_bf16 v[126:129], v[154:157], v[190:193], v[126:129]
	v_mfma_f32_16x16x32_bf16 v[122:125], v[162:165], v[190:193], v[122:125]
	v_mfma_f32_16x16x32_bf16 v[118:121], v[154:157], v[198:201], v[118:121]
	v_mfma_f32_16x16x32_bf16 v[114:117], v[162:165], v[198:201], v[114:117]
	v_mfma_f32_16x16x32_bf16 v[106:109], v[154:157], v[206:209], v[106:109]
	v_mfma_f32_16x16x32_bf16 v[98:101], v[162:165], v[206:209], v[98:101]
	v_mfma_f32_16x16x32_bf16 v[90:93], v[154:157], v[214:217], v[90:93]
	v_mfma_f32_16x16x32_bf16 v[82:85], v[162:165], v[214:217], v[82:85]
	v_mfma_f32_16x16x32_bf16 v[110:113], v[166:169], v[186:189], v[110:113]
	v_mfma_f32_16x16x32_bf16 v[102:105], v[174:177], v[186:189], v[102:105]
	v_mfma_f32_16x16x32_bf16 v[94:97], v[166:169], v[194:197], v[94:97]
	v_mfma_f32_16x16x32_bf16 v[86:89], v[174:177], v[194:197], v[86:89]
	v_mfma_f32_16x16x32_bf16 v[78:81], v[166:169], v[202:205], v[78:81]
	v_mfma_f32_16x16x32_bf16 v[74:77], v[174:177], v[202:205], v[74:77]
	v_mfma_f32_16x16x32_bf16 v[70:73], v[166:169], v[210:213], v[70:73]
	v_mfma_f32_16x16x32_bf16 v[66:69], v[174:177], v[210:213], v[66:69]
	v_mfma_f32_16x16x32_bf16 v[110:113], v[170:173], v[190:193], v[110:113]
	v_mfma_f32_16x16x32_bf16 v[102:105], v[182:185], v[190:193], v[102:105]
	v_mfma_f32_16x16x32_bf16 v[94:97], v[170:173], v[198:201], v[94:97]
	v_mfma_f32_16x16x32_bf16 v[86:89], v[182:185], v[198:201], v[86:89]
	v_mfma_f32_16x16x32_bf16 v[78:81], v[170:173], v[206:209], v[78:81]
	v_mfma_f32_16x16x32_bf16 v[74:77], v[182:185], v[206:209], v[74:77]
	v_mfma_f32_16x16x32_bf16 v[70:73], v[170:173], v[214:217], v[70:73]
	v_mfma_f32_16x16x32_bf16 v[66:69], v[182:185], v[214:217], v[66:69]
	s_barrier
	s_setprio 0
	s_add_i32 s72, s52, s31
	v_lshl_add_u64 v[218:219], s[22:23], 0, v[132:133]
	s_mov_b32 m0, s72
	ds_read_b128 v[186:189], v153 offset:16384
	ds_read_b128 v[190:193], v153 offset:17408
	ds_read_b128 v[194:197], v153 offset:18432
	ds_read_b128 v[198:201], v153 offset:19456
	ds_read_b128 v[202:205], v153 offset:20480
	ds_read_b128 v[206:209], v153 offset:21504
	ds_read_b128 v[210:213], v153 offset:22528
	ds_read_b128 v[214:217], v153 offset:23552
	global_load_lds_dwordx4 v[218:219], off
	s_add_i32 m0, s72, 0x2000
	s_add_u32 s72, s22, 0x160000
	v_lshl_add_u64 v[220:221], s[22:23], 0, v[136:137]
	s_addc_u32 s73, s23, 0
	s_add_i32 s76, s53, s31
	global_load_lds_dwordx4 v[220:221], off
	v_lshl_add_u64 v[222:223], s[72:73], 0, v[132:133]
	s_mov_b32 m0, s76
	v_lshl_add_u64 v[224:225], s[26:27], 0, v[134:135]
	global_load_lds_dwordx4 v[222:223], off
	v_lshl_add_u64 v[222:223], s[72:73], 0, v[136:137]
	s_add_i32 m0, s76, 0x2000
	s_nop 0
	global_load_lds_dwordx4 v[222:223], off
	v_lshl_add_u64 v[222:223], s[26:27], 0, v[130:131]
	s_mov_b32 m0, s35
	s_nop 0
	global_load_lds_dwordx4 v[222:223], off
	s_mov_b32 m0, s36
	s_nop 0
	global_load_lds_dwordx4 v[224:225], off
	s_waitcnt vmcnt(8)
	s_waitcnt lgkmcnt(0)
	s_setprio 1
	s_barrier
	v_mfma_f32_16x16x32_bf16 v[62:65], v[144:147], v[186:189], v[62:65]
	v_mfma_f32_16x16x32_bf16 v[58:61], v[158:161], v[186:189], v[58:61]
	v_mfma_f32_16x16x32_bf16 v[54:57], v[144:147], v[194:197], v[54:57]
	v_mfma_f32_16x16x32_bf16 v[50:53], v[158:161], v[194:197], v[50:53]
	v_mfma_f32_16x16x32_bf16 v[42:45], v[144:147], v[202:205], v[42:45]
	v_mfma_f32_16x16x32_bf16 v[34:37], v[158:161], v[202:205], v[34:37]
	v_mfma_f32_16x16x32_bf16 v[26:29], v[144:147], v[210:213], v[26:29]
	v_mfma_f32_16x16x32_bf16 v[18:21], v[158:161], v[210:213], v[18:21]
	v_mfma_f32_16x16x32_bf16 v[62:65], v[154:157], v[190:193], v[62:65]
	v_mfma_f32_16x16x32_bf16 v[58:61], v[162:165], v[190:193], v[58:61]
	v_mfma_f32_16x16x32_bf16 v[54:57], v[154:157], v[198:201], v[54:57]
	v_mfma_f32_16x16x32_bf16 v[50:53], v[162:165], v[198:201], v[50:53]
	v_mfma_f32_16x16x32_bf16 v[42:45], v[154:157], v[206:209], v[42:45]
	v_mfma_f32_16x16x32_bf16 v[34:37], v[162:165], v[206:209], v[34:37]
	v_mfma_f32_16x16x32_bf16 v[26:29], v[154:157], v[214:217], v[26:29]
	v_mfma_f32_16x16x32_bf16 v[18:21], v[162:165], v[214:217], v[18:21]
	v_mfma_f32_16x16x32_bf16 v[46:49], v[166:169], v[186:189], v[46:49]
	v_mfma_f32_16x16x32_bf16 v[38:41], v[174:177], v[186:189], v[38:41]
	v_mfma_f32_16x16x32_bf16 v[30:33], v[166:169], v[194:197], v[30:33]
	v_mfma_f32_16x16x32_bf16 v[22:25], v[174:177], v[194:197], v[22:25]
	v_mfma_f32_16x16x32_bf16 v[14:17], v[166:169], v[202:205], v[14:17]
	v_mfma_f32_16x16x32_bf16 v[10:13], v[174:177], v[202:205], v[10:13]
	v_mfma_f32_16x16x32_bf16 v[6:9], v[166:169], v[210:213], v[6:9]
	v_mfma_f32_16x16x32_bf16 v[2:5], v[174:177], v[210:213], v[2:5]
	v_mfma_f32_16x16x32_bf16 v[46:49], v[170:173], v[190:193], v[46:49]
	v_mfma_f32_16x16x32_bf16 v[38:41], v[182:185], v[190:193], v[38:41]
	v_mfma_f32_16x16x32_bf16 v[30:33], v[170:173], v[198:201], v[30:33]
	v_mfma_f32_16x16x32_bf16 v[22:25], v[182:185], v[198:201], v[22:25]
	v_mfma_f32_16x16x32_bf16 v[14:17], v[170:173], v[206:209], v[14:17]
	v_mfma_f32_16x16x32_bf16 v[10:13], v[182:185], v[206:209], v[10:13]
	v_mfma_f32_16x16x32_bf16 v[6:9], v[170:173], v[214:217], v[6:9]
	v_mfma_f32_16x16x32_bf16 v[2:5], v[182:185], v[214:217], v[2:5]
	s_barrier
	s_setprio 0
	s_add_i32 s72, 0, 0x18000
	s_add_i32 s73, 0, 0x1c000
	v_add_u32_e32 v162, s72, v149
	v_add_u32_e32 v179, s73, v149
	ds_read_b128 v[144:147], v162
	ds_read_b128 v[154:157], v162 offset:1024
	ds_read_b128 v[158:161], v162 offset:2048
	ds_read_b128 v[162:165], v162 offset:3072
	ds_read_b128 v[166:169], v179
	ds_read_b128 v[170:173], v179 offset:1024
	ds_read_b128 v[174:177], v179 offset:2048
	ds_read_b128 v[182:185], v179 offset:3072
	s_add_u32 s26, s26, 0x160000
	s_addc_u32 s27, s27, 0
	s_mov_b32 m0, s37
	v_lshl_add_u64 v[226:227], s[26:27], 0, v[130:131]
	ds_read_b128 v[186:189], v153 offset:32768
	ds_read_b128 v[190:193], v153 offset:33792
	ds_read_b128 v[194:197], v153 offset:34816
	ds_read_b128 v[198:201], v153 offset:35840
	ds_read_b128 v[202:205], v153 offset:36864
	ds_read_b128 v[206:209], v153 offset:37888
	ds_read_b128 v[210:213], v153 offset:38912
	ds_read_b128 v[214:217], v153 offset:39936
	global_load_lds_dwordx4 v[226:227], off
	v_lshl_add_u64 v[226:227], s[26:27], 0, v[134:135]
	s_mov_b32 m0, s38
	s_nop 0
	global_load_lds_dwordx4 v[226:227], off
	s_waitcnt vmcnt(8)
	s_waitcnt lgkmcnt(0)
	s_setprio 1
	s_barrier
	v_mfma_f32_16x16x32_bf16 v[126:129], v[144:147], v[186:189], v[126:129]
	v_mfma_f32_16x16x32_bf16 v[122:125], v[158:161], v[186:189], v[122:125]
	v_mfma_f32_16x16x32_bf16 v[118:121], v[144:147], v[194:197], v[118:121]
	v_mfma_f32_16x16x32_bf16 v[114:117], v[158:161], v[194:197], v[114:117]
	v_mfma_f32_16x16x32_bf16 v[106:109], v[144:147], v[202:205], v[106:109]
	v_mfma_f32_16x16x32_bf16 v[98:101], v[158:161], v[202:205], v[98:101]
	v_mfma_f32_16x16x32_bf16 v[90:93], v[144:147], v[210:213], v[90:93]
	v_mfma_f32_16x16x32_bf16 v[82:85], v[158:161], v[210:213], v[82:85]
	v_mfma_f32_16x16x32_bf16 v[126:129], v[154:157], v[190:193], v[126:129]
	v_mfma_f32_16x16x32_bf16 v[122:125], v[162:165], v[190:193], v[122:125]
	v_mfma_f32_16x16x32_bf16 v[118:121], v[154:157], v[198:201], v[118:121]
	v_mfma_f32_16x16x32_bf16 v[114:117], v[162:165], v[198:201], v[114:117]
	v_mfma_f32_16x16x32_bf16 v[106:109], v[154:157], v[206:209], v[106:109]
	v_mfma_f32_16x16x32_bf16 v[98:101], v[162:165], v[206:209], v[98:101]
	v_mfma_f32_16x16x32_bf16 v[90:93], v[154:157], v[214:217], v[90:93]
	v_mfma_f32_16x16x32_bf16 v[82:85], v[162:165], v[214:217], v[82:85]
	v_mfma_f32_16x16x32_bf16 v[110:113], v[166:169], v[186:189], v[110:113]
	v_mfma_f32_16x16x32_bf16 v[102:105], v[174:177], v[186:189], v[102:105]
	v_mfma_f32_16x16x32_bf16 v[94:97], v[166:169], v[194:197], v[94:97]
	v_mfma_f32_16x16x32_bf16 v[86:89], v[174:177], v[194:197], v[86:89]
	v_mfma_f32_16x16x32_bf16 v[78:81], v[166:169], v[202:205], v[78:81]
	v_mfma_f32_16x16x32_bf16 v[74:77], v[174:177], v[202:205], v[74:77]
	v_mfma_f32_16x16x32_bf16 v[70:73], v[166:169], v[210:213], v[70:73]
	v_mfma_f32_16x16x32_bf16 v[66:69], v[174:177], v[210:213], v[66:69]
	v_mfma_f32_16x16x32_bf16 v[110:113], v[170:173], v[190:193], v[110:113]
	v_mfma_f32_16x16x32_bf16 v[102:105], v[182:185], v[190:193], v[102:105]
	v_mfma_f32_16x16x32_bf16 v[94:97], v[170:173], v[198:201], v[94:97]
	v_mfma_f32_16x16x32_bf16 v[86:89], v[182:185], v[198:201], v[86:89]
	v_mfma_f32_16x16x32_bf16 v[78:81], v[170:173], v[206:209], v[78:81]
	v_mfma_f32_16x16x32_bf16 v[74:77], v[182:185], v[206:209], v[74:77]
	v_mfma_f32_16x16x32_bf16 v[70:73], v[170:173], v[214:217], v[70:73]
	v_mfma_f32_16x16x32_bf16 v[66:69], v[182:185], v[214:217], v[66:69]
	s_barrier
	s_setprio 0
	s_add_i32 s26, s72, s31
	v_lshl_add_u64 v[218:219], v[218:219], 0, s[4:5]
	s_mov_b32 m0, s26
	ds_read_b128 v[186:189], v153 offset:49152
	ds_read_b128 v[190:193], v153 offset:50176
	ds_read_b128 v[194:197], v153 offset:51200
	ds_read_b128 v[198:201], v153 offset:52224
	ds_read_b128 v[202:205], v153 offset:53248
	ds_read_b128 v[206:209], v153 offset:54272
	ds_read_b128 v[210:213], v153 offset:55296
	ds_read_b128 v[214:217], v153 offset:56320
	global_load_lds_dwordx4 v[218:219], off
	s_add_i32 m0, s26, 0x2000
	s_add_u32 s22, s22, 0x160080
	v_lshl_add_u64 v[218:219], v[220:221], 0, s[4:5]
	s_addc_u32 s23, s23, 0
	s_add_i32 s26, s73, s31
	global_load_lds_dwordx4 v[218:219], off
	v_lshl_add_u64 v[218:219], s[22:23], 0, v[132:133]
	s_mov_b32 m0, s26
	s_nop 0
	global_load_lds_dwordx4 v[218:219], off
	v_lshl_add_u64 v[218:219], s[22:23], 0, v[136:137]
	s_add_i32 m0, s26, 0x2000
	s_nop 0
	global_load_lds_dwordx4 v[218:219], off
	v_lshl_add_u64 v[218:219], v[222:223], 0, s[4:5]
	s_mov_b32 m0, s42
	s_nop 0
	global_load_lds_dwordx4 v[218:219], off
	v_lshl_add_u64 v[218:219], v[224:225], 0, s[4:5]
	s_mov_b32 m0, s43
	s_nop 0
	global_load_lds_dwordx4 v[218:219], off
	s_waitcnt vmcnt(8)
	s_waitcnt lgkmcnt(0)
	s_setprio 1
	s_barrier
	v_mfma_f32_16x16x32_bf16 v[62:65], v[144:147], v[186:189], v[62:65]
	v_mfma_f32_16x16x32_bf16 v[58:61], v[158:161], v[186:189], v[58:61]
	v_mfma_f32_16x16x32_bf16 v[54:57], v[144:147], v[194:197], v[54:57]
	v_mfma_f32_16x16x32_bf16 v[50:53], v[158:161], v[194:197], v[50:53]
	v_mfma_f32_16x16x32_bf16 v[42:45], v[144:147], v[202:205], v[42:45]
	v_mfma_f32_16x16x32_bf16 v[34:37], v[158:161], v[202:205], v[34:37]
	v_mfma_f32_16x16x32_bf16 v[26:29], v[144:147], v[210:213], v[26:29]
	v_mfma_f32_16x16x32_bf16 v[18:21], v[158:161], v[210:213], v[18:21]
	v_mfma_f32_16x16x32_bf16 v[62:65], v[154:157], v[190:193], v[62:65]
	v_mfma_f32_16x16x32_bf16 v[58:61], v[162:165], v[190:193], v[58:61]
	v_mfma_f32_16x16x32_bf16 v[54:57], v[154:157], v[198:201], v[54:57]
	v_mfma_f32_16x16x32_bf16 v[50:53], v[162:165], v[198:201], v[50:53]
	v_mfma_f32_16x16x32_bf16 v[42:45], v[154:157], v[206:209], v[42:45]
	v_mfma_f32_16x16x32_bf16 v[34:37], v[162:165], v[206:209], v[34:37]
	v_mfma_f32_16x16x32_bf16 v[26:29], v[154:157], v[214:217], v[26:29]
	v_mfma_f32_16x16x32_bf16 v[18:21], v[162:165], v[214:217], v[18:21]
	v_mfma_f32_16x16x32_bf16 v[46:49], v[166:169], v[186:189], v[46:49]
	v_mfma_f32_16x16x32_bf16 v[38:41], v[174:177], v[186:189], v[38:41]
	v_mfma_f32_16x16x32_bf16 v[30:33], v[166:169], v[194:197], v[30:33]
	v_mfma_f32_16x16x32_bf16 v[22:25], v[174:177], v[194:197], v[22:25]
	v_mfma_f32_16x16x32_bf16 v[14:17], v[166:169], v[202:205], v[14:17]
	v_mfma_f32_16x16x32_bf16 v[10:13], v[174:177], v[202:205], v[10:13]
	v_mfma_f32_16x16x32_bf16 v[6:9], v[166:169], v[210:213], v[6:9]
	v_mfma_f32_16x16x32_bf16 v[2:5], v[174:177], v[210:213], v[2:5]
	v_mfma_f32_16x16x32_bf16 v[46:49], v[170:173], v[190:193], v[46:49]
	v_mfma_f32_16x16x32_bf16 v[38:41], v[182:185], v[190:193], v[38:41]
	v_mfma_f32_16x16x32_bf16 v[30:33], v[170:173], v[198:201], v[30:33]
	v_mfma_f32_16x16x32_bf16 v[22:25], v[182:185], v[198:201], v[22:25]
	v_mfma_f32_16x16x32_bf16 v[14:17], v[170:173], v[206:209], v[14:17]
	v_mfma_f32_16x16x32_bf16 v[10:13], v[182:185], v[206:209], v[10:13]
	v_mfma_f32_16x16x32_bf16 v[6:9], v[170:173], v[214:217], v[6:9]
	v_mfma_f32_16x16x32_bf16 v[2:5], v[182:185], v[214:217], v[2:5]
	s_barrier
	s_setprio 0
	s_add_u32 s20, s20, 0x100
	s_addc_u32 s21, s21, 0
	s_add_u32 s69, s69, 0x100
	s_addc_u32 s70, s70, 0
	s_cmp_ge_i32 s71, s67
	s_mov_b32 s22, s71
	s_cbranch_scc0 .LBB0_2565
	s_and_b64 vcc, exec, s[6:7]
	s_cbranch_vccz .LBB0_2568
	s_barrier

.LBB0_2731:
	ds_read_b128 v[146:149], v162
	ds_read_b128 v[150:153], v162 offset:1024
	ds_read_b128 v[166:169], v162 offset:2048
	ds_read_b128 v[170:173], v162 offset:3072
	ds_read_b128 v[174:177], v163
	ds_read_b128 v[182:185], v163 offset:1024
	ds_read_b128 v[186:189], v163 offset:2048
	ds_read_b128 v[190:193], v163 offset:3072
	s_add_u32 s24, s4, 0xfff80080
	s_addc_u32 s25, s5, -1
	s_cmp_eq_u32 s55, 28
	s_cselect_b32 s27, s15, s25
	s_cselect_b32 s26, s47, s24
	s_cselect_b32 s25, s13, s54
	s_cselect_b32 s24, s52, s53
	v_lshl_add_u64 v[226:227], s[4:5], 0, v[138:139]
	s_add_i32 m0, s21, 0xc000
	ds_read_b128 v[194:197], v164
	ds_read_b128 v[198:201], v164 offset:1024
	ds_read_b128 v[202:205], v164 offset:2048
	ds_read_b128 v[206:209], v164 offset:3072
	ds_read_b128 v[210:213], v164 offset:4096
	ds_read_b128 v[214:217], v164 offset:5120
	ds_read_b128 v[218:221], v164 offset:6144
	ds_read_b128 v[222:225], v164 offset:7168
	global_load_lds_dwordx4 v[226:227], off
	v_lshl_add_u64 v[226:227], s[4:5], 0, v[140:141]
	s_add_i32 m0, s21, 0xe000
	s_nop 0
	global_load_lds_dwordx4 v[226:227], off
	s_waitcnt vmcnt(8)
	s_waitcnt lgkmcnt(0)
	s_setprio 1
	s_barrier
	v_mfma_f32_16x16x32_bf16 v[126:129], v[146:149], v[194:197], v[126:129]
	v_mfma_f32_16x16x32_bf16 v[122:125], v[166:169], v[194:197], v[122:125]
	v_mfma_f32_16x16x32_bf16 v[110:113], v[146:149], v[202:205], v[110:113]
	v_mfma_f32_16x16x32_bf16 v[106:109], v[166:169], v[202:205], v[106:109]
	v_mfma_f32_16x16x32_bf16 v[94:97], v[146:149], v[210:213], v[94:97]
	v_mfma_f32_16x16x32_bf16 v[90:93], v[166:169], v[210:213], v[90:93]
	v_mfma_f32_16x16x32_bf16 v[78:81], v[146:149], v[218:221], v[78:81]
	v_mfma_f32_16x16x32_bf16 v[74:77], v[166:169], v[218:221], v[74:77]
	v_mfma_f32_16x16x32_bf16 v[126:129], v[150:153], v[198:201], v[126:129]
	v_mfma_f32_16x16x32_bf16 v[122:125], v[170:173], v[198:201], v[122:125]
	v_mfma_f32_16x16x32_bf16 v[110:113], v[150:153], v[206:209], v[110:113]
	v_mfma_f32_16x16x32_bf16 v[106:109], v[170:173], v[206:209], v[106:109]
	v_mfma_f32_16x16x32_bf16 v[94:97], v[150:153], v[214:217], v[94:97]
	v_mfma_f32_16x16x32_bf16 v[90:93], v[170:173], v[214:217], v[90:93]
	v_mfma_f32_16x16x32_bf16 v[78:81], v[150:153], v[222:225], v[78:81]
	v_mfma_f32_16x16x32_bf16 v[74:77], v[170:173], v[222:225], v[74:77]
	v_mfma_f32_16x16x32_bf16 v[118:121], v[174:177], v[194:197], v[118:121]
	v_mfma_f32_16x16x32_bf16 v[114:117], v[186:189], v[194:197], v[114:117]
	v_mfma_f32_16x16x32_bf16 v[102:105], v[174:177], v[202:205], v[102:105]
	v_mfma_f32_16x16x32_bf16 v[98:101], v[186:189], v[202:205], v[98:101]
	v_mfma_f32_16x16x32_bf16 v[86:89], v[174:177], v[210:213], v[86:89]
	v_mfma_f32_16x16x32_bf16 v[82:85], v[186:189], v[210:213], v[82:85]
	v_mfma_f32_16x16x32_bf16 v[70:73], v[174:177], v[218:221], v[70:73]
	v_mfma_f32_16x16x32_bf16 v[66:69], v[186:189], v[218:221], v[66:69]
	v_mfma_f32_16x16x32_bf16 v[118:121], v[182:185], v[198:201], v[118:121]
	v_mfma_f32_16x16x32_bf16 v[114:117], v[190:193], v[198:201], v[114:117]
	v_mfma_f32_16x16x32_bf16 v[102:105], v[182:185], v[206:209], v[102:105]
	v_mfma_f32_16x16x32_bf16 v[98:101], v[190:193], v[206:209], v[98:101]
	v_mfma_f32_16x16x32_bf16 v[86:89], v[182:185], v[214:217], v[86:89]
	v_mfma_f32_16x16x32_bf16 v[82:85], v[190:193], v[214:217], v[82:85]
	v_mfma_f32_16x16x32_bf16 v[70:73], v[182:185], v[222:225], v[70:73]
	v_mfma_f32_16x16x32_bf16 v[66:69], v[190:193], v[222:225], v[66:69]
	s_barrier
	s_setprio 0
	s_add_i32 s56, s44, s30
	v_lshl_add_u64 v[226:227], s[24:25], 0, v[132:133]
	s_mov_b32 m0, s56
	ds_read_b128 v[194:197], v164 offset:16384
	ds_read_b128 v[198:201], v164 offset:17408
	ds_read_b128 v[202:205], v164 offset:18432
	ds_read_b128 v[206:209], v164 offset:19456
	ds_read_b128 v[210:213], v164 offset:20480
	ds_read_b128 v[214:217], v164 offset:21504
	ds_read_b128 v[218:221], v164 offset:22528
	ds_read_b128 v[222:225], v164 offset:23552
	global_load_lds_dwordx4 v[226:227], off
	s_add_i32 m0, s56, 0x2000
	s_add_u32 s56, s24, 0x80000
	v_lshl_add_u64 v[228:229], s[24:25], 0, v[136:137]
	s_addc_u32 s57, s25, 0
	s_add_i32 s58, s45, s30
	global_load_lds_dwordx4 v[228:229], off
	v_lshl_add_u64 v[230:231], s[56:57], 0, v[132:133]
	s_mov_b32 m0, s58
	v_lshl_add_u64 v[232:233], s[26:27], 0, v[134:135]
	global_load_lds_dwordx4 v[230:231], off
	v_lshl_add_u64 v[230:231], s[56:57], 0, v[136:137]
	s_add_i32 m0, s58, 0x2000
	s_nop 0
	global_load_lds_dwordx4 v[230:231], off
	v_lshl_add_u64 v[230:231], s[26:27], 0, v[130:131]
	s_mov_b32 m0, s21
	s_nop 0
	global_load_lds_dwordx4 v[230:231], off
	s_mov_b32 m0, s23
	s_nop 0
	global_load_lds_dwordx4 v[232:233], off
	s_waitcnt vmcnt(8)
	s_waitcnt lgkmcnt(0)
	s_setprio 1
	s_barrier
	v_mfma_f32_16x16x32_bf16 v[62:65], v[146:149], v[194:197], v[62:65]
	v_mfma_f32_16x16x32_bf16 v[58:61], v[166:169], v[194:197], v[58:61]
	v_mfma_f32_16x16x32_bf16 v[46:49], v[146:149], v[202:205], v[46:49]
	v_mfma_f32_16x16x32_bf16 v[42:45], v[166:169], v[202:205], v[42:45]
	v_mfma_f32_16x16x32_bf16 v[30:33], v[146:149], v[210:213], v[30:33]
	v_mfma_f32_16x16x32_bf16 v[26:29], v[166:169], v[210:213], v[26:29]
	v_mfma_f32_16x16x32_bf16 v[14:17], v[146:149], v[218:221], v[14:17]
	v_mfma_f32_16x16x32_bf16 v[10:13], v[166:169], v[218:221], v[10:13]
	v_mfma_f32_16x16x32_bf16 v[62:65], v[150:153], v[198:201], v[62:65]
	v_mfma_f32_16x16x32_bf16 v[58:61], v[170:173], v[198:201], v[58:61]
	v_mfma_f32_16x16x32_bf16 v[46:49], v[150:153], v[206:209], v[46:49]
	v_mfma_f32_16x16x32_bf16 v[42:45], v[170:173], v[206:209], v[42:45]
	v_mfma_f32_16x16x32_bf16 v[30:33], v[150:153], v[214:217], v[30:33]
	v_mfma_f32_16x16x32_bf16 v[26:29], v[170:173], v[214:217], v[26:29]
	v_mfma_f32_16x16x32_bf16 v[14:17], v[150:153], v[222:225], v[14:17]
	v_mfma_f32_16x16x32_bf16 v[10:13], v[170:173], v[222:225], v[10:13]
	v_mfma_f32_16x16x32_bf16 v[54:57], v[174:177], v[194:197], v[54:57]
	v_mfma_f32_16x16x32_bf16 v[50:53], v[186:189], v[194:197], v[50:53]
	v_mfma_f32_16x16x32_bf16 v[38:41], v[174:177], v[202:205], v[38:41]
	v_mfma_f32_16x16x32_bf16 v[34:37], v[186:189], v[202:205], v[34:37]
	v_mfma_f32_16x16x32_bf16 v[22:25], v[174:177], v[210:213], v[22:25]
	v_mfma_f32_16x16x32_bf16 v[18:21], v[186:189], v[210:213], v[18:21]
	v_mfma_f32_16x16x32_bf16 v[6:9], v[174:177], v[218:221], v[6:9]
	v_mfma_f32_16x16x32_bf16 v[2:5], v[186:189], v[218:221], v[2:5]
	v_mfma_f32_16x16x32_bf16 v[54:57], v[182:185], v[198:201], v[54:57]
	v_mfma_f32_16x16x32_bf16 v[50:53], v[190:193], v[198:201], v[50:53]
	v_mfma_f32_16x16x32_bf16 v[38:41], v[182:185], v[206:209], v[38:41]
	v_mfma_f32_16x16x32_bf16 v[34:37], v[190:193], v[206:209], v[34:37]
	v_mfma_f32_16x16x32_bf16 v[22:25], v[182:185], v[214:217], v[22:25]
	v_mfma_f32_16x16x32_bf16 v[18:21], v[190:193], v[214:217], v[18:21]
	v_mfma_f32_16x16x32_bf16 v[6:9], v[182:185], v[222:225], v[6:9]
	v_mfma_f32_16x16x32_bf16 v[2:5], v[190:193], v[222:225], v[2:5]
	s_barrier
	s_setprio 0
	s_add_i32 s56, 0, 0x18000
	s_add_i32 s57, 0, 0x1c000
	v_add_u32_e32 v170, s56, v156
	v_add_u32_e32 v179, s57, v156
	ds_read_b128 v[146:149], v170
	ds_read_b128 v[150:153], v170 offset:1024
	ds_read_b128 v[166:169], v170 offset:2048
	ds_read_b128 v[170:173], v170 offset:3072
	ds_read_b128 v[174:177], v179
	ds_read_b128 v[182:185], v179 offset:1024
	ds_read_b128 v[186:189], v179 offset:2048
	ds_read_b128 v[190:193], v179 offset:3072
	s_add_u32 s26, s26, 0x80000
	s_addc_u32 s27, s27, 0
	s_mov_b32 m0, s31
	v_lshl_add_u64 v[234:235], s[26:27], 0, v[130:131]
	ds_read_b128 v[194:197], v164 offset:32768
	ds_read_b128 v[198:201], v164 offset:33792
	ds_read_b128 v[202:205], v164 offset:34816
	ds_read_b128 v[206:209], v164 offset:35840
	ds_read_b128 v[210:213], v164 offset:36864
	ds_read_b128 v[214:217], v164 offset:37888
	ds_read_b128 v[218:221], v164 offset:38912
	ds_read_b128 v[222:225], v164 offset:39936
	global_load_lds_dwordx4 v[234:235], off
	v_lshl_add_u64 v[234:235], s[26:27], 0, v[134:135]
	s_mov_b32 m0, s34
	s_nop 0
	global_load_lds_dwordx4 v[234:235], off
	s_waitcnt vmcnt(8)
	s_waitcnt lgkmcnt(0)
	s_setprio 1
	s_barrier
	v_mfma_f32_16x16x32_bf16 v[126:129], v[146:149], v[194:197], v[126:129]
	v_mfma_f32_16x16x32_bf16 v[122:125], v[166:169], v[194:197], v[122:125]
	v_mfma_f32_16x16x32_bf16 v[110:113], v[146:149], v[202:205], v[110:113]
	v_mfma_f32_16x16x32_bf16 v[106:109], v[166:169], v[202:205], v[106:109]
	v_mfma_f32_16x16x32_bf16 v[94:97], v[146:149], v[210:213], v[94:97]
	v_mfma_f32_16x16x32_bf16 v[90:93], v[166:169], v[210:213], v[90:93]
	v_mfma_f32_16x16x32_bf16 v[78:81], v[146:149], v[218:221], v[78:81]
	v_mfma_f32_16x16x32_bf16 v[74:77], v[166:169], v[218:221], v[74:77]
	v_mfma_f32_16x16x32_bf16 v[126:129], v[150:153], v[198:201], v[126:129]
	v_mfma_f32_16x16x32_bf16 v[122:125], v[170:173], v[198:201], v[122:125]
	v_mfma_f32_16x16x32_bf16 v[110:113], v[150:153], v[206:209], v[110:113]
	v_mfma_f32_16x16x32_bf16 v[106:109], v[170:173], v[206:209], v[106:109]
	v_mfma_f32_16x16x32_bf16 v[94:97], v[150:153], v[214:217], v[94:97]
	v_mfma_f32_16x16x32_bf16 v[90:93], v[170:173], v[214:217], v[90:93]
	v_mfma_f32_16x16x32_bf16 v[78:81], v[150:153], v[222:225], v[78:81]
	v_mfma_f32_16x16x32_bf16 v[74:77], v[170:173], v[222:225], v[74:77]
	v_mfma_f32_16x16x32_bf16 v[118:121], v[174:177], v[194:197], v[118:121]
	v_mfma_f32_16x16x32_bf16 v[114:117], v[186:189], v[194:197], v[114:117]
	v_mfma_f32_16x16x32_bf16 v[102:105], v[174:177], v[202:205], v[102:105]
	v_mfma_f32_16x16x32_bf16 v[98:101], v[186:189], v[202:205], v[98:101]
	v_mfma_f32_16x16x32_bf16 v[86:89], v[174:177], v[210:213], v[86:89]
	v_mfma_f32_16x16x32_bf16 v[82:85], v[186:189], v[210:213], v[82:85]
	v_mfma_f32_16x16x32_bf16 v[70:73], v[174:177], v[218:221], v[70:73]
	v_mfma_f32_16x16x32_bf16 v[66:69], v[186:189], v[218:221], v[66:69]
	v_mfma_f32_16x16x32_bf16 v[118:121], v[182:185], v[198:201], v[118:121]
	v_mfma_f32_16x16x32_bf16 v[114:117], v[190:193], v[198:201], v[114:117]
	v_mfma_f32_16x16x32_bf16 v[102:105], v[182:185], v[206:209], v[102:105]
	v_mfma_f32_16x16x32_bf16 v[98:101], v[190:193], v[206:209], v[98:101]
	v_mfma_f32_16x16x32_bf16 v[86:89], v[182:185], v[214:217], v[86:89]
	v_mfma_f32_16x16x32_bf16 v[82:85], v[190:193], v[214:217], v[82:85]
	v_mfma_f32_16x16x32_bf16 v[70:73], v[182:185], v[222:225], v[70:73]
	v_mfma_f32_16x16x32_bf16 v[66:69], v[190:193], v[222:225], v[66:69]
	s_barrier
	s_setprio 0
	s_add_i32 s26, s56, s30
	v_lshl_add_u64 v[226:227], v[226:227], 0, s[8:9]
	s_mov_b32 m0, s26
	ds_read_b128 v[194:197], v164 offset:49152
	ds_read_b128 v[198:201], v164 offset:50176
	ds_read_b128 v[202:205], v164 offset:51200
	ds_read_b128 v[206:209], v164 offset:52224
	ds_read_b128 v[210:213], v164 offset:53248
	ds_read_b128 v[214:217], v164 offset:54272
	ds_read_b128 v[218:221], v164 offset:55296
	ds_read_b128 v[222:225], v164 offset:56320
	global_load_lds_dwordx4 v[226:227], off
	s_add_i32 m0, s26, 0x2000
	s_add_u32 s24, s24, 0x80080
	v_lshl_add_u64 v[226:227], v[228:229], 0, s[8:9]
	s_addc_u32 s25, s25, 0
	s_add_i32 s26, s57, s30
	global_load_lds_dwordx4 v[226:227], off
	v_lshl_add_u64 v[226:227], s[24:25], 0, v[132:133]
	s_mov_b32 m0, s26
	s_nop 0
	global_load_lds_dwordx4 v[226:227], off
	v_lshl_add_u64 v[226:227], s[24:25], 0, v[136:137]
	s_add_i32 m0, s26, 0x2000
	s_nop 0
	global_load_lds_dwordx4 v[226:227], off
	v_lshl_add_u64 v[226:227], v[230:231], 0, s[8:9]
	s_mov_b32 m0, s36
	s_nop 0
	global_load_lds_dwordx4 v[226:227], off
	v_lshl_add_u64 v[226:227], v[232:233], 0, s[8:9]
	s_mov_b32 m0, s37
	s_nop 0
	global_load_lds_dwordx4 v[226:227], off
	s_waitcnt vmcnt(8)
	s_waitcnt lgkmcnt(0)
	s_setprio 1
	s_barrier
	v_mfma_f32_16x16x32_bf16 v[62:65], v[146:149], v[194:197], v[62:65]
	v_mfma_f32_16x16x32_bf16 v[58:61], v[166:169], v[194:197], v[58:61]
	v_mfma_f32_16x16x32_bf16 v[46:49], v[146:149], v[202:205], v[46:49]
	v_mfma_f32_16x16x32_bf16 v[42:45], v[166:169], v[202:205], v[42:45]
	v_mfma_f32_16x16x32_bf16 v[30:33], v[146:149], v[210:213], v[30:33]
	v_mfma_f32_16x16x32_bf16 v[26:29], v[166:169], v[210:213], v[26:29]
	v_mfma_f32_16x16x32_bf16 v[14:17], v[146:149], v[218:221], v[14:17]
	v_mfma_f32_16x16x32_bf16 v[10:13], v[166:169], v[218:221], v[10:13]
	v_mfma_f32_16x16x32_bf16 v[62:65], v[150:153], v[198:201], v[62:65]
	v_mfma_f32_16x16x32_bf16 v[58:61], v[170:173], v[198:201], v[58:61]
	v_mfma_f32_16x16x32_bf16 v[46:49], v[150:153], v[206:209], v[46:49]
	v_mfma_f32_16x16x32_bf16 v[42:45], v[170:173], v[206:209], v[42:45]
	v_mfma_f32_16x16x32_bf16 v[30:33], v[150:153], v[214:217], v[30:33]
	v_mfma_f32_16x16x32_bf16 v[26:29], v[170:173], v[214:217], v[26:29]
	v_mfma_f32_16x16x32_bf16 v[14:17], v[150:153], v[222:225], v[14:17]
	v_mfma_f32_16x16x32_bf16 v[10:13], v[170:173], v[222:225], v[10:13]
	v_mfma_f32_16x16x32_bf16 v[54:57], v[174:177], v[194:197], v[54:57]
	v_mfma_f32_16x16x32_bf16 v[50:53], v[186:189], v[194:197], v[50:53]
	v_mfma_f32_16x16x32_bf16 v[38:41], v[174:177], v[202:205], v[38:41]
	v_mfma_f32_16x16x32_bf16 v[34:37], v[186:189], v[202:205], v[34:37]
	v_mfma_f32_16x16x32_bf16 v[22:25], v[174:177], v[210:213], v[22:25]
	v_mfma_f32_16x16x32_bf16 v[18:21], v[186:189], v[210:213], v[18:21]
	v_mfma_f32_16x16x32_bf16 v[6:9], v[174:177], v[218:221], v[6:9]
	v_mfma_f32_16x16x32_bf16 v[2:5], v[186:189], v[218:221], v[2:5]
	v_mfma_f32_16x16x32_bf16 v[54:57], v[182:185], v[198:201], v[54:57]
	v_mfma_f32_16x16x32_bf16 v[50:53], v[190:193], v[198:201], v[50:53]
	v_mfma_f32_16x16x32_bf16 v[38:41], v[182:185], v[206:209], v[38:41]
	v_mfma_f32_16x16x32_bf16 v[34:37], v[190:193], v[206:209], v[34:37]
	v_mfma_f32_16x16x32_bf16 v[22:25], v[182:185], v[214:217], v[22:25]
	v_mfma_f32_16x16x32_bf16 v[18:21], v[190:193], v[214:217], v[18:21]
	v_mfma_f32_16x16x32_bf16 v[6:9], v[182:185], v[222:225], v[6:9]
	v_mfma_f32_16x16x32_bf16 v[2:5], v[190:193], v[222:225], v[2:5]
	s_barrier
	s_setprio 0
	s_add_i32 s55, s55, 2
	s_add_u32 s4, s4, 0x100
	s_addc_u32 s5, s5, 0
	s_add_u32 s53, s53, 0x100
	s_addc_u32 s54, s54, 0
	s_cmp_gt_u32 s55, 29
	s_cbranch_scc0 .LBB0_2731
	s_and_b64 vcc, exec, s[10:11]
	s_cbranch_vccz .LBB0_2734
	s_barrier

.LBB0_2861:
	s_add_i32 s70, s69, 5
	s_add_i32 s71, s69, 4
	ds_read_b128 v[66:69], v204 offset:49152
	ds_read_b128 v[70:73], v204 offset:57344
	ds_read_b128 v[228:231], v205 offset:49152
	ds_read_b128 v[232:235], v205 offset:57344
	v_add_f32_e32 v131, 0, v145
	v_add_f32_e32 v131, v227, v131
	s_waitcnt lgkmcnt(3)
	v_mfma_f32_32x32x16_bf16 v[82:97], v[66:69], v[110:113], 0
	v_add_f32_e32 v131, v143, v131
	v_add_f32_e32 v131, v224, v131
	v_add_f32_e32 v131, v142, v131
	v_add_f32_e32 v131, v144, v131
	v_add_f32_e32 v131, v140, v131
	v_add_f32_e32 v131, v141, v131
	v_add_f32_e32 v131, v137, v131
	s_waitcnt lgkmcnt(2)
	v_mfma_f32_32x32x16_bf16 v[66:81], v[70:73], v[110:113], 0
	v_add_f32_e32 v131, v139, v131
	v_add_f32_e32 v131, v136, v131
	v_add_f32_e32 v131, v138, v131
	v_exp_f32_e32 v128, v128
	v_add_f32_e32 v131, v133, v131
	v_exp_f32_e32 v129, v129
	v_add_f32_e32 v131, v134, v131
	s_waitcnt lgkmcnt(1)
	v_mfma_f32_32x32x16_bf16 v[82:97], v[228:231], v[106:109], v[82:97]
	v_exp_f32_e32 v126, v126
	v_add_f32_e32 v131, v132, v131
	v_exp_f32_e32 v127, v127
	v_add_f32_e32 v131, v135, v131
	v_exp_f32_e32 v124, v124
	v_add_f32_e32 v131, v128, v131
	v_exp_f32_e32 v125, v125
	s_waitcnt lgkmcnt(0)
	v_mfma_f32_32x32x16_bf16 v[66:81], v[232:235], v[106:109], v[66:81]
	ds_read_b128 v[228:231], v206 offset:49152
	ds_read_b128 v[232:235], v206 offset:57344
	v_add_f32_e32 v131, v129, v131
	v_exp_f32_e32 v122, v122
	v_add_f32_e32 v131, v126, v131
	v_exp_f32_e32 v123, v123
	v_add_f32_e32 v131, v127, v131
	v_exp_f32_e32 v120, v120
	s_waitcnt lgkmcnt(1)
	v_mfma_f32_32x32x16_bf16 v[82:97], v[228:231], v[102:105], v[82:97]
	v_add_f32_e32 v131, v124, v131
	v_exp_f32_e32 v121, v121
	v_add_f32_e32 v131, v125, v131
	v_exp_f32_e32 v118, v118
	v_add_f32_e32 v131, v122, v131
	v_exp_f32_e32 v119, v119
	v_add_f32_e32 v131, v123, v131
	s_waitcnt lgkmcnt(0)
	v_mfma_f32_32x32x16_bf16 v[66:81], v[232:235], v[102:105], v[66:81]
	ds_read_b128 v[228:231], v207 offset:49152
	ds_read_b128 v[232:235], v207 offset:57344
	v_exp_f32_e32 v116, v116
	v_add_f32_e32 v131, v120, v131
	v_exp_f32_e32 v117, v117
	v_add_f32_e32 v131, v121, v131
	v_exp_f32_e32 v114, v114
	v_add_f32_e32 v131, v118, v131
	s_waitcnt lgkmcnt(1)
	v_mfma_f32_32x32x16_bf16 v[82:97], v[228:231], v[98:101], v[82:97]
	v_exp_f32_e32 v115, v115
	v_add_f32_e32 v131, v119, v131
	v_add_f32_e32 v131, v116, v131
	v_add_f32_e32 v131, v117, v131
	v_add_f32_e32 v131, v114, v131
	v_add_f32_e32 v221, v115, v131
	v_mov_b32_e32 v222, v221
	s_waitcnt lgkmcnt(0)
	v_mfma_f32_32x32x16_bf16 v[66:81], v[232:235], v[98:101], v[66:81]
	ds_read_b128 v[228:231], v208 offset:49152
	ds_read_b128 v[232:235], v208 offset:57344
	ds_read_b128 v[236:239], v216
	v_permlane32_swap_b32_e32 v221, v222
	s_waitcnt lgkmcnt(0)
	v_mfma_f32_32x32x16_bf16 v[82:97], v[228:231], v[236:239], v[82:97]
	v_mfma_f32_32x32x16_bf16 v[66:81], v[232:235], v[236:239], v[66:81]
	ds_read_b128 v[228:231], v209 offset:49152
	ds_read_b128 v[232:235], v209 offset:57344
	ds_read_b128 v[236:239], v216 offset:1024
	s_waitcnt lgkmcnt(0)
	v_mfma_f32_32x32x16_bf16 v[82:97], v[228:231], v[236:239], v[82:97]
	v_mfma_f32_32x32x16_bf16 v[66:81], v[232:235], v[236:239], v[66:81]
	ds_read_b128 v[228:231], v210 offset:49152
	ds_read_b128 v[232:235], v210 offset:57344
	ds_read_b128 v[236:239], v216 offset:2048
	s_waitcnt lgkmcnt(0)
	v_mfma_f32_32x32x16_bf16 v[82:97], v[228:231], v[236:239], v[82:97]
	v_mfma_f32_32x32x16_bf16 v[66:81], v[232:235], v[236:239], v[66:81]
	ds_read_b128 v[228:231], v211 offset:49152
	ds_read_b128 v[232:235], v211 offset:57344
	ds_read_b128 v[236:239], v216 offset:3072
	v_cvt_pk_bf16_f32 v226, v145, v227
	v_cvt_pk_bf16_f32 v227, v143, v224
	s_waitcnt lgkmcnt(0)
	v_mfma_f32_32x32x16_bf16 v[82:97], v[228:231], v[236:239], v[82:97]
	v_cvt_pk_bf16_f32 v228, v142, v144
	v_cvt_pk_bf16_f32 v229, v140, v141
	v_cvt_pk_bf16_f32 v140, v137, v139
	v_cvt_pk_bf16_f32 v141, v136, v138
	v_cvt_pk_bf16_f32 v142, v133, v134
	v_cvt_pk_bf16_f32 v143, v132, v135
	v_cvt_pk_bf16_f32 v132, v128, v129
	v_mfma_f32_32x32x16_bf16 v[66:81], v[232:235], v[236:239], v[66:81]
	v_cvt_pk_bf16_f32 v133, v126, v127
	v_cvt_pk_bf16_f32 v134, v124, v125
	v_cvt_pk_bf16_f32 v135, v122, v123
	v_cvt_pk_bf16_f32 v136, v120, v121
	v_cvt_pk_bf16_f32 v137, v118, v119
	v_cvt_pk_bf16_f32 v138, v116, v117
	v_cvt_pk_bf16_f32 v139, v114, v115
	v_permlane32_swap_b32_e32 v226, v228
	v_permlane32_swap_b32_e32 v227, v229
	v_permlane32_swap_b32_e32 v140, v142
	v_permlane32_swap_b32_e32 v141, v143
	v_permlane32_swap_b32_e32 v132, v134
	v_permlane32_swap_b32_e32 v133, v135
	v_permlane32_swap_b32_e32 v136, v138
	v_permlane32_swap_b32_e32 v137, v139
	s_min_i32 s0, s70, s66
	s_add_i32 s0, s0, s60
	s_cmp_lt_u32 s71, 3
	s_cselect_b32 s0, s70, s0
	s_lshl_b32 s0, s0, 6
	s_add_i32 s6, s0, s63
	v_mad_i64_i32 v[114:115], s[0:1], s6, v199, v[156:157]
	v_add_co_u32_e32 v118, vcc, s52, v114
	v_mad_i64_i32 v[122:123], s[0:1], s6, v199, v[154:155]
	s_nop 0
	v_addc_co_u32_e32 v119, vcc, 0, v115, vcc
	v_add_co_u32_e32 v126, vcc, s52, v122
	global_load_dwordx4 v[114:117], v[114:115], off
	s_nop 0
	global_load_dwordx4 v[118:121], v[118:119], off
	v_addc_co_u32_e32 v127, vcc, 0, v123, vcc
	global_load_dwordx4 v[122:125], v[122:123], off
	s_nop 0
	global_load_dwordx4 v[126:129], v[126:127], off
	ds_read_b64_tr_b16 v[230:231], v195 offset:0
	ds_read_b64_tr_b16 v[232:233], v195 offset:0x800
	ds_read_b64_tr_b16 v[234:235], v195 offset:0x1000
	ds_read_b64_tr_b16 v[236:237], v195 offset:0x1800
	ds_read_b64_tr_b16 v[238:239], v195 offset:0x2000
	ds_read_b64_tr_b16 v[240:241], v195 offset:0x2800
	ds_read_b64_tr_b16 v[242:243], v195 offset:0x3000
	ds_read_b64_tr_b16 v[244:245], v195 offset:0x3800
	s_waitcnt lgkmcnt(0)
	s_nop 0
	v_mfma_f32_32x32x16_bf16 v[50:65], v[226:229], v[230:233], v[50:65]
	ds_read_b64_tr_b16 v[230:231], v195 offset:0x200
	ds_read_b64_tr_b16 v[232:233], v195 offset:0xa00
	v_mfma_f32_32x32x16_bf16 v[50:65], v[140:143], v[234:237], v[50:65]
	ds_read_b64_tr_b16 v[234:235], v195 offset:0x1200
	ds_read_b64_tr_b16 v[236:237], v195 offset:0x1a00
	v_mfma_f32_32x32x16_bf16 v[50:65], v[132:135], v[238:241], v[50:65]
	ds_read_b64_tr_b16 v[238:239], v195 offset:0x2200
	ds_read_b64_tr_b16 v[240:241], v195 offset:0x2a00
	ds_read_b64_tr_b16 v[246:247], v195 offset:0x3200
	ds_read_b64_tr_b16 v[248:249], v195 offset:0x3a00
	s_waitcnt lgkmcnt(0)
	v_mfma_f32_32x32x16_bf16 v[50:65], v[136:139], v[242:245], v[50:65]
	v_mfma_f32_32x32x16_bf16 v[34:49], v[226:229], v[230:233], v[34:49]
	ds_read_b64_tr_b16 v[230:231], v195 offset:0x400
	ds_read_b64_tr_b16 v[232:233], v195 offset:0xc00
	v_mfma_f32_32x32x16_bf16 v[34:49], v[140:143], v[234:237], v[34:49]
	ds_read_b64_tr_b16 v[234:235], v195 offset:0x1400
	ds_read_b64_tr_b16 v[236:237], v195 offset:0x1c00
	v_mfma_f32_32x32x16_bf16 v[34:49], v[132:135], v[238:241], v[34:49]
	ds_read_b64_tr_b16 v[238:239], v195 offset:0x2400
	ds_read_b64_tr_b16 v[240:241], v195 offset:0x2c00
	ds_read_b64_tr_b16 v[242:243], v195 offset:0x3400
	ds_read_b64_tr_b16 v[244:245], v195 offset:0x3c00
	s_waitcnt lgkmcnt(0)
	v_mfma_f32_32x32x16_bf16 v[34:49], v[136:139], v[246:249], v[34:49]
	v_mfma_f32_32x32x16_bf16 v[18:33], v[226:229], v[230:233], v[18:33]
	ds_read_b64_tr_b16 v[230:231], v195 offset:0x600
	ds_read_b64_tr_b16 v[232:233], v195 offset:0xe00
	v_mfma_f32_32x32x16_bf16 v[18:33], v[140:143], v[234:237], v[18:33]
	ds_read_b64_tr_b16 v[234:235], v195 offset:0x1600
	ds_read_b64_tr_b16 v[236:237], v195 offset:0x1e00
	v_mfma_f32_32x32x16_bf16 v[18:33], v[132:135], v[238:241], v[18:33]
	ds_read_b64_tr_b16 v[238:239], v195 offset:0x2600
	ds_read_b64_tr_b16 v[240:241], v195 offset:0x2e00
	ds_read_b64_tr_b16 v[246:247], v195 offset:0x3600
	ds_read_b64_tr_b16 v[248:249], v195 offset:0x3e00
	s_waitcnt lgkmcnt(0)
	v_mfma_f32_32x32x16_bf16 v[18:33], v[136:139], v[242:245], v[18:33]
	v_mfma_f32_32x32x16_bf16 v[2:17], v[226:229], v[230:233], v[2:17]
	v_mfma_f32_32x32x16_bf16 v[2:17], v[140:143], v[234:237], v[2:17]
	v_mfma_f32_32x32x16_bf16 v[2:17], v[132:135], v[238:241], v[2:17]
	v_mfma_f32_32x32x16_bf16 v[2:17], v[136:139], v[246:249], v[2:17]
	s_cmp_lt_u32 s71, 4
	s_cbranch_scc1 .LBB0_2897
	s_add_i32 s6, s60, s69
	s_cmp_lt_i32 s71, s58
	s_cselect_b64 s[0:1], -1, 0
	s_cmp_lt_i32 s6, s67
	v_cmp_ge_i32_e32 vcc, s6, v219
	s_cselect_b64 s[6:7], -1, 0
	s_and_b64 s[0:1], s[0:1], s[6:7]
	s_and_b64 s[0:1], s[0:1], vcc
	v_mov_b32_e32 v136, v218
	v_mov_b32_e32 v224, 0xf149f2ca
	s_andn2_b64 vcc, exec, s[0:1]
	v_mov_b32_e32 v225, 0xf149f2ca
	v_mov_b32_e32 v145, 0xf149f2ca
	v_mov_b32_e32 v223, 0xf149f2ca
	v_mov_b32_e32 v143, 0xf149f2ca
	v_mov_b32_e32 v144, 0xf149f2ca
	v_mov_b32_e32 v141, 0xf149f2ca
	v_mov_b32_e32 v142, 0xf149f2ca
	v_mov_b32_e32 v139, 0xf149f2ca
	v_mov_b32_e32 v140, 0xf149f2ca
	v_mov_b32_e32 v135, 0xf149f2ca
	v_mov_b32_e32 v137, 0xf149f2ca
	v_mov_b32_e32 v133, 0xf149f2ca
	v_mov_b32_e32 v134, 0xf149f2ca
	v_mov_b32_e32 v131, 0xf149f2ca
	v_mov_b32_e32 v132, 0xf149f2ca
	v_mov_b32_e32 v138, 0xf149f2ca
	v_mov_b32_e32 v226, 0xf149f2ca
	v_mov_b32_e32 v227, 0xf149f2ca
	v_mov_b32_e32 v228, 0xf149f2ca
	v_mov_b32_e32 v229, 0xf149f2ca
	v_mov_b32_e32 v230, 0xf149f2ca
	v_mov_b32_e32 v231, 0xf149f2ca
	v_mov_b32_e32 v232, 0xf149f2ca
	v_mov_b32_e32 v233, 0xf149f2ca
	v_mov_b32_e32 v234, 0xf149f2ca
	v_mov_b32_e32 v235, 0xf149f2ca
	v_mov_b32_e32 v236, 0xf149f2ca
	v_mov_b32_e32 v237, 0xf149f2ca
	v_mov_b32_e32 v238, 0xf149f2ca
	v_mov_b32_e32 v239, 0xf149f2ca
	v_mov_b32_e32 v240, 0xf149f2ca
	s_cbranch_vccnz .LBB0_2896
	v_sub_u32_e32 v251, v159, v136
	v_mov_b32_e32 v132, 0xf149f2ca
	v_cmp_gt_u32_e32 vcc, 16, v251
	s_nop 1
	s_and_saveexec_b64 s[6:7], vcc
	v_add_u32_e32 v132, v220, v158
	ds_read_b32 v132, v132
	s_or_b64 exec, exec, s[6:7]
	v_sub_u32_e32 v251, v161, v136
	v_mov_b32_e32 v131, 0xf149f2ca
	v_cmp_gt_u32_e32 vcc, 16, v251
	s_nop 1
	s_and_saveexec_b64 s[6:7], vcc
	v_add_u32_e32 v131, v220, v158
	ds_read_b32 v131, v131 offset:4
	s_or_b64 exec, exec, s[6:7]
	v_sub_u32_e32 v251, v163, v136
	v_mov_b32_e32 v134, 0xf149f2ca
	v_cmp_gt_u32_e32 vcc, 16, v251
	s_nop 1
	s_and_saveexec_b64 s[6:7], vcc
	v_add_u32_e32 v134, v220, v158
	ds_read_b32 v134, v134 offset:8
	s_or_b64 exec, exec, s[6:7]
	v_sub_u32_e32 v251, v165, v136
	v_mov_b32_e32 v133, 0xf149f2ca
	v_cmp_gt_u32_e32 vcc, 16, v251
	s_nop 1
	s_and_saveexec_b64 s[6:7], vcc
	v_add_u32_e32 v133, v220, v158
	ds_read_b32 v133, v133 offset:12
	s_or_b64 exec, exec, s[6:7]
	v_sub_u32_e32 v251, v167, v136
	v_mov_b32_e32 v137, 0xf149f2ca
	v_cmp_gt_u32_e32 vcc, 16, v251
	s_nop 1
	s_and_saveexec_b64 s[6:7], vcc
	v_add_u32_e32 v137, v220, v158
	ds_read_b32 v137, v137 offset:32
	s_or_b64 exec, exec, s[6:7]
	v_sub_u32_e32 v251, v169, v136
	v_mov_b32_e32 v135, 0xf149f2ca
	v_cmp_gt_u32_e32 vcc, 16, v251
	s_nop 1
	s_and_saveexec_b64 s[6:7], vcc
	v_add_u32_e32 v135, v220, v158
	ds_read_b32 v135, v135 offset:36
	s_or_b64 exec, exec, s[6:7]
	v_sub_u32_e32 v251, v171, v136
	v_mov_b32_e32 v140, 0xf149f2ca
	v_cmp_gt_u32_e32 vcc, 16, v251
	s_nop 1
	s_and_saveexec_b64 s[6:7], vcc
	v_add_u32_e32 v140, v220, v158
	ds_read_b32 v140, v140 offset:40
	s_or_b64 exec, exec, s[6:7]
	v_sub_u32_e32 v251, v173, v136
	v_mov_b32_e32 v139, 0xf149f2ca
	v_cmp_gt_u32_e32 vcc, 16, v251
	s_nop 1
	s_and_saveexec_b64 s[6:7], vcc
	v_add_u32_e32 v139, v220, v158
	ds_read_b32 v139, v139 offset:44
	s_or_b64 exec, exec, s[6:7]
	v_sub_u32_e32 v251, v175, v136
	v_mov_b32_e32 v142, 0xf149f2ca
	v_cmp_gt_u32_e32 vcc, 16, v251
	s_nop 1
	s_and_saveexec_b64 s[6:7], vcc
	v_add_u32_e32 v142, v220, v158
	ds_read_b32 v142, v142 offset:64
	s_or_b64 exec, exec, s[6:7]
	v_sub_u32_e32 v251, v177, v136
	v_mov_b32_e32 v141, 0xf149f2ca
	v_cmp_gt_u32_e32 vcc, 16, v251
	s_nop 1
	s_and_saveexec_b64 s[6:7], vcc
	v_add_u32_e32 v141, v220, v158
	ds_read_b32 v141, v141 offset:68
	s_or_b64 exec, exec, s[6:7]
	v_sub_u32_e32 v251, v181, v136
	v_mov_b32_e32 v144, 0xf149f2ca
	v_cmp_gt_u32_e32 vcc, 16, v251
	s_nop 1
	s_and_saveexec_b64 s[6:7], vcc
	v_add_u32_e32 v144, v220, v158
	ds_read_b32 v144, v144 offset:72
	s_or_b64 exec, exec, s[6:7]
	v_sub_u32_e32 v251, v183, v136
	v_mov_b32_e32 v143, 0xf149f2ca
	v_cmp_gt_u32_e32 vcc, 16, v251
	s_nop 1
	s_and_saveexec_b64 s[6:7], vcc
	v_add_u32_e32 v143, v220, v158
	ds_read_b32 v143, v143 offset:76
	s_or_b64 exec, exec, s[6:7]
	v_sub_u32_e32 v251, v185, v136
	v_mov_b32_e32 v223, 0xf149f2ca
	v_cmp_gt_u32_e32 vcc, 16, v251
	s_nop 1
	s_and_saveexec_b64 s[6:7], vcc
	v_add_u32_e32 v223, v220, v158
	ds_read_b32 v223, v223 offset:96
	s_or_b64 exec, exec, s[6:7]
	v_sub_u32_e32 v251, v187, v136
	v_mov_b32_e32 v145, 0xf149f2ca
	v_cmp_gt_u32_e32 vcc, 16, v251
	s_nop 1
	s_and_saveexec_b64 s[6:7], vcc
	v_add_u32_e32 v145, v220, v158
	ds_read_b32 v145, v145 offset:100
	s_or_b64 exec, exec, s[6:7]
	v_sub_u32_e32 v251, v189, v136
	v_mov_b32_e32 v225, 0xf149f2ca
	v_cmp_gt_u32_e32 vcc, 16, v251
	s_nop 1
	s_and_saveexec_b64 s[6:7], vcc
	v_add_u32_e32 v225, v220, v158
	ds_read_b32 v225, v225 offset:104
	s_or_b64 exec, exec, s[6:7]
	v_sub_u32_e32 v251, v191, v136
	v_mov_b32_e32 v224, 0xf149f2ca
	v_cmp_gt_u32_e32 vcc, 16, v251
	s_nop 1
	s_and_saveexec_b64 s[6:7], vcc
	v_add_u32_e32 v224, v220, v158
	ds_read_b32 v224, v224 offset:108
	s_or_b64 exec, exec, s[6:7]
	s_waitcnt lgkmcnt(0)
	v_add_f32_e32 v132, v82, v132
	v_add_f32_e32 v131, v83, v131
	v_add_f32_e32 v134, v84, v134
	v_add_f32_e32 v133, v85, v133
	v_add_f32_e32 v137, v86, v137
	v_add_f32_e32 v135, v87, v135
	v_add_f32_e32 v140, v88, v140
	v_add_f32_e32 v139, v89, v139
	v_add_f32_e32 v142, v90, v142
	v_add_f32_e32 v141, v91, v141
	v_add_f32_e32 v144, v92, v144
	v_add_f32_e32 v143, v93, v143
	v_add_f32_e32 v223, v94, v223
	v_add_f32_e32 v145, v95, v145
	v_add_f32_e32 v225, v96, v225
	v_add_f32_e32 v224, v97, v224
	v_sub_u32_e32 v251, v160, v136
	v_cmp_gt_u32_e32 vcc, 16, v251
	s_nop 0
	s_nop 0
	v_cndmask_b32_e32 v251, v215, v160, vcc
	v_lshl_add_u32 v251, v251, 2, v220
	ds_read_b32 v138, v251
	v_sub_u32_e32 v82, v162, v136
	v_cmp_gt_u32_e64 s[0:1], 16, v82
	s_nop 0
	s_nop 0
	v_cndmask_b32_e64 v82, v215, v162, s[0:1]
	v_lshl_add_u32 v82, v82, 2, v220
	ds_read_b32 v82, v82
	v_sub_u32_e32 v83, v164, v136
	v_cmp_gt_u32_e64 s[8:9], 16, v83
	s_nop 0
	s_nop 0
	v_cndmask_b32_e64 v83, v215, v164, s[8:9]
	v_lshl_add_u32 v83, v83, 2, v220
	ds_read_b32 v83, v83
	v_sub_u32_e32 v84, v166, v136
	v_cmp_gt_u32_e64 s[10:11], 16, v84
	s_nop 0
	s_nop 0
	v_cndmask_b32_e64 v84, v215, v166, s[10:11]
	v_lshl_add_u32 v84, v84, 2, v220
	ds_read_b32 v84, v84
	v_sub_u32_e32 v85, v168, v136
	v_cmp_gt_u32_e64 s[12:13], 16, v85
	s_nop 0
	s_nop 0
	v_cndmask_b32_e64 v85, v215, v168, s[12:13]
	v_lshl_add_u32 v85, v85, 2, v220
	ds_read_b32 v85, v85
	v_sub_u32_e32 v86, v170, v136
	v_cmp_gt_u32_e64 s[14:15], 16, v86
	s_nop 0
	s_nop 0
	v_cndmask_b32_e64 v86, v215, v170, s[14:15]
	v_lshl_add_u32 v86, v86, 2, v220
	ds_read_b32 v86, v86
	v_sub_u32_e32 v87, v172, v136
	v_cmp_gt_u32_e64 s[16:17], 16, v87
	s_nop 0
	s_nop 0
	v_cndmask_b32_e64 v87, v215, v172, s[16:17]
	v_lshl_add_u32 v87, v87, 2, v220
	ds_read_b32 v87, v87
	v_sub_u32_e32 v88, v174, v136
	v_cmp_gt_u32_e64 s[18:19], 16, v88
	s_nop 0
	s_nop 0
	v_cndmask_b32_e64 v88, v215, v174, s[18:19]
	v_lshl_add_u32 v88, v88, 2, v220
	ds_read_b32 v88, v88
	v_sub_u32_e32 v89, v176, v136
	v_cmp_gt_u32_e64 s[20:21], 16, v89
	s_nop 0
	s_nop 0
	v_cndmask_b32_e64 v89, v215, v176, s[20:21]
	v_lshl_add_u32 v89, v89, 2, v220
	ds_read_b32 v89, v89
	v_sub_u32_e32 v90, v179, v136
	v_cmp_gt_u32_e64 s[22:23], 16, v90
	s_nop 0
	s_nop 0
	v_cndmask_b32_e64 v90, v215, v179, s[22:23]
	v_lshl_add_u32 v90, v90, 2, v220
	ds_read_b32 v90, v90
	v_sub_u32_e32 v91, v182, v136
	v_cmp_gt_u32_e64 s[24:25], 16, v91
	s_nop 0
	s_nop 0
	v_cndmask_b32_e64 v91, v215, v182, s[24:25]
	v_lshl_add_u32 v91, v91, 2, v220
	ds_read_b32 v91, v91
	v_sub_u32_e32 v92, v184, v136
	v_cmp_gt_u32_e64 s[26:27], 16, v92
	s_nop 0
	s_nop 0
	v_cndmask_b32_e64 v92, v215, v184, s[26:27]
	v_lshl_add_u32 v92, v92, 2, v220
	ds_read_b32 v92, v92
	v_sub_u32_e32 v93, v186, v136
	v_cmp_gt_u32_e64 s[28:29], 16, v93
	s_nop 0
	s_nop 0
	v_cndmask_b32_e64 v93, v215, v186, s[28:29]
	v_lshl_add_u32 v93, v93, 2, v220
	ds_read_b32 v93, v93
	v_sub_u32_e32 v94, v188, v136
	v_cmp_gt_u32_e64 s[30:31], 16, v94
	s_nop 0
	s_nop 0
	v_cndmask_b32_e64 v94, v215, v188, s[30:31]
	v_lshl_add_u32 v94, v94, 2, v220
	ds_read_b32 v94, v94
	v_sub_u32_e32 v95, v190, v136
	v_cmp_gt_u32_e64 s[34:35], 16, v95
	s_nop 0
	s_nop 0
	v_cndmask_b32_e64 v95, v215, v190, s[34:35]
	v_lshl_add_u32 v95, v95, 2, v220
	ds_read_b32 v95, v95
	v_sub_u32_e32 v96, v192, v136
	v_cmp_gt_u32_e64 s[36:37], 16, v96
	s_nop 0
	s_nop 0
	v_cndmask_b32_e64 v96, v215, v192, s[36:37]
	v_lshl_add_u32 v96, v96, 2, v220
	ds_read_b32 v96, v96
.LBB0_2895:
	s_waitcnt lgkmcnt(14)
	v_add_f32_e32 v66, v66, v138
	v_cndmask_b32_e32 v240, v212, v66, vcc
	v_add_f32_e32 v66, v67, v82
	v_cndmask_b32_e64 v239, v212, v66, s[0:1]
	s_waitcnt lgkmcnt(13)
	v_add_f32_e32 v66, v68, v83
	v_cndmask_b32_e64 v238, v212, v66, s[8:9]
	s_waitcnt lgkmcnt(12)
	v_add_f32_e32 v66, v69, v84
	v_cndmask_b32_e64 v237, v212, v66, s[10:11]
	s_waitcnt lgkmcnt(11)
	v_add_f32_e32 v66, v70, v85
	v_cndmask_b32_e64 v236, v212, v66, s[12:13]
	s_waitcnt lgkmcnt(10)
	v_add_f32_e32 v66, v71, v86
	v_cndmask_b32_e64 v235, v212, v66, s[14:15]
	s_waitcnt lgkmcnt(9)
	v_add_f32_e32 v66, v72, v87
	v_cndmask_b32_e64 v234, v212, v66, s[16:17]
	s_waitcnt lgkmcnt(8)
	v_add_f32_e32 v66, v73, v88
	v_cndmask_b32_e64 v233, v212, v66, s[18:19]
	s_waitcnt lgkmcnt(7)
	v_add_f32_e32 v66, v74, v89
	v_cndmask_b32_e64 v232, v212, v66, s[20:21]
	s_waitcnt lgkmcnt(6)
	v_add_f32_e32 v66, v75, v90
	v_cndmask_b32_e64 v231, v212, v66, s[22:23]
	s_waitcnt lgkmcnt(5)
	v_add_f32_e32 v66, v76, v91
	v_cndmask_b32_e64 v230, v212, v66, s[24:25]
	s_waitcnt lgkmcnt(4)
	v_add_f32_e32 v66, v77, v92
	v_cndmask_b32_e64 v229, v212, v66, s[26:27]
	s_waitcnt lgkmcnt(3)
	v_add_f32_e32 v66, v78, v93
	v_cndmask_b32_e64 v228, v212, v66, s[28:29]
	s_waitcnt lgkmcnt(2)
	v_add_f32_e32 v66, v79, v94
	v_cndmask_b32_e64 v227, v212, v66, s[30:31]
	s_waitcnt lgkmcnt(1)
	v_add_f32_e32 v66, v80, v95
	v_cndmask_b32_e64 v226, v212, v66, s[34:35]
	s_waitcnt lgkmcnt(0)
	v_add_f32_e32 v66, v81, v96
	v_cndmask_b32_e64 v138, v212, v66, s[36:37]

.LBB0_2903:
	v_mad_i64_i32 v[114:115], s[6:7], s0, v199, v[156:157]
	v_add_co_u32_e32 v118, vcc, 0x60000, v114
	v_mad_i64_i32 v[122:123], s[0:1], s0, v199, v[154:155]
	s_nop 0
	v_addc_co_u32_e32 v119, vcc, 0, v115, vcc
	v_add_co_u32_e32 v126, vcc, 0x60000, v122
	global_load_dwordx4 v[114:117], v[114:115], off
	s_nop 0
	global_load_dwordx4 v[118:121], v[118:119], off
	v_addc_co_u32_e32 v127, vcc, 0, v123, vcc
	global_load_dwordx4 v[122:125], v[122:123], off
	s_nop 0
	global_load_dwordx4 v[126:129], v[126:127], off
	ds_read_b64_tr_b16 v[228:229], v197 offset:0
	ds_read_b64_tr_b16 v[230:231], v197 offset:0x800
	ds_read_b64_tr_b16 v[232:233], v197 offset:0x1000
	ds_read_b64_tr_b16 v[234:235], v197 offset:0x1800
	ds_read_b64_tr_b16 v[236:237], v197 offset:0x2000
	ds_read_b64_tr_b16 v[238:239], v197 offset:0x2800
	ds_read_b64_tr_b16 v[240:241], v197 offset:0x3000
	ds_read_b64_tr_b16 v[242:243], v197 offset:0x3800
	s_waitcnt lgkmcnt(0)
	s_nop 0
	v_mfma_f32_32x32x16_bf16 v[50:65], v[130:133], v[228:231], v[50:65]
	ds_read_b64_tr_b16 v[228:229], v197 offset:0x200
	ds_read_b64_tr_b16 v[230:231], v197 offset:0xa00
	v_mfma_f32_32x32x16_bf16 v[50:65], v[134:137], v[232:235], v[50:65]
	ds_read_b64_tr_b16 v[232:233], v197 offset:0x1200
	ds_read_b64_tr_b16 v[234:235], v197 offset:0x1a00
	v_mfma_f32_32x32x16_bf16 v[50:65], v[138:141], v[236:239], v[50:65]
	ds_read_b64_tr_b16 v[236:237], v197 offset:0x2200
	ds_read_b64_tr_b16 v[238:239], v197 offset:0x2a00
	ds_read_b64_tr_b16 v[244:245], v197 offset:0x3200
	ds_read_b64_tr_b16 v[246:247], v197 offset:0x3a00
	s_waitcnt lgkmcnt(0)
	v_mfma_f32_32x32x16_bf16 v[50:65], v[142:145], v[240:243], v[50:65]
	v_mfma_f32_32x32x16_bf16 v[34:49], v[130:133], v[228:231], v[34:49]
	ds_read_b64_tr_b16 v[228:229], v197 offset:0x400
	ds_read_b64_tr_b16 v[230:231], v197 offset:0xc00
	v_mfma_f32_32x32x16_bf16 v[34:49], v[134:137], v[232:235], v[34:49]
	ds_read_b64_tr_b16 v[232:233], v197 offset:0x1400
	ds_read_b64_tr_b16 v[234:235], v197 offset:0x1c00
	v_mfma_f32_32x32x16_bf16 v[34:49], v[138:141], v[236:239], v[34:49]
	ds_read_b64_tr_b16 v[236:237], v197 offset:0x2400
	ds_read_b64_tr_b16 v[238:239], v197 offset:0x2c00
	ds_read_b64_tr_b16 v[240:241], v197 offset:0x3400
	ds_read_b64_tr_b16 v[242:243], v197 offset:0x3c00
	s_waitcnt lgkmcnt(0)
	v_mfma_f32_32x32x16_bf16 v[34:49], v[142:145], v[244:247], v[34:49]
	v_mfma_f32_32x32x16_bf16 v[18:33], v[130:133], v[228:231], v[18:33]
	ds_read_b64_tr_b16 v[228:229], v197 offset:0x600
	ds_read_b64_tr_b16 v[230:231], v197 offset:0xe00
	v_mfma_f32_32x32x16_bf16 v[18:33], v[134:137], v[232:235], v[18:33]
	ds_read_b64_tr_b16 v[232:233], v197 offset:0x1600
	ds_read_b64_tr_b16 v[234:235], v197 offset:0x1e00
	v_mfma_f32_32x32x16_bf16 v[18:33], v[138:141], v[236:239], v[18:33]
	ds_read_b64_tr_b16 v[236:237], v197 offset:0x2600
	ds_read_b64_tr_b16 v[238:239], v197 offset:0x2e00
	ds_read_b64_tr_b16 v[244:245], v197 offset:0x3600
	ds_read_b64_tr_b16 v[246:247], v197 offset:0x3e00
	s_waitcnt lgkmcnt(0)
	v_mfma_f32_32x32x16_bf16 v[18:33], v[142:145], v[240:243], v[18:33]
	v_mfma_f32_32x32x16_bf16 v[2:17], v[130:133], v[228:231], v[2:17]
	v_mfma_f32_32x32x16_bf16 v[2:17], v[134:137], v[232:235], v[2:17]
	v_mfma_f32_32x32x16_bf16 v[2:17], v[138:141], v[236:239], v[2:17]
	v_mfma_f32_32x32x16_bf16 v[2:17], v[142:145], v[244:247], v[2:17]
	s_cmp_lt_u32 s71, 3
	s_cbranch_scc1 .LBB0_2939
	s_add_i32 s0, s60, s69
	s_add_i32 s6, s0, 1
	s_cmp_lt_i32 s70, s58
	s_cselect_b64 s[0:1], -1, 0
	s_cmp_lt_i32 s6, s67
	v_cmp_ge_i32_e32 vcc, s6, v219
	s_cselect_b64 s[6:7], -1, 0
	s_and_b64 s[0:1], s[0:1], s[6:7]
	s_and_b64 s[0:1], s[0:1], vcc
	v_mov_b32_e32 v134, v218
	v_mov_b32_e32 v137, 0xf149f2ca
	s_andn2_b64 vcc, exec, s[0:1]
	v_mov_b32_e32 v138, 0xf149f2ca
	v_mov_b32_e32 v230, 0xf149f2ca
	v_mov_b32_e32 v231, 0xf149f2ca
	v_mov_b32_e32 v232, 0xf149f2ca
	v_mov_b32_e32 v233, 0xf149f2ca
	v_mov_b32_e32 v234, 0xf149f2ca
	v_mov_b32_e32 v235, 0xf149f2ca
	v_mov_b32_e32 v236, 0xf149f2ca
	v_mov_b32_e32 v237, 0xf149f2ca
	v_mov_b32_e32 v238, 0xf149f2ca
	v_mov_b32_e32 v239, 0xf149f2ca
	v_mov_b32_e32 v240, 0xf149f2ca
	v_mov_b32_e32 v241, 0xf149f2ca
	v_mov_b32_e32 v242, 0xf149f2ca
	v_mov_b32_e32 v243, 0xf149f2ca
	v_mov_b32_e32 v228, 0xf149f2ca
	v_mov_b32_e32 v229, 0xf149f2ca
	v_mov_b32_e32 v145, 0xf149f2ca
	v_mov_b32_e32 v227, 0xf149f2ca
	v_mov_b32_e32 v143, 0xf149f2ca
	v_mov_b32_e32 v144, 0xf149f2ca
	v_mov_b32_e32 v141, 0xf149f2ca
	v_mov_b32_e32 v142, 0xf149f2ca
	v_mov_b32_e32 v139, 0xf149f2ca
	v_mov_b32_e32 v140, 0xf149f2ca
	v_mov_b32_e32 v135, 0xf149f2ca
	v_mov_b32_e32 v136, 0xf149f2ca
	v_mov_b32_e32 v132, 0xf149f2ca
	v_mov_b32_e32 v133, 0xf149f2ca
	v_mov_b32_e32 v130, 0xf149f2ca
	v_mov_b32_e32 v131, 0xf149f2ca
	s_cbranch_vccnz .LBB0_2938
	v_add_u32_e32 v138, v220, v158
	v_sub_u32_e32 v251, v159, v134
	v_mov_b32_e32 v131, 0xf149f2ca
	v_cmp_gt_u32_e32 vcc, 16, v251
	s_nop 1
	s_and_saveexec_b64 s[6:7], vcc
	ds_read_b32 v131, v138 offset:124
	s_or_b64 exec, exec, s[6:7]
	v_sub_u32_e32 v251, v161, v134
	v_mov_b32_e32 v130, 0xf149f2ca
	v_cmp_gt_u32_e32 vcc, 16, v251
	s_nop 1
	s_and_saveexec_b64 s[6:7], vcc
	ds_read_b32 v130, v138 offset:128
	s_or_b64 exec, exec, s[6:7]
	v_sub_u32_e32 v251, v163, v134
	v_mov_b32_e32 v133, 0xf149f2ca
	v_cmp_gt_u32_e32 vcc, 16, v251
	s_nop 1
	s_and_saveexec_b64 s[6:7], vcc
	ds_read_b32 v133, v138 offset:132
	s_or_b64 exec, exec, s[6:7]
	v_sub_u32_e32 v251, v165, v134
	v_mov_b32_e32 v132, 0xf149f2ca
	v_cmp_gt_u32_e32 vcc, 16, v251
	s_nop 1
	s_and_saveexec_b64 s[6:7], vcc
	ds_read_b32 v132, v138 offset:136
	s_or_b64 exec, exec, s[6:7]
	v_sub_u32_e32 v251, v167, v134
	v_mov_b32_e32 v136, 0xf149f2ca
	v_cmp_gt_u32_e32 vcc, 16, v251
	s_nop 1
	s_and_saveexec_b64 s[6:7], vcc
	ds_read_b32 v136, v138 offset:156
	s_or_b64 exec, exec, s[6:7]
	v_sub_u32_e32 v251, v169, v134
	v_mov_b32_e32 v135, 0xf149f2ca
	v_cmp_gt_u32_e32 vcc, 16, v251
	s_nop 1
	s_and_saveexec_b64 s[6:7], vcc
	ds_read_b32 v135, v138 offset:160
	s_or_b64 exec, exec, s[6:7]
	v_sub_u32_e32 v251, v171, v134
	v_mov_b32_e32 v140, 0xf149f2ca
	v_cmp_gt_u32_e32 vcc, 16, v251
	s_nop 1
	s_and_saveexec_b64 s[6:7], vcc
	ds_read_b32 v140, v138 offset:164
	s_or_b64 exec, exec, s[6:7]
	v_sub_u32_e32 v251, v173, v134
	v_mov_b32_e32 v139, 0xf149f2ca
	v_cmp_gt_u32_e32 vcc, 16, v251
	s_nop 1
	s_and_saveexec_b64 s[6:7], vcc
	ds_read_b32 v139, v138 offset:168
	s_or_b64 exec, exec, s[6:7]
	v_sub_u32_e32 v251, v175, v134
	v_mov_b32_e32 v142, 0xf149f2ca
	v_cmp_gt_u32_e32 vcc, 16, v251
	s_nop 1
	s_and_saveexec_b64 s[6:7], vcc
	ds_read_b32 v142, v138 offset:188
	s_or_b64 exec, exec, s[6:7]
	v_sub_u32_e32 v251, v177, v134
	v_mov_b32_e32 v141, 0xf149f2ca
	v_cmp_gt_u32_e32 vcc, 16, v251
	s_nop 1
	s_and_saveexec_b64 s[6:7], vcc
	ds_read_b32 v141, v138 offset:192
	s_or_b64 exec, exec, s[6:7]
	v_sub_u32_e32 v251, v181, v134
	v_mov_b32_e32 v144, 0xf149f2ca
	v_cmp_gt_u32_e32 vcc, 16, v251
	s_nop 1
	s_and_saveexec_b64 s[6:7], vcc
	ds_read_b32 v144, v138 offset:196
	s_or_b64 exec, exec, s[6:7]
	v_sub_u32_e32 v251, v183, v134
	v_mov_b32_e32 v143, 0xf149f2ca
	v_cmp_gt_u32_e32 vcc, 16, v251
	s_nop 1
	s_and_saveexec_b64 s[6:7], vcc
	ds_read_b32 v143, v138 offset:200
	s_or_b64 exec, exec, s[6:7]
	v_sub_u32_e32 v251, v185, v134
	v_mov_b32_e32 v227, 0xf149f2ca
	v_cmp_gt_u32_e32 vcc, 16, v251
	s_nop 1
	s_and_saveexec_b64 s[6:7], vcc
	ds_read_b32 v227, v138 offset:220
	s_or_b64 exec, exec, s[6:7]
	v_sub_u32_e32 v251, v187, v134
	v_mov_b32_e32 v145, 0xf149f2ca
	v_cmp_gt_u32_e32 vcc, 16, v251
	s_nop 1
	s_and_saveexec_b64 s[6:7], vcc
	ds_read_b32 v145, v138 offset:224
	s_or_b64 exec, exec, s[6:7]
	v_sub_u32_e32 v251, v189, v134
	v_mov_b32_e32 v229, 0xf149f2ca
	v_cmp_gt_u32_e32 vcc, 16, v251
	s_nop 1
	s_and_saveexec_b64 s[6:7], vcc
	ds_read_b32 v229, v138 offset:228
	s_or_b64 exec, exec, s[6:7]
	v_sub_u32_e32 v251, v191, v134
	v_mov_b32_e32 v228, 0xf149f2ca
	v_cmp_gt_u32_e32 vcc, 16, v251
	s_nop 1
	s_and_saveexec_b64 s[6:7], vcc
	ds_read_b32 v228, v138 offset:232
	s_or_b64 exec, exec, s[6:7]
	s_waitcnt lgkmcnt(0)
	v_add_f32_e32 v131, v82, v131
	v_add_f32_e32 v130, v83, v130
	v_add_f32_e32 v133, v84, v133
	v_add_f32_e32 v132, v85, v132
	v_add_f32_e32 v136, v86, v136
	v_add_f32_e32 v135, v87, v135
	v_add_f32_e32 v140, v88, v140
	v_add_f32_e32 v139, v89, v139
	v_add_f32_e32 v142, v90, v142
	v_add_f32_e32 v141, v91, v141
	v_add_f32_e32 v144, v92, v144
	v_add_f32_e32 v143, v93, v143
	v_add_f32_e32 v227, v94, v227
	v_add_f32_e32 v145, v95, v145
	v_add_f32_e32 v229, v96, v229
	v_add_f32_e32 v228, v97, v228
	v_sub_u32_e32 v251, v160, v134
	v_cmp_gt_u32_e32 vcc, 16, v251
	s_nop 0
	s_nop 0
	v_cndmask_b32_e32 v251, v215, v160, vcc
	v_lshl_add_u32 v251, v251, 2, v220
	ds_read_b32 v137, v251 offset:124
	v_sub_u32_e32 v82, v162, v134
	v_cmp_gt_u32_e64 s[0:1], 16, v82
	s_nop 0
	s_nop 0
	v_cndmask_b32_e64 v82, v215, v162, s[0:1]
	v_lshl_add_u32 v82, v82, 2, v220
	ds_read_b32 v82, v82 offset:124
	v_sub_u32_e32 v83, v164, v134
	v_cmp_gt_u32_e64 s[8:9], 16, v83
	s_nop 0
	s_nop 0
	v_cndmask_b32_e64 v83, v215, v164, s[8:9]
	v_lshl_add_u32 v83, v83, 2, v220
	ds_read_b32 v83, v83 offset:124
	v_sub_u32_e32 v84, v166, v134
	v_cmp_gt_u32_e64 s[10:11], 16, v84
	s_nop 0
	s_nop 0
	v_cndmask_b32_e64 v84, v215, v166, s[10:11]
	v_lshl_add_u32 v84, v84, 2, v220
	ds_read_b32 v84, v84 offset:124
	v_sub_u32_e32 v85, v168, v134
	v_cmp_gt_u32_e64 s[12:13], 16, v85
	s_nop 0
	s_nop 0
	v_cndmask_b32_e64 v85, v215, v168, s[12:13]
	v_lshl_add_u32 v85, v85, 2, v220
	ds_read_b32 v85, v85 offset:124
	v_sub_u32_e32 v86, v170, v134
	v_cmp_gt_u32_e64 s[14:15], 16, v86
	s_nop 0
	s_nop 0
	v_cndmask_b32_e64 v86, v215, v170, s[14:15]
	v_lshl_add_u32 v86, v86, 2, v220
	ds_read_b32 v86, v86 offset:124
	v_sub_u32_e32 v87, v172, v134
	v_cmp_gt_u32_e64 s[16:17], 16, v87
	s_nop 0
	s_nop 0
	v_cndmask_b32_e64 v87, v215, v172, s[16:17]
	v_lshl_add_u32 v87, v87, 2, v220
	ds_read_b32 v87, v87 offset:124
	v_sub_u32_e32 v88, v174, v134
	v_cmp_gt_u32_e64 s[18:19], 16, v88
	s_nop 0
	s_nop 0
	v_cndmask_b32_e64 v88, v215, v174, s[18:19]
	v_lshl_add_u32 v88, v88, 2, v220
	ds_read_b32 v88, v88 offset:124
	v_sub_u32_e32 v89, v176, v134
	v_cmp_gt_u32_e64 s[20:21], 16, v89
	s_nop 0
	s_nop 0
	v_cndmask_b32_e64 v89, v215, v176, s[20:21]
	v_lshl_add_u32 v89, v89, 2, v220
	ds_read_b32 v89, v89 offset:124
	v_sub_u32_e32 v90, v179, v134
	v_cmp_gt_u32_e64 s[22:23], 16, v90
	s_nop 0
	s_nop 0
	v_cndmask_b32_e64 v90, v215, v179, s[22:23]
	v_lshl_add_u32 v90, v90, 2, v220
	ds_read_b32 v90, v90 offset:124
	v_sub_u32_e32 v91, v182, v134
	v_cmp_gt_u32_e64 s[24:25], 16, v91
	s_nop 0
	s_nop 0
	v_cndmask_b32_e64 v91, v215, v182, s[24:25]
	v_lshl_add_u32 v91, v91, 2, v220
	ds_read_b32 v91, v91 offset:124
	v_sub_u32_e32 v92, v184, v134
	v_cmp_gt_u32_e64 s[26:27], 16, v92
	s_nop 0
	s_nop 0
	v_cndmask_b32_e64 v92, v215, v184, s[26:27]
	v_lshl_add_u32 v92, v92, 2, v220
	ds_read_b32 v92, v92 offset:124
	v_sub_u32_e32 v93, v186, v134
	v_cmp_gt_u32_e64 s[28:29], 16, v93
	s_nop 0
	s_nop 0
	v_cndmask_b32_e64 v93, v215, v186, s[28:29]
	v_lshl_add_u32 v93, v93, 2, v220
	ds_read_b32 v93, v93 offset:124
	v_sub_u32_e32 v94, v188, v134
	v_cmp_gt_u32_e64 s[30:31], 16, v94
	s_nop 0
	s_nop 0
	v_cndmask_b32_e64 v94, v215, v188, s[30:31]
	v_lshl_add_u32 v94, v94, 2, v220
	ds_read_b32 v94, v94 offset:124
	v_sub_u32_e32 v95, v190, v134
	v_cmp_gt_u32_e64 s[34:35], 16, v95
	s_nop 0
	s_nop 0
	v_cndmask_b32_e64 v95, v215, v190, s[34:35]
	v_lshl_add_u32 v95, v95, 2, v220
	ds_read_b32 v95, v95 offset:124
	v_sub_u32_e32 v96, v192, v134
	v_cmp_gt_u32_e64 s[36:37], 16, v96
	s_nop 0
	s_nop 0
	v_cndmask_b32_e64 v96, v215, v192, s[36:37]
	v_lshl_add_u32 v96, v96, 2, v220
	ds_read_b32 v96, v96 offset:124
.LBB0_2937:
	s_waitcnt lgkmcnt(14)
	v_add_f32_e32 v66, v66, v137
	v_cndmask_b32_e32 v243, v212, v66, vcc
	v_add_f32_e32 v66, v67, v82
	v_cndmask_b32_e64 v242, v212, v66, s[0:1]
	s_waitcnt lgkmcnt(13)
	v_add_f32_e32 v66, v68, v83
	v_cndmask_b32_e64 v241, v212, v66, s[8:9]
	s_waitcnt lgkmcnt(12)
	v_add_f32_e32 v66, v69, v84
	v_cndmask_b32_e64 v240, v212, v66, s[10:11]
	s_waitcnt lgkmcnt(11)
	v_add_f32_e32 v66, v70, v85
	v_cndmask_b32_e64 v239, v212, v66, s[12:13]
	s_waitcnt lgkmcnt(10)
	v_add_f32_e32 v66, v71, v86
	v_cndmask_b32_e64 v238, v212, v66, s[14:15]
	s_waitcnt lgkmcnt(9)
	v_add_f32_e32 v66, v72, v87
	v_cndmask_b32_e64 v237, v212, v66, s[16:17]
	s_waitcnt lgkmcnt(8)
	v_add_f32_e32 v66, v73, v88
	v_cndmask_b32_e64 v236, v212, v66, s[18:19]
	s_waitcnt lgkmcnt(7)
	v_add_f32_e32 v66, v74, v89
	v_cndmask_b32_e64 v235, v212, v66, s[20:21]
	s_waitcnt lgkmcnt(6)
	v_add_f32_e32 v66, v75, v90
	v_cndmask_b32_e64 v234, v212, v66, s[22:23]
	s_waitcnt lgkmcnt(5)
	v_add_f32_e32 v66, v76, v91
	v_cndmask_b32_e64 v233, v212, v66, s[24:25]
	s_waitcnt lgkmcnt(4)
	v_add_f32_e32 v66, v77, v92
	v_cndmask_b32_e64 v232, v212, v66, s[26:27]
	s_waitcnt lgkmcnt(3)
	v_add_f32_e32 v66, v78, v93
	v_cndmask_b32_e64 v231, v212, v66, s[28:29]
	s_waitcnt lgkmcnt(2)
	v_add_f32_e32 v66, v79, v94
	v_cndmask_b32_e64 v230, v212, v66, s[30:31]
	s_waitcnt lgkmcnt(1)
	v_add_f32_e32 v66, v80, v95
	v_cndmask_b32_e64 v138, v212, v66, s[34:35]
	s_waitcnt lgkmcnt(0)
	v_add_f32_e32 v66, v81, v96
	v_cndmask_b32_e64 v137, v212, v66, s[36:37]

.LBB0_3060:
	ds_read_b128 v[154:157], v150
	ds_read_b128 v[158:161], v150 offset:1024
	ds_read_b128 v[162:165], v150 offset:2048
	ds_read_b128 v[166:169], v150 offset:3072
	ds_read_b128 v[170:173], v151
	ds_read_b128 v[174:177], v151 offset:1024
	ds_read_b128 v[182:185], v151 offset:2048
	ds_read_b128 v[186:189], v151 offset:3072
	s_add_u32 s28, s26, 0xfff80080
	s_addc_u32 s29, s27, -1
	s_cmp_eq_u32 s60, 28
	s_cselect_b32 s31, s19, s29
	s_cselect_b32 s30, s56, s28
	s_cselect_b32 s29, s17, s59
	s_cselect_b32 s28, s57, s58
	v_lshl_add_u64 v[146:147], s[26:27], 0, v[138:139]
	s_add_i32 m0, s25, 0xc000
	ds_read_b128 v[190:193], v152
	ds_read_b128 v[194:197], v152 offset:1024
	ds_read_b128 v[198:201], v152 offset:2048
	ds_read_b128 v[202:205], v152 offset:3072
	ds_read_b128 v[206:209], v152 offset:4096
	ds_read_b128 v[210:213], v152 offset:5120
	ds_read_b128 v[214:217], v152 offset:6144
	ds_read_b128 v[218:221], v152 offset:7168
	global_load_lds_dwordx4 v[146:147], off
	v_lshl_add_u64 v[146:147], s[26:27], 0, v[140:141]
	s_add_i32 m0, s25, 0xe000
	s_nop 0
	global_load_lds_dwordx4 v[146:147], off
	s_waitcnt vmcnt(8)
	s_waitcnt lgkmcnt(0)
	s_setprio 1
	s_barrier
	v_mfma_f32_16x16x32_bf16 v[126:129], v[154:157], v[190:193], v[126:129]
	v_mfma_f32_16x16x32_bf16 v[122:125], v[162:165], v[190:193], v[122:125]
	v_mfma_f32_16x16x32_bf16 v[118:121], v[154:157], v[198:201], v[118:121]
	v_mfma_f32_16x16x32_bf16 v[110:113], v[162:165], v[198:201], v[110:113]
	v_mfma_f32_16x16x32_bf16 v[102:105], v[154:157], v[206:209], v[102:105]
	v_mfma_f32_16x16x32_bf16 v[94:97], v[162:165], v[206:209], v[94:97]
	v_mfma_f32_16x16x32_bf16 v[86:89], v[154:157], v[214:217], v[86:89]
	v_mfma_f32_16x16x32_bf16 v[78:81], v[162:165], v[214:217], v[78:81]
	v_mfma_f32_16x16x32_bf16 v[126:129], v[158:161], v[194:197], v[126:129]
	v_mfma_f32_16x16x32_bf16 v[122:125], v[166:169], v[194:197], v[122:125]
	v_mfma_f32_16x16x32_bf16 v[118:121], v[158:161], v[202:205], v[118:121]
	v_mfma_f32_16x16x32_bf16 v[110:113], v[166:169], v[202:205], v[110:113]
	v_mfma_f32_16x16x32_bf16 v[102:105], v[158:161], v[210:213], v[102:105]
	v_mfma_f32_16x16x32_bf16 v[94:97], v[166:169], v[210:213], v[94:97]
	v_mfma_f32_16x16x32_bf16 v[86:89], v[158:161], v[218:221], v[86:89]
	v_mfma_f32_16x16x32_bf16 v[78:81], v[166:169], v[218:221], v[78:81]
	v_mfma_f32_16x16x32_bf16 v[114:117], v[170:173], v[190:193], v[114:117]
	v_mfma_f32_16x16x32_bf16 v[106:109], v[182:185], v[190:193], v[106:109]
	v_mfma_f32_16x16x32_bf16 v[98:101], v[170:173], v[198:201], v[98:101]
	v_mfma_f32_16x16x32_bf16 v[90:93], v[182:185], v[198:201], v[90:93]
	v_mfma_f32_16x16x32_bf16 v[82:85], v[170:173], v[206:209], v[82:85]
	v_mfma_f32_16x16x32_bf16 v[74:77], v[182:185], v[206:209], v[74:77]
	v_mfma_f32_16x16x32_bf16 v[70:73], v[170:173], v[214:217], v[70:73]
	v_mfma_f32_16x16x32_bf16 v[66:69], v[182:185], v[214:217], v[66:69]
	v_mfma_f32_16x16x32_bf16 v[114:117], v[174:177], v[194:197], v[114:117]
	v_mfma_f32_16x16x32_bf16 v[106:109], v[186:189], v[194:197], v[106:109]
	v_mfma_f32_16x16x32_bf16 v[98:101], v[174:177], v[202:205], v[98:101]
	v_mfma_f32_16x16x32_bf16 v[90:93], v[186:189], v[202:205], v[90:93]
	v_mfma_f32_16x16x32_bf16 v[82:85], v[174:177], v[210:213], v[82:85]
	v_mfma_f32_16x16x32_bf16 v[74:77], v[186:189], v[210:213], v[74:77]
	v_mfma_f32_16x16x32_bf16 v[70:73], v[174:177], v[218:221], v[70:73]
	v_mfma_f32_16x16x32_bf16 v[66:69], v[186:189], v[218:221], v[66:69]
	s_barrier
	s_setprio 0
	s_add_i32 s62, s47, s37
	v_lshl_add_u64 v[146:147], s[28:29], 0, v[132:133]
	s_mov_b32 m0, s62
	ds_read_b128 v[190:193], v152 offset:16384
	ds_read_b128 v[194:197], v152 offset:17408
	ds_read_b128 v[198:201], v152 offset:18432
	ds_read_b128 v[202:205], v152 offset:19456
	ds_read_b128 v[206:209], v152 offset:20480
	ds_read_b128 v[210:213], v152 offset:21504
	ds_read_b128 v[214:217], v152 offset:22528
	ds_read_b128 v[218:221], v152 offset:23552
	global_load_lds_dwordx4 v[146:147], off
	s_add_i32 m0, s62, 0x2000
	s_add_u32 s62, s28, 0x80000
	v_lshl_add_u64 v[222:223], s[28:29], 0, v[136:137]
	s_addc_u32 s63, s29, 0
	s_add_i32 s66, s50, s37
	global_load_lds_dwordx4 v[222:223], off
	v_lshl_add_u64 v[224:225], s[62:63], 0, v[132:133]
	s_mov_b32 m0, s66
	v_lshl_add_u64 v[226:227], s[30:31], 0, v[134:135]
	global_load_lds_dwordx4 v[224:225], off
	v_lshl_add_u64 v[224:225], s[62:63], 0, v[136:137]
	s_add_i32 m0, s66, 0x2000
	s_nop 0
	global_load_lds_dwordx4 v[224:225], off
	v_lshl_add_u64 v[224:225], s[30:31], 0, v[130:131]
	s_mov_b32 m0, s25
	s_nop 0
	global_load_lds_dwordx4 v[224:225], off
	s_mov_b32 m0, s38
	s_nop 0
	global_load_lds_dwordx4 v[226:227], off
	s_waitcnt vmcnt(8)
	s_waitcnt lgkmcnt(0)
	s_setprio 1
	s_barrier
	v_mfma_f32_16x16x32_bf16 v[62:65], v[154:157], v[190:193], v[62:65]
	v_mfma_f32_16x16x32_bf16 v[58:61], v[162:165], v[190:193], v[58:61]
	v_mfma_f32_16x16x32_bf16 v[54:57], v[154:157], v[198:201], v[54:57]
	v_mfma_f32_16x16x32_bf16 v[46:49], v[162:165], v[198:201], v[46:49]
	v_mfma_f32_16x16x32_bf16 v[38:41], v[154:157], v[206:209], v[38:41]
	v_mfma_f32_16x16x32_bf16 v[30:33], v[162:165], v[206:209], v[30:33]
	v_mfma_f32_16x16x32_bf16 v[22:25], v[154:157], v[214:217], v[22:25]
	v_mfma_f32_16x16x32_bf16 v[14:17], v[162:165], v[214:217], v[14:17]
	v_mfma_f32_16x16x32_bf16 v[62:65], v[158:161], v[194:197], v[62:65]
	v_mfma_f32_16x16x32_bf16 v[58:61], v[166:169], v[194:197], v[58:61]
	v_mfma_f32_16x16x32_bf16 v[54:57], v[158:161], v[202:205], v[54:57]
	v_mfma_f32_16x16x32_bf16 v[46:49], v[166:169], v[202:205], v[46:49]
	v_mfma_f32_16x16x32_bf16 v[38:41], v[158:161], v[210:213], v[38:41]
	v_mfma_f32_16x16x32_bf16 v[30:33], v[166:169], v[210:213], v[30:33]
	v_mfma_f32_16x16x32_bf16 v[22:25], v[158:161], v[218:221], v[22:25]
	v_mfma_f32_16x16x32_bf16 v[14:17], v[166:169], v[218:221], v[14:17]
	v_mfma_f32_16x16x32_bf16 v[50:53], v[170:173], v[190:193], v[50:53]
	v_mfma_f32_16x16x32_bf16 v[42:45], v[182:185], v[190:193], v[42:45]
	v_mfma_f32_16x16x32_bf16 v[34:37], v[170:173], v[198:201], v[34:37]
	v_mfma_f32_16x16x32_bf16 v[26:29], v[182:185], v[198:201], v[26:29]
	v_mfma_f32_16x16x32_bf16 v[18:21], v[170:173], v[206:209], v[18:21]
	v_mfma_f32_16x16x32_bf16 v[10:13], v[182:185], v[206:209], v[10:13]
	v_mfma_f32_16x16x32_bf16 v[6:9], v[170:173], v[214:217], v[6:9]
	v_mfma_f32_16x16x32_bf16 v[2:5], v[182:185], v[214:217], v[2:5]
	v_mfma_f32_16x16x32_bf16 v[50:53], v[174:177], v[194:197], v[50:53]
	v_mfma_f32_16x16x32_bf16 v[42:45], v[186:189], v[194:197], v[42:45]
	v_mfma_f32_16x16x32_bf16 v[34:37], v[174:177], v[202:205], v[34:37]
	v_mfma_f32_16x16x32_bf16 v[26:29], v[186:189], v[202:205], v[26:29]
	v_mfma_f32_16x16x32_bf16 v[18:21], v[174:177], v[210:213], v[18:21]
	v_mfma_f32_16x16x32_bf16 v[10:13], v[186:189], v[210:213], v[10:13]
	v_mfma_f32_16x16x32_bf16 v[6:9], v[174:177], v[218:221], v[6:9]
	v_mfma_f32_16x16x32_bf16 v[2:5], v[186:189], v[218:221], v[2:5]
	s_barrier
	s_setprio 0
	s_add_i32 s62, 0, 0x18000
	v_add_u32_e32 v153, s62, v148
	s_add_i32 s63, 0, 0x1c000
	ds_read_b128 v[154:157], v153
	ds_read_b128 v[158:161], v153 offset:1024
	ds_read_b128 v[162:165], v153 offset:2048
	ds_read_b128 v[166:169], v153 offset:3072
	v_add_u32_e32 v153, s63, v148
	ds_read_b128 v[170:173], v153
	ds_read_b128 v[174:177], v153 offset:1024
	ds_read_b128 v[182:185], v153 offset:2048
	ds_read_b128 v[186:189], v153 offset:3072
	s_add_u32 s30, s30, 0x80000
	s_addc_u32 s31, s31, 0
	s_mov_b32 m0, s39
	v_lshl_add_u64 v[228:229], s[30:31], 0, v[130:131]
	ds_read_b128 v[190:193], v152 offset:32768
	ds_read_b128 v[194:197], v152 offset:33792
	ds_read_b128 v[198:201], v152 offset:34816
	ds_read_b128 v[202:205], v152 offset:35840
	ds_read_b128 v[206:209], v152 offset:36864
	ds_read_b128 v[210:213], v152 offset:37888
	ds_read_b128 v[214:217], v152 offset:38912
	ds_read_b128 v[218:221], v152 offset:39936
	global_load_lds_dwordx4 v[228:229], off
	v_lshl_add_u64 v[228:229], s[30:31], 0, v[134:135]
	s_mov_b32 m0, s42
	s_nop 0
	global_load_lds_dwordx4 v[228:229], off
	s_waitcnt vmcnt(8)
	s_waitcnt lgkmcnt(0)
	s_setprio 1
	s_barrier
	v_mfma_f32_16x16x32_bf16 v[126:129], v[154:157], v[190:193], v[126:129]
	v_mfma_f32_16x16x32_bf16 v[122:125], v[162:165], v[190:193], v[122:125]
	v_mfma_f32_16x16x32_bf16 v[118:121], v[154:157], v[198:201], v[118:121]
	v_mfma_f32_16x16x32_bf16 v[110:113], v[162:165], v[198:201], v[110:113]
	v_mfma_f32_16x16x32_bf16 v[102:105], v[154:157], v[206:209], v[102:105]
	v_mfma_f32_16x16x32_bf16 v[94:97], v[162:165], v[206:209], v[94:97]
	v_mfma_f32_16x16x32_bf16 v[86:89], v[154:157], v[214:217], v[86:89]
	v_mfma_f32_16x16x32_bf16 v[78:81], v[162:165], v[214:217], v[78:81]
	v_mfma_f32_16x16x32_bf16 v[126:129], v[158:161], v[194:197], v[126:129]
	v_mfma_f32_16x16x32_bf16 v[122:125], v[166:169], v[194:197], v[122:125]
	v_mfma_f32_16x16x32_bf16 v[118:121], v[158:161], v[202:205], v[118:121]
	v_mfma_f32_16x16x32_bf16 v[110:113], v[166:169], v[202:205], v[110:113]
	v_mfma_f32_16x16x32_bf16 v[102:105], v[158:161], v[210:213], v[102:105]
	v_mfma_f32_16x16x32_bf16 v[94:97], v[166:169], v[210:213], v[94:97]
	v_mfma_f32_16x16x32_bf16 v[86:89], v[158:161], v[218:221], v[86:89]
	v_mfma_f32_16x16x32_bf16 v[78:81], v[166:169], v[218:221], v[78:81]
	v_mfma_f32_16x16x32_bf16 v[114:117], v[170:173], v[190:193], v[114:117]
	v_mfma_f32_16x16x32_bf16 v[106:109], v[182:185], v[190:193], v[106:109]
	v_mfma_f32_16x16x32_bf16 v[98:101], v[170:173], v[198:201], v[98:101]
	v_mfma_f32_16x16x32_bf16 v[90:93], v[182:185], v[198:201], v[90:93]
	v_mfma_f32_16x16x32_bf16 v[82:85], v[170:173], v[206:209], v[82:85]
	v_mfma_f32_16x16x32_bf16 v[74:77], v[182:185], v[206:209], v[74:77]
	v_mfma_f32_16x16x32_bf16 v[70:73], v[170:173], v[214:217], v[70:73]
	v_mfma_f32_16x16x32_bf16 v[66:69], v[182:185], v[214:217], v[66:69]
	v_mfma_f32_16x16x32_bf16 v[114:117], v[174:177], v[194:197], v[114:117]
	v_mfma_f32_16x16x32_bf16 v[106:109], v[186:189], v[194:197], v[106:109]
	v_mfma_f32_16x16x32_bf16 v[98:101], v[174:177], v[202:205], v[98:101]
	v_mfma_f32_16x16x32_bf16 v[90:93], v[186:189], v[202:205], v[90:93]
	v_mfma_f32_16x16x32_bf16 v[82:85], v[174:177], v[210:213], v[82:85]
	v_mfma_f32_16x16x32_bf16 v[74:77], v[186:189], v[210:213], v[74:77]
	v_mfma_f32_16x16x32_bf16 v[70:73], v[174:177], v[218:221], v[70:73]
	v_mfma_f32_16x16x32_bf16 v[66:69], v[186:189], v[218:221], v[66:69]
	s_barrier
	s_setprio 0
	s_add_i32 s30, s62, s37
	v_lshl_add_u64 v[146:147], v[146:147], 0, s[6:7]
	s_mov_b32 m0, s30
	ds_read_b128 v[190:193], v152 offset:49152
	ds_read_b128 v[194:197], v152 offset:50176
	ds_read_b128 v[198:201], v152 offset:51200
	ds_read_b128 v[202:205], v152 offset:52224
	ds_read_b128 v[206:209], v152 offset:53248
	ds_read_b128 v[210:213], v152 offset:54272
	ds_read_b128 v[214:217], v152 offset:55296
	ds_read_b128 v[218:221], v152 offset:56320
	global_load_lds_dwordx4 v[146:147], off
	s_add_i32 m0, s30, 0x2000
	s_add_u32 s28, s28, 0x80080
	v_lshl_add_u64 v[146:147], v[222:223], 0, s[6:7]
	s_addc_u32 s29, s29, 0
	s_add_i32 s30, s63, s37
	global_load_lds_dwordx4 v[146:147], off
	v_lshl_add_u64 v[146:147], s[28:29], 0, v[132:133]
	s_mov_b32 m0, s30
	s_nop 0
	global_load_lds_dwordx4 v[146:147], off
	v_lshl_add_u64 v[146:147], s[28:29], 0, v[136:137]
	s_add_i32 m0, s30, 0x2000
	s_nop 0
	global_load_lds_dwordx4 v[146:147], off
	v_lshl_add_u64 v[146:147], v[224:225], 0, s[6:7]
	s_mov_b32 m0, s44
	s_nop 0
	global_load_lds_dwordx4 v[146:147], off
	v_lshl_add_u64 v[146:147], v[226:227], 0, s[6:7]
	s_mov_b32 m0, s45
	s_nop 0
	global_load_lds_dwordx4 v[146:147], off
	s_waitcnt vmcnt(8)
	s_waitcnt lgkmcnt(0)
	s_setprio 1
	s_barrier
	v_mfma_f32_16x16x32_bf16 v[62:65], v[154:157], v[190:193], v[62:65]
	v_mfma_f32_16x16x32_bf16 v[58:61], v[162:165], v[190:193], v[58:61]
	v_mfma_f32_16x16x32_bf16 v[54:57], v[154:157], v[198:201], v[54:57]
	v_mfma_f32_16x16x32_bf16 v[46:49], v[162:165], v[198:201], v[46:49]
	v_mfma_f32_16x16x32_bf16 v[38:41], v[154:157], v[206:209], v[38:41]
	v_mfma_f32_16x16x32_bf16 v[30:33], v[162:165], v[206:209], v[30:33]
	v_mfma_f32_16x16x32_bf16 v[22:25], v[154:157], v[214:217], v[22:25]
	v_mfma_f32_16x16x32_bf16 v[14:17], v[162:165], v[214:217], v[14:17]
	v_mfma_f32_16x16x32_bf16 v[62:65], v[158:161], v[194:197], v[62:65]
	v_mfma_f32_16x16x32_bf16 v[58:61], v[166:169], v[194:197], v[58:61]
	v_mfma_f32_16x16x32_bf16 v[54:57], v[158:161], v[202:205], v[54:57]
	v_mfma_f32_16x16x32_bf16 v[46:49], v[166:169], v[202:205], v[46:49]
	v_mfma_f32_16x16x32_bf16 v[38:41], v[158:161], v[210:213], v[38:41]
	v_mfma_f32_16x16x32_bf16 v[30:33], v[166:169], v[210:213], v[30:33]
	v_mfma_f32_16x16x32_bf16 v[22:25], v[158:161], v[218:221], v[22:25]
	v_mfma_f32_16x16x32_bf16 v[14:17], v[166:169], v[218:221], v[14:17]
	v_mfma_f32_16x16x32_bf16 v[50:53], v[170:173], v[190:193], v[50:53]
	v_mfma_f32_16x16x32_bf16 v[42:45], v[182:185], v[190:193], v[42:45]
	v_mfma_f32_16x16x32_bf16 v[34:37], v[170:173], v[198:201], v[34:37]
	v_mfma_f32_16x16x32_bf16 v[26:29], v[182:185], v[198:201], v[26:29]
	v_mfma_f32_16x16x32_bf16 v[18:21], v[170:173], v[206:209], v[18:21]
	v_mfma_f32_16x16x32_bf16 v[10:13], v[182:185], v[206:209], v[10:13]
	v_mfma_f32_16x16x32_bf16 v[6:9], v[170:173], v[214:217], v[6:9]
	v_mfma_f32_16x16x32_bf16 v[2:5], v[182:185], v[214:217], v[2:5]
	v_mfma_f32_16x16x32_bf16 v[50:53], v[174:177], v[194:197], v[50:53]
	v_mfma_f32_16x16x32_bf16 v[42:45], v[186:189], v[194:197], v[42:45]
	v_mfma_f32_16x16x32_bf16 v[34:37], v[174:177], v[202:205], v[34:37]
	v_mfma_f32_16x16x32_bf16 v[26:29], v[186:189], v[202:205], v[26:29]
	v_mfma_f32_16x16x32_bf16 v[18:21], v[174:177], v[210:213], v[18:21]
	v_mfma_f32_16x16x32_bf16 v[10:13], v[186:189], v[210:213], v[10:13]
	v_mfma_f32_16x16x32_bf16 v[6:9], v[174:177], v[218:221], v[6:9]
	v_mfma_f32_16x16x32_bf16 v[2:5], v[186:189], v[218:221], v[2:5]
	s_barrier
	s_setprio 0
	s_add_i32 s60, s60, 2
	s_add_u32 s26, s26, 0x100
	s_addc_u32 s27, s27, 0
	s_add_u32 s58, s58, 0x100
	s_addc_u32 s59, s59, 0
	s_cmp_gt_u32 s60, 29
	s_cbranch_scc0 .LBB0_3060
	s_and_b64 vcc, exec, s[8:9]
	s_cbranch_vccz .LBB0_3063
	s_barrier

.LBB0_3191:
	ds_read_b128 v[154:157], v150
	ds_read_b128 v[158:161], v150 offset:1024
	ds_read_b128 v[162:165], v150 offset:2048
	ds_read_b128 v[166:169], v150 offset:3072
	ds_read_b128 v[170:173], v151
	ds_read_b128 v[174:177], v151 offset:1024
	ds_read_b128 v[182:185], v151 offset:2048
	ds_read_b128 v[186:189], v151 offset:3072
	s_add_u32 s20, s18, 0xfff80080
	s_addc_u32 s21, s19, -1
	s_cmp_eq_u32 s50, 28
	s_cselect_b32 s23, s11, s21
	s_cselect_b32 s22, s44, s20
	s_cselect_b32 s21, s9, s47
	s_cselect_b32 s20, s45, s46
	v_lshl_add_u64 v[146:147], s[18:19], 0, v[138:139]
	s_add_i32 m0, s17, 0xc000
	ds_read_b128 v[190:193], v152
	ds_read_b128 v[194:197], v152 offset:1024
	ds_read_b128 v[198:201], v152 offset:2048
	ds_read_b128 v[202:205], v152 offset:3072
	ds_read_b128 v[206:209], v152 offset:4096
	ds_read_b128 v[210:213], v152 offset:5120
	ds_read_b128 v[214:217], v152 offset:6144
	ds_read_b128 v[218:221], v152 offset:7168
	global_load_lds_dwordx4 v[146:147], off
	v_lshl_add_u64 v[146:147], s[18:19], 0, v[140:141]
	s_add_i32 m0, s17, 0xe000
	s_nop 0
	global_load_lds_dwordx4 v[146:147], off
	s_waitcnt vmcnt(8)
	s_waitcnt lgkmcnt(0)
	s_setprio 1
	s_barrier
	v_mfma_f32_16x16x32_bf16 v[126:129], v[154:157], v[190:193], v[126:129]
	v_mfma_f32_16x16x32_bf16 v[122:125], v[162:165], v[190:193], v[122:125]
	v_mfma_f32_16x16x32_bf16 v[110:113], v[154:157], v[198:201], v[110:113]
	v_mfma_f32_16x16x32_bf16 v[106:109], v[162:165], v[198:201], v[106:109]
	v_mfma_f32_16x16x32_bf16 v[94:97], v[154:157], v[206:209], v[94:97]
	v_mfma_f32_16x16x32_bf16 v[90:93], v[162:165], v[206:209], v[90:93]
	v_mfma_f32_16x16x32_bf16 v[78:81], v[154:157], v[214:217], v[78:81]
	v_mfma_f32_16x16x32_bf16 v[74:77], v[162:165], v[214:217], v[74:77]
	v_mfma_f32_16x16x32_bf16 v[126:129], v[158:161], v[194:197], v[126:129]
	v_mfma_f32_16x16x32_bf16 v[122:125], v[166:169], v[194:197], v[122:125]
	v_mfma_f32_16x16x32_bf16 v[110:113], v[158:161], v[202:205], v[110:113]
	v_mfma_f32_16x16x32_bf16 v[106:109], v[166:169], v[202:205], v[106:109]
	v_mfma_f32_16x16x32_bf16 v[94:97], v[158:161], v[210:213], v[94:97]
	v_mfma_f32_16x16x32_bf16 v[90:93], v[166:169], v[210:213], v[90:93]
	v_mfma_f32_16x16x32_bf16 v[78:81], v[158:161], v[218:221], v[78:81]
	v_mfma_f32_16x16x32_bf16 v[74:77], v[166:169], v[218:221], v[74:77]
	v_mfma_f32_16x16x32_bf16 v[118:121], v[170:173], v[190:193], v[118:121]
	v_mfma_f32_16x16x32_bf16 v[114:117], v[182:185], v[190:193], v[114:117]
	v_mfma_f32_16x16x32_bf16 v[102:105], v[170:173], v[198:201], v[102:105]
	v_mfma_f32_16x16x32_bf16 v[98:101], v[182:185], v[198:201], v[98:101]
	v_mfma_f32_16x16x32_bf16 v[86:89], v[170:173], v[206:209], v[86:89]
	v_mfma_f32_16x16x32_bf16 v[82:85], v[182:185], v[206:209], v[82:85]
	v_mfma_f32_16x16x32_bf16 v[70:73], v[170:173], v[214:217], v[70:73]
	v_mfma_f32_16x16x32_bf16 v[66:69], v[182:185], v[214:217], v[66:69]
	v_mfma_f32_16x16x32_bf16 v[118:121], v[174:177], v[194:197], v[118:121]
	v_mfma_f32_16x16x32_bf16 v[114:117], v[186:189], v[194:197], v[114:117]
	v_mfma_f32_16x16x32_bf16 v[102:105], v[174:177], v[202:205], v[102:105]
	v_mfma_f32_16x16x32_bf16 v[98:101], v[186:189], v[202:205], v[98:101]
	v_mfma_f32_16x16x32_bf16 v[86:89], v[174:177], v[210:213], v[86:89]
	v_mfma_f32_16x16x32_bf16 v[82:85], v[186:189], v[210:213], v[82:85]
	v_mfma_f32_16x16x32_bf16 v[70:73], v[174:177], v[218:221], v[70:73]
	v_mfma_f32_16x16x32_bf16 v[66:69], v[186:189], v[218:221], v[66:69]
	s_barrier
	s_setprio 0
	s_add_i32 s51, s38, s26
	v_lshl_add_u64 v[146:147], s[20:21], 0, v[134:135]
	s_mov_b32 m0, s51
	ds_read_b128 v[190:193], v152 offset:16384
	ds_read_b128 v[194:197], v152 offset:17408
	ds_read_b128 v[198:201], v152 offset:18432
	ds_read_b128 v[202:205], v152 offset:19456
	ds_read_b128 v[206:209], v152 offset:20480
	ds_read_b128 v[210:213], v152 offset:21504
	ds_read_b128 v[214:217], v152 offset:22528
	ds_read_b128 v[218:221], v152 offset:23552
	global_load_lds_dwordx4 v[146:147], off
	s_add_i32 m0, s51, 0x2000
	s_add_u32 s52, s20, 0x80000
	v_lshl_add_u64 v[222:223], s[20:21], 0, v[130:131]
	s_addc_u32 s53, s21, 0
	s_add_i32 s51, s39, s26
	global_load_lds_dwordx4 v[222:223], off
	v_lshl_add_u64 v[224:225], s[52:53], 0, v[134:135]
	s_mov_b32 m0, s51
	v_lshl_add_u64 v[226:227], s[22:23], 0, v[132:133]
	global_load_lds_dwordx4 v[224:225], off
	v_lshl_add_u64 v[224:225], s[52:53], 0, v[130:131]
	s_add_i32 m0, s51, 0x2000
	s_nop 0
	global_load_lds_dwordx4 v[224:225], off
	v_lshl_add_u64 v[224:225], s[22:23], 0, v[136:137]
	s_mov_b32 m0, s17
	s_nop 0
	global_load_lds_dwordx4 v[224:225], off
	s_mov_b32 m0, s29
	s_nop 0
	global_load_lds_dwordx4 v[226:227], off
	s_waitcnt vmcnt(8)
	s_waitcnt lgkmcnt(0)
	s_setprio 1
	s_barrier
	v_mfma_f32_16x16x32_bf16 v[62:65], v[154:157], v[190:193], v[62:65]
	v_mfma_f32_16x16x32_bf16 v[58:61], v[162:165], v[190:193], v[58:61]
	v_mfma_f32_16x16x32_bf16 v[46:49], v[154:157], v[198:201], v[46:49]
	v_mfma_f32_16x16x32_bf16 v[42:45], v[162:165], v[198:201], v[42:45]
	v_mfma_f32_16x16x32_bf16 v[30:33], v[154:157], v[206:209], v[30:33]
	v_mfma_f32_16x16x32_bf16 v[26:29], v[162:165], v[206:209], v[26:29]
	v_mfma_f32_16x16x32_bf16 v[14:17], v[154:157], v[214:217], v[14:17]
	v_mfma_f32_16x16x32_bf16 v[10:13], v[162:165], v[214:217], v[10:13]
	v_mfma_f32_16x16x32_bf16 v[62:65], v[158:161], v[194:197], v[62:65]
	v_mfma_f32_16x16x32_bf16 v[58:61], v[166:169], v[194:197], v[58:61]
	v_mfma_f32_16x16x32_bf16 v[46:49], v[158:161], v[202:205], v[46:49]
	v_mfma_f32_16x16x32_bf16 v[42:45], v[166:169], v[202:205], v[42:45]
	v_mfma_f32_16x16x32_bf16 v[30:33], v[158:161], v[210:213], v[30:33]
	v_mfma_f32_16x16x32_bf16 v[26:29], v[166:169], v[210:213], v[26:29]
	v_mfma_f32_16x16x32_bf16 v[14:17], v[158:161], v[218:221], v[14:17]
	v_mfma_f32_16x16x32_bf16 v[10:13], v[166:169], v[218:221], v[10:13]
	v_mfma_f32_16x16x32_bf16 v[54:57], v[170:173], v[190:193], v[54:57]
	v_mfma_f32_16x16x32_bf16 v[50:53], v[182:185], v[190:193], v[50:53]
	v_mfma_f32_16x16x32_bf16 v[38:41], v[170:173], v[198:201], v[38:41]
	v_mfma_f32_16x16x32_bf16 v[34:37], v[182:185], v[198:201], v[34:37]
	v_mfma_f32_16x16x32_bf16 v[22:25], v[170:173], v[206:209], v[22:25]
	v_mfma_f32_16x16x32_bf16 v[18:21], v[182:185], v[206:209], v[18:21]
	v_mfma_f32_16x16x32_bf16 v[6:9], v[170:173], v[214:217], v[6:9]
	v_mfma_f32_16x16x32_bf16 v[2:5], v[182:185], v[214:217], v[2:5]
	v_mfma_f32_16x16x32_bf16 v[54:57], v[174:177], v[194:197], v[54:57]
	v_mfma_f32_16x16x32_bf16 v[50:53], v[186:189], v[194:197], v[50:53]
	v_mfma_f32_16x16x32_bf16 v[38:41], v[174:177], v[202:205], v[38:41]
	v_mfma_f32_16x16x32_bf16 v[34:37], v[186:189], v[202:205], v[34:37]
	v_mfma_f32_16x16x32_bf16 v[22:25], v[174:177], v[210:213], v[22:25]
	v_mfma_f32_16x16x32_bf16 v[18:21], v[186:189], v[210:213], v[18:21]
	v_mfma_f32_16x16x32_bf16 v[6:9], v[174:177], v[218:221], v[6:9]
	v_mfma_f32_16x16x32_bf16 v[2:5], v[186:189], v[218:221], v[2:5]
	s_barrier
	s_setprio 0
	s_add_i32 s51, 0, 0x18000
	v_add_u32_e32 v153, s51, v148
	s_add_i32 s52, 0, 0x1c000
	ds_read_b128 v[154:157], v153
	ds_read_b128 v[158:161], v153 offset:1024
	ds_read_b128 v[162:165], v153 offset:2048
	ds_read_b128 v[166:169], v153 offset:3072
	v_add_u32_e32 v153, s52, v148
	ds_read_b128 v[170:173], v153
	ds_read_b128 v[174:177], v153 offset:1024
	ds_read_b128 v[182:185], v153 offset:2048
	ds_read_b128 v[186:189], v153 offset:3072
	s_add_u32 s22, s22, 0x80000
	s_addc_u32 s23, s23, 0
	s_mov_b32 m0, s30
	v_lshl_add_u64 v[228:229], s[22:23], 0, v[136:137]
	ds_read_b128 v[190:193], v152 offset:32768
	ds_read_b128 v[194:197], v152 offset:33792
	ds_read_b128 v[198:201], v152 offset:34816
	ds_read_b128 v[202:205], v152 offset:35840
	ds_read_b128 v[206:209], v152 offset:36864
	ds_read_b128 v[210:213], v152 offset:37888
	ds_read_b128 v[214:217], v152 offset:38912
	ds_read_b128 v[218:221], v152 offset:39936
	global_load_lds_dwordx4 v[228:229], off
	v_lshl_add_u64 v[228:229], s[22:23], 0, v[132:133]
	s_mov_b32 m0, s31
	s_nop 0
	global_load_lds_dwordx4 v[228:229], off
	s_waitcnt vmcnt(8)
	s_waitcnt lgkmcnt(0)
	s_setprio 1
	s_barrier
	v_mfma_f32_16x16x32_bf16 v[126:129], v[154:157], v[190:193], v[126:129]
	v_mfma_f32_16x16x32_bf16 v[122:125], v[162:165], v[190:193], v[122:125]
	v_mfma_f32_16x16x32_bf16 v[110:113], v[154:157], v[198:201], v[110:113]
	v_mfma_f32_16x16x32_bf16 v[106:109], v[162:165], v[198:201], v[106:109]
	v_mfma_f32_16x16x32_bf16 v[94:97], v[154:157], v[206:209], v[94:97]
	v_mfma_f32_16x16x32_bf16 v[90:93], v[162:165], v[206:209], v[90:93]
	v_mfma_f32_16x16x32_bf16 v[78:81], v[154:157], v[214:217], v[78:81]
	v_mfma_f32_16x16x32_bf16 v[74:77], v[162:165], v[214:217], v[74:77]
	v_mfma_f32_16x16x32_bf16 v[126:129], v[158:161], v[194:197], v[126:129]
	v_mfma_f32_16x16x32_bf16 v[122:125], v[166:169], v[194:197], v[122:125]
	v_mfma_f32_16x16x32_bf16 v[110:113], v[158:161], v[202:205], v[110:113]
	v_mfma_f32_16x16x32_bf16 v[106:109], v[166:169], v[202:205], v[106:109]
	v_mfma_f32_16x16x32_bf16 v[94:97], v[158:161], v[210:213], v[94:97]
	v_mfma_f32_16x16x32_bf16 v[90:93], v[166:169], v[210:213], v[90:93]
	v_mfma_f32_16x16x32_bf16 v[78:81], v[158:161], v[218:221], v[78:81]
	v_mfma_f32_16x16x32_bf16 v[74:77], v[166:169], v[218:221], v[74:77]
	v_mfma_f32_16x16x32_bf16 v[118:121], v[170:173], v[190:193], v[118:121]
	v_mfma_f32_16x16x32_bf16 v[114:117], v[182:185], v[190:193], v[114:117]
	v_mfma_f32_16x16x32_bf16 v[102:105], v[170:173], v[198:201], v[102:105]
	v_mfma_f32_16x16x32_bf16 v[98:101], v[182:185], v[198:201], v[98:101]
	v_mfma_f32_16x16x32_bf16 v[86:89], v[170:173], v[206:209], v[86:89]
	v_mfma_f32_16x16x32_bf16 v[82:85], v[182:185], v[206:209], v[82:85]
	v_mfma_f32_16x16x32_bf16 v[70:73], v[170:173], v[214:217], v[70:73]
	v_mfma_f32_16x16x32_bf16 v[66:69], v[182:185], v[214:217], v[66:69]
	v_mfma_f32_16x16x32_bf16 v[118:121], v[174:177], v[194:197], v[118:121]
	v_mfma_f32_16x16x32_bf16 v[114:117], v[186:189], v[194:197], v[114:117]
	v_mfma_f32_16x16x32_bf16 v[102:105], v[174:177], v[202:205], v[102:105]
	v_mfma_f32_16x16x32_bf16 v[98:101], v[186:189], v[202:205], v[98:101]
	v_mfma_f32_16x16x32_bf16 v[86:89], v[174:177], v[210:213], v[86:89]
	v_mfma_f32_16x16x32_bf16 v[82:85], v[186:189], v[210:213], v[82:85]
	v_mfma_f32_16x16x32_bf16 v[70:73], v[174:177], v[218:221], v[70:73]
	v_mfma_f32_16x16x32_bf16 v[66:69], v[186:189], v[218:221], v[66:69]
	s_barrier
	s_setprio 0
	s_add_i32 s22, s51, s26
	v_lshl_add_u64 v[146:147], v[146:147], 0, s[4:5]
	s_mov_b32 m0, s22
	ds_read_b128 v[190:193], v152 offset:49152
	ds_read_b128 v[194:197], v152 offset:50176
	ds_read_b128 v[198:201], v152 offset:51200
	ds_read_b128 v[202:205], v152 offset:52224
	ds_read_b128 v[206:209], v152 offset:53248
	ds_read_b128 v[210:213], v152 offset:54272
	ds_read_b128 v[214:217], v152 offset:55296
	ds_read_b128 v[218:221], v152 offset:56320
	global_load_lds_dwordx4 v[146:147], off
	s_add_i32 m0, s22, 0x2000
	s_add_u32 s20, s20, 0x80080
	v_lshl_add_u64 v[146:147], v[222:223], 0, s[4:5]
	s_addc_u32 s21, s21, 0
	s_add_i32 s22, s52, s26
	global_load_lds_dwordx4 v[146:147], off
	v_lshl_add_u64 v[146:147], s[20:21], 0, v[134:135]
	s_mov_b32 m0, s22
	s_nop 0
	global_load_lds_dwordx4 v[146:147], off
	v_lshl_add_u64 v[146:147], s[20:21], 0, v[130:131]
	s_add_i32 m0, s22, 0x2000
	s_nop 0
	global_load_lds_dwordx4 v[146:147], off
	v_lshl_add_u64 v[146:147], v[224:225], 0, s[4:5]
	s_mov_b32 m0, s35
	s_nop 0
	global_load_lds_dwordx4 v[146:147], off
	v_lshl_add_u64 v[146:147], v[226:227], 0, s[4:5]
	s_mov_b32 m0, s36
	s_nop 0
	global_load_lds_dwordx4 v[146:147], off
	s_waitcnt vmcnt(8)
	s_waitcnt lgkmcnt(0)
	s_setprio 1
	s_barrier
	v_mfma_f32_16x16x32_bf16 v[62:65], v[154:157], v[190:193], v[62:65]
	v_mfma_f32_16x16x32_bf16 v[58:61], v[162:165], v[190:193], v[58:61]
	v_mfma_f32_16x16x32_bf16 v[46:49], v[154:157], v[198:201], v[46:49]
	v_mfma_f32_16x16x32_bf16 v[42:45], v[162:165], v[198:201], v[42:45]
	v_mfma_f32_16x16x32_bf16 v[30:33], v[154:157], v[206:209], v[30:33]
	v_mfma_f32_16x16x32_bf16 v[26:29], v[162:165], v[206:209], v[26:29]
	v_mfma_f32_16x16x32_bf16 v[14:17], v[154:157], v[214:217], v[14:17]
	v_mfma_f32_16x16x32_bf16 v[10:13], v[162:165], v[214:217], v[10:13]
	v_mfma_f32_16x16x32_bf16 v[62:65], v[158:161], v[194:197], v[62:65]
	v_mfma_f32_16x16x32_bf16 v[58:61], v[166:169], v[194:197], v[58:61]
	v_mfma_f32_16x16x32_bf16 v[46:49], v[158:161], v[202:205], v[46:49]
	v_mfma_f32_16x16x32_bf16 v[42:45], v[166:169], v[202:205], v[42:45]
	v_mfma_f32_16x16x32_bf16 v[30:33], v[158:161], v[210:213], v[30:33]
	v_mfma_f32_16x16x32_bf16 v[26:29], v[166:169], v[210:213], v[26:29]
	v_mfma_f32_16x16x32_bf16 v[14:17], v[158:161], v[218:221], v[14:17]
	v_mfma_f32_16x16x32_bf16 v[10:13], v[166:169], v[218:221], v[10:13]
	v_mfma_f32_16x16x32_bf16 v[54:57], v[170:173], v[190:193], v[54:57]
	v_mfma_f32_16x16x32_bf16 v[50:53], v[182:185], v[190:193], v[50:53]
	v_mfma_f32_16x16x32_bf16 v[38:41], v[170:173], v[198:201], v[38:41]
	v_mfma_f32_16x16x32_bf16 v[34:37], v[182:185], v[198:201], v[34:37]
	v_mfma_f32_16x16x32_bf16 v[22:25], v[170:173], v[206:209], v[22:25]
	v_mfma_f32_16x16x32_bf16 v[18:21], v[182:185], v[206:209], v[18:21]
	v_mfma_f32_16x16x32_bf16 v[6:9], v[170:173], v[214:217], v[6:9]
	v_mfma_f32_16x16x32_bf16 v[2:5], v[182:185], v[214:217], v[2:5]
	v_mfma_f32_16x16x32_bf16 v[54:57], v[174:177], v[194:197], v[54:57]
	v_mfma_f32_16x16x32_bf16 v[50:53], v[186:189], v[194:197], v[50:53]
	v_mfma_f32_16x16x32_bf16 v[38:41], v[174:177], v[202:205], v[38:41]
	v_mfma_f32_16x16x32_bf16 v[34:37], v[186:189], v[202:205], v[34:37]
	v_mfma_f32_16x16x32_bf16 v[22:25], v[174:177], v[210:213], v[22:25]
	v_mfma_f32_16x16x32_bf16 v[18:21], v[186:189], v[210:213], v[18:21]
	v_mfma_f32_16x16x32_bf16 v[6:9], v[174:177], v[218:221], v[6:9]
	v_mfma_f32_16x16x32_bf16 v[2:5], v[186:189], v[218:221], v[2:5]
	s_barrier
	s_setprio 0
	s_add_i32 s50, s50, 2
	s_add_u32 s18, s18, 0x100
	s_addc_u32 s19, s19, 0
	s_add_u32 s46, s46, 0x100
	s_addc_u32 s47, s47, 0
	s_cmp_gt_u32 s50, 29
	s_cbranch_scc0 .LBB0_3191
	s_and_b64 vcc, exec, s[6:7]
	s_cbranch_vccz .LBB0_3194
	s_barrier

.LBB0_3274:
	ds_read_b128 v[152:155], v149
	ds_read_b128 v[156:159], v149 offset:1024
	ds_read_b128 v[160:163], v149 offset:2048
	ds_read_b128 v[164:167], v149 offset:3072
	ds_read_b128 v[168:171], v150
	ds_read_b128 v[172:175], v150 offset:1024
	ds_read_b128 v[182:185], v150 offset:2048
	ds_read_b128 v[186:189], v150 offset:3072
	s_add_u32 s22, s20, 0xffea0080
	s_addc_u32 s23, s21, -1
	s_cmpk_eq_i32 s56, 0x54
	s_cselect_b32 s25, s3, s23
	s_cselect_b32 s24, s2, s22
	s_cselect_b32 s23, s19, s55
	s_cselect_b32 s22, s18, s54
	v_lshl_add_u64 v[144:145], s[20:21], 0, v[136:137]
	s_add_i32 m0, s30, 0xc000
	ds_read_b128 v[190:193], v151
	ds_read_b128 v[194:197], v151 offset:1024
	ds_read_b128 v[198:201], v151 offset:2048
	ds_read_b128 v[202:205], v151 offset:3072
	ds_read_b128 v[206:209], v151 offset:4096
	ds_read_b128 v[210:213], v151 offset:5120
	ds_read_b128 v[214:217], v151 offset:6144
	ds_read_b128 v[218:221], v151 offset:7168
	global_load_lds_dwordx4 v[144:145], off
	v_lshl_add_u64 v[144:145], s[20:21], 0, v[138:139]
	s_add_i32 m0, s30, 0xe000
	s_nop 0
	global_load_lds_dwordx4 v[144:145], off
	s_waitcnt vmcnt(8)
	s_waitcnt lgkmcnt(0)
	s_setprio 1
	s_barrier
	v_mfma_f32_16x16x32_bf16 v[124:127], v[152:155], v[190:193], v[124:127]
	v_mfma_f32_16x16x32_bf16 v[120:123], v[160:163], v[190:193], v[120:123]
	v_mfma_f32_16x16x32_bf16 v[116:119], v[152:155], v[198:201], v[116:119]
	v_mfma_f32_16x16x32_bf16 v[108:111], v[160:163], v[198:201], v[108:111]
	v_mfma_f32_16x16x32_bf16 v[100:103], v[152:155], v[206:209], v[100:103]
	v_mfma_f32_16x16x32_bf16 v[92:95], v[160:163], v[206:209], v[92:95]
	v_mfma_f32_16x16x32_bf16 v[84:87], v[152:155], v[214:217], v[84:87]
	v_mfma_f32_16x16x32_bf16 v[76:79], v[160:163], v[214:217], v[76:79]
	v_mfma_f32_16x16x32_bf16 v[124:127], v[156:159], v[194:197], v[124:127]
	v_mfma_f32_16x16x32_bf16 v[120:123], v[164:167], v[194:197], v[120:123]
	v_mfma_f32_16x16x32_bf16 v[116:119], v[156:159], v[202:205], v[116:119]
	v_mfma_f32_16x16x32_bf16 v[108:111], v[164:167], v[202:205], v[108:111]
	v_mfma_f32_16x16x32_bf16 v[100:103], v[156:159], v[210:213], v[100:103]
	v_mfma_f32_16x16x32_bf16 v[92:95], v[164:167], v[210:213], v[92:95]
	v_mfma_f32_16x16x32_bf16 v[84:87], v[156:159], v[218:221], v[84:87]
	v_mfma_f32_16x16x32_bf16 v[76:79], v[164:167], v[218:221], v[76:79]
	v_mfma_f32_16x16x32_bf16 v[112:115], v[168:171], v[190:193], v[112:115]
	v_mfma_f32_16x16x32_bf16 v[104:107], v[182:185], v[190:193], v[104:107]
	v_mfma_f32_16x16x32_bf16 v[96:99], v[168:171], v[198:201], v[96:99]
	v_mfma_f32_16x16x32_bf16 v[88:91], v[182:185], v[198:201], v[88:91]
	v_mfma_f32_16x16x32_bf16 v[80:83], v[168:171], v[206:209], v[80:83]
	v_mfma_f32_16x16x32_bf16 v[72:75], v[182:185], v[206:209], v[72:75]
	v_mfma_f32_16x16x32_bf16 v[68:71], v[168:171], v[214:217], v[68:71]
	v_mfma_f32_16x16x32_bf16 v[64:67], v[182:185], v[214:217], v[64:67]
	v_mfma_f32_16x16x32_bf16 v[112:115], v[172:175], v[194:197], v[112:115]
	v_mfma_f32_16x16x32_bf16 v[104:107], v[186:189], v[194:197], v[104:107]
	v_mfma_f32_16x16x32_bf16 v[96:99], v[172:175], v[202:205], v[96:99]
	v_mfma_f32_16x16x32_bf16 v[88:91], v[186:189], v[202:205], v[88:91]
	v_mfma_f32_16x16x32_bf16 v[80:83], v[172:175], v[210:213], v[80:83]
	v_mfma_f32_16x16x32_bf16 v[72:75], v[186:189], v[210:213], v[72:75]
	v_mfma_f32_16x16x32_bf16 v[68:71], v[172:175], v[218:221], v[68:71]
	v_mfma_f32_16x16x32_bf16 v[64:67], v[186:189], v[218:221], v[64:67]
	s_barrier
	s_setprio 0
	s_add_i32 s57, s42, s29
	v_lshl_add_u64 v[144:145], s[22:23], 0, v[130:131]
	s_mov_b32 m0, s57
	ds_read_b128 v[190:193], v151 offset:16384
	ds_read_b128 v[194:197], v151 offset:17408
	ds_read_b128 v[198:201], v151 offset:18432
	ds_read_b128 v[202:205], v151 offset:19456
	ds_read_b128 v[206:209], v151 offset:20480
	ds_read_b128 v[210:213], v151 offset:21504
	ds_read_b128 v[214:217], v151 offset:22528
	ds_read_b128 v[218:221], v151 offset:23552
	global_load_lds_dwordx4 v[144:145], off
	s_add_i32 m0, s57, 0x2000
	s_add_u32 s58, s22, 0x160000
	v_lshl_add_u64 v[176:177], s[22:23], 0, v[134:135]
	s_addc_u32 s59, s23, 0
	s_add_i32 s57, s43, s29
	global_load_lds_dwordx4 v[176:177], off
	v_lshl_add_u64 v[222:223], s[58:59], 0, v[130:131]
	s_mov_b32 m0, s57
	v_lshl_add_u64 v[224:225], s[24:25], 0, v[132:133]
	global_load_lds_dwordx4 v[222:223], off
	v_lshl_add_u64 v[222:223], s[58:59], 0, v[134:135]
	s_add_i32 m0, s57, 0x2000
	s_nop 0
	global_load_lds_dwordx4 v[222:223], off
	v_lshl_add_u64 v[222:223], s[24:25], 0, v[128:129]
	s_mov_b32 m0, s30
	s_nop 0
	global_load_lds_dwordx4 v[222:223], off
	s_mov_b32 m0, s31
	s_nop 0
	global_load_lds_dwordx4 v[224:225], off
	s_waitcnt vmcnt(8)
	s_waitcnt lgkmcnt(0)
	s_setprio 1
	s_barrier
	v_mfma_f32_16x16x32_bf16 v[60:63], v[152:155], v[190:193], v[60:63]
	v_mfma_f32_16x16x32_bf16 v[56:59], v[160:163], v[190:193], v[56:59]
	v_mfma_f32_16x16x32_bf16 v[52:55], v[152:155], v[198:201], v[52:55]
	v_mfma_f32_16x16x32_bf16 v[44:47], v[160:163], v[198:201], v[44:47]
	v_mfma_f32_16x16x32_bf16 v[36:39], v[152:155], v[206:209], v[36:39]
	v_mfma_f32_16x16x32_bf16 v[28:31], v[160:163], v[206:209], v[28:31]
	v_mfma_f32_16x16x32_bf16 v[20:23], v[152:155], v[214:217], v[20:23]
	v_mfma_f32_16x16x32_bf16 v[12:15], v[160:163], v[214:217], v[12:15]
	v_mfma_f32_16x16x32_bf16 v[60:63], v[156:159], v[194:197], v[60:63]
	v_mfma_f32_16x16x32_bf16 v[56:59], v[164:167], v[194:197], v[56:59]
	v_mfma_f32_16x16x32_bf16 v[52:55], v[156:159], v[202:205], v[52:55]
	v_mfma_f32_16x16x32_bf16 v[44:47], v[164:167], v[202:205], v[44:47]
	v_mfma_f32_16x16x32_bf16 v[36:39], v[156:159], v[210:213], v[36:39]
	v_mfma_f32_16x16x32_bf16 v[28:31], v[164:167], v[210:213], v[28:31]
	v_mfma_f32_16x16x32_bf16 v[20:23], v[156:159], v[218:221], v[20:23]
	v_mfma_f32_16x16x32_bf16 v[12:15], v[164:167], v[218:221], v[12:15]
	v_mfma_f32_16x16x32_bf16 v[48:51], v[168:171], v[190:193], v[48:51]
	v_mfma_f32_16x16x32_bf16 v[40:43], v[182:185], v[190:193], v[40:43]
	v_mfma_f32_16x16x32_bf16 v[32:35], v[168:171], v[198:201], v[32:35]
	v_mfma_f32_16x16x32_bf16 v[24:27], v[182:185], v[198:201], v[24:27]
	v_mfma_f32_16x16x32_bf16 v[16:19], v[168:171], v[206:209], v[16:19]
	v_mfma_f32_16x16x32_bf16 v[8:11], v[182:185], v[206:209], v[8:11]
	v_mfma_f32_16x16x32_bf16 v[4:7], v[168:171], v[214:217], v[4:7]
	v_mfma_f32_16x16x32_bf16 v[0:3], v[182:185], v[214:217], v[0:3]
	v_mfma_f32_16x16x32_bf16 v[48:51], v[172:175], v[194:197], v[48:51]
	v_mfma_f32_16x16x32_bf16 v[40:43], v[186:189], v[194:197], v[40:43]
	v_mfma_f32_16x16x32_bf16 v[32:35], v[172:175], v[202:205], v[32:35]
	v_mfma_f32_16x16x32_bf16 v[24:27], v[186:189], v[202:205], v[24:27]
	v_mfma_f32_16x16x32_bf16 v[16:19], v[172:175], v[210:213], v[16:19]
	v_mfma_f32_16x16x32_bf16 v[8:11], v[186:189], v[210:213], v[8:11]
	v_mfma_f32_16x16x32_bf16 v[4:7], v[172:175], v[218:221], v[4:7]
	v_mfma_f32_16x16x32_bf16 v[0:3], v[186:189], v[218:221], v[0:3]
	s_barrier
	s_setprio 0
	s_add_i32 s57, 0, 0x18000
	s_add_i32 s58, 0, 0x1c000
	v_add_u32_e32 v164, s57, v147
	v_add_u32_e32 v179, s58, v147
	ds_read_b128 v[152:155], v164
	ds_read_b128 v[156:159], v164 offset:1024
	ds_read_b128 v[160:163], v164 offset:2048
	ds_read_b128 v[164:167], v164 offset:3072
	ds_read_b128 v[168:171], v179
	ds_read_b128 v[172:175], v179 offset:1024
	ds_read_b128 v[182:185], v179 offset:2048
	ds_read_b128 v[186:189], v179 offset:3072
	s_add_u32 s24, s24, 0x160000
	s_addc_u32 s25, s25, 0
	s_mov_b32 m0, s34
	v_lshl_add_u64 v[226:227], s[24:25], 0, v[128:129]
	ds_read_b128 v[190:193], v151 offset:32768
	ds_read_b128 v[194:197], v151 offset:33792
	ds_read_b128 v[198:201], v151 offset:34816
	ds_read_b128 v[202:205], v151 offset:35840
	ds_read_b128 v[206:209], v151 offset:36864
	ds_read_b128 v[210:213], v151 offset:37888
	ds_read_b128 v[214:217], v151 offset:38912
	ds_read_b128 v[218:221], v151 offset:39936
	global_load_lds_dwordx4 v[226:227], off
	v_lshl_add_u64 v[226:227], s[24:25], 0, v[132:133]
	s_mov_b32 m0, s35
	s_nop 0
	global_load_lds_dwordx4 v[226:227], off
	s_waitcnt vmcnt(8)
	s_waitcnt lgkmcnt(0)
	s_setprio 1
	s_barrier
	v_mfma_f32_16x16x32_bf16 v[124:127], v[152:155], v[190:193], v[124:127]
	v_mfma_f32_16x16x32_bf16 v[120:123], v[160:163], v[190:193], v[120:123]
	v_mfma_f32_16x16x32_bf16 v[116:119], v[152:155], v[198:201], v[116:119]
	v_mfma_f32_16x16x32_bf16 v[108:111], v[160:163], v[198:201], v[108:111]
	v_mfma_f32_16x16x32_bf16 v[100:103], v[152:155], v[206:209], v[100:103]
	v_mfma_f32_16x16x32_bf16 v[92:95], v[160:163], v[206:209], v[92:95]
	v_mfma_f32_16x16x32_bf16 v[84:87], v[152:155], v[214:217], v[84:87]
	v_mfma_f32_16x16x32_bf16 v[76:79], v[160:163], v[214:217], v[76:79]
	v_mfma_f32_16x16x32_bf16 v[124:127], v[156:159], v[194:197], v[124:127]
	v_mfma_f32_16x16x32_bf16 v[120:123], v[164:167], v[194:197], v[120:123]
	v_mfma_f32_16x16x32_bf16 v[116:119], v[156:159], v[202:205], v[116:119]
	v_mfma_f32_16x16x32_bf16 v[108:111], v[164:167], v[202:205], v[108:111]
	v_mfma_f32_16x16x32_bf16 v[100:103], v[156:159], v[210:213], v[100:103]
	v_mfma_f32_16x16x32_bf16 v[92:95], v[164:167], v[210:213], v[92:95]
	v_mfma_f32_16x16x32_bf16 v[84:87], v[156:159], v[218:221], v[84:87]
	v_mfma_f32_16x16x32_bf16 v[76:79], v[164:167], v[218:221], v[76:79]
	v_mfma_f32_16x16x32_bf16 v[112:115], v[168:171], v[190:193], v[112:115]
	v_mfma_f32_16x16x32_bf16 v[104:107], v[182:185], v[190:193], v[104:107]
	v_mfma_f32_16x16x32_bf16 v[96:99], v[168:171], v[198:201], v[96:99]
	v_mfma_f32_16x16x32_bf16 v[88:91], v[182:185], v[198:201], v[88:91]
	v_mfma_f32_16x16x32_bf16 v[80:83], v[168:171], v[206:209], v[80:83]
	v_mfma_f32_16x16x32_bf16 v[72:75], v[182:185], v[206:209], v[72:75]
	v_mfma_f32_16x16x32_bf16 v[68:71], v[168:171], v[214:217], v[68:71]
	v_mfma_f32_16x16x32_bf16 v[64:67], v[182:185], v[214:217], v[64:67]
	v_mfma_f32_16x16x32_bf16 v[112:115], v[172:175], v[194:197], v[112:115]
	v_mfma_f32_16x16x32_bf16 v[104:107], v[186:189], v[194:197], v[104:107]
	v_mfma_f32_16x16x32_bf16 v[96:99], v[172:175], v[202:205], v[96:99]
	v_mfma_f32_16x16x32_bf16 v[88:91], v[186:189], v[202:205], v[88:91]
	v_mfma_f32_16x16x32_bf16 v[80:83], v[172:175], v[210:213], v[80:83]
	v_mfma_f32_16x16x32_bf16 v[72:75], v[186:189], v[210:213], v[72:75]
	v_mfma_f32_16x16x32_bf16 v[68:71], v[172:175], v[218:221], v[68:71]
	v_mfma_f32_16x16x32_bf16 v[64:67], v[186:189], v[218:221], v[64:67]
	s_barrier
	s_setprio 0
	s_add_i32 s24, s57, s29
	v_lshl_add_u64 v[144:145], v[144:145], 0, s[6:7]
	s_mov_b32 m0, s24
	ds_read_b128 v[190:193], v151 offset:49152
	ds_read_b128 v[194:197], v151 offset:50176
	ds_read_b128 v[198:201], v151 offset:51200
	ds_read_b128 v[202:205], v151 offset:52224
	ds_read_b128 v[206:209], v151 offset:53248
	ds_read_b128 v[210:213], v151 offset:54272
	ds_read_b128 v[214:217], v151 offset:55296
	ds_read_b128 v[218:221], v151 offset:56320
	global_load_lds_dwordx4 v[144:145], off
	s_add_i32 m0, s24, 0x2000
	s_add_u32 s22, s22, 0x160080
	v_lshl_add_u64 v[144:145], v[176:177], 0, s[6:7]
	s_addc_u32 s23, s23, 0
	s_add_i32 s24, s58, s29
	global_load_lds_dwordx4 v[144:145], off
	v_lshl_add_u64 v[144:145], s[22:23], 0, v[130:131]
	s_mov_b32 m0, s24
	s_nop 0
	global_load_lds_dwordx4 v[144:145], off
	v_lshl_add_u64 v[144:145], s[22:23], 0, v[134:135]
	s_add_i32 m0, s24, 0x2000
	s_nop 0
	global_load_lds_dwordx4 v[144:145], off
	v_lshl_add_u64 v[144:145], v[222:223], 0, s[6:7]
	s_mov_b32 m0, s37
	s_nop 0
	global_load_lds_dwordx4 v[144:145], off
	v_lshl_add_u64 v[144:145], v[224:225], 0, s[6:7]
	s_mov_b32 m0, s38
	s_nop 0
	global_load_lds_dwordx4 v[144:145], off
	s_waitcnt vmcnt(8)
	s_waitcnt lgkmcnt(0)
	s_setprio 1
	s_barrier
	v_mfma_f32_16x16x32_bf16 v[60:63], v[152:155], v[190:193], v[60:63]
	v_mfma_f32_16x16x32_bf16 v[56:59], v[160:163], v[190:193], v[56:59]
	v_mfma_f32_16x16x32_bf16 v[52:55], v[152:155], v[198:201], v[52:55]
	v_mfma_f32_16x16x32_bf16 v[44:47], v[160:163], v[198:201], v[44:47]
	v_mfma_f32_16x16x32_bf16 v[36:39], v[152:155], v[206:209], v[36:39]
	v_mfma_f32_16x16x32_bf16 v[28:31], v[160:163], v[206:209], v[28:31]
	v_mfma_f32_16x16x32_bf16 v[20:23], v[152:155], v[214:217], v[20:23]
	v_mfma_f32_16x16x32_bf16 v[12:15], v[160:163], v[214:217], v[12:15]
	v_mfma_f32_16x16x32_bf16 v[60:63], v[156:159], v[194:197], v[60:63]
	v_mfma_f32_16x16x32_bf16 v[56:59], v[164:167], v[194:197], v[56:59]
	v_mfma_f32_16x16x32_bf16 v[52:55], v[156:159], v[202:205], v[52:55]
	v_mfma_f32_16x16x32_bf16 v[44:47], v[164:167], v[202:205], v[44:47]
	v_mfma_f32_16x16x32_bf16 v[36:39], v[156:159], v[210:213], v[36:39]
	v_mfma_f32_16x16x32_bf16 v[28:31], v[164:167], v[210:213], v[28:31]
	v_mfma_f32_16x16x32_bf16 v[20:23], v[156:159], v[218:221], v[20:23]
	v_mfma_f32_16x16x32_bf16 v[12:15], v[164:167], v[218:221], v[12:15]
	v_mfma_f32_16x16x32_bf16 v[48:51], v[168:171], v[190:193], v[48:51]
	v_mfma_f32_16x16x32_bf16 v[40:43], v[182:185], v[190:193], v[40:43]
	v_mfma_f32_16x16x32_bf16 v[32:35], v[168:171], v[198:201], v[32:35]
	v_mfma_f32_16x16x32_bf16 v[24:27], v[182:185], v[198:201], v[24:27]
	v_mfma_f32_16x16x32_bf16 v[16:19], v[168:171], v[206:209], v[16:19]
	v_mfma_f32_16x16x32_bf16 v[8:11], v[182:185], v[206:209], v[8:11]
	v_mfma_f32_16x16x32_bf16 v[4:7], v[168:171], v[214:217], v[4:7]
	v_mfma_f32_16x16x32_bf16 v[0:3], v[182:185], v[214:217], v[0:3]
	v_mfma_f32_16x16x32_bf16 v[48:51], v[172:175], v[194:197], v[48:51]
	v_mfma_f32_16x16x32_bf16 v[40:43], v[186:189], v[194:197], v[40:43]
	v_mfma_f32_16x16x32_bf16 v[32:35], v[172:175], v[202:205], v[32:35]
	v_mfma_f32_16x16x32_bf16 v[24:27], v[186:189], v[202:205], v[24:27]
	v_mfma_f32_16x16x32_bf16 v[16:19], v[172:175], v[210:213], v[16:19]
	v_mfma_f32_16x16x32_bf16 v[8:11], v[186:189], v[210:213], v[8:11]
	v_mfma_f32_16x16x32_bf16 v[4:7], v[172:175], v[218:221], v[4:7]
	v_mfma_f32_16x16x32_bf16 v[0:3], v[186:189], v[218:221], v[0:3]
	s_barrier
	s_setprio 0
	s_add_i32 s56, s56, 2
	s_add_u32 s20, s20, 0x100
	s_addc_u32 s21, s21, 0
	s_add_u32 s54, s54, 0x100
	s_addc_u32 s55, s55, 0
	s_cmpk_gt_u32 s56, 0x55
	s_cbranch_scc0 .LBB0_3274
	s_and_b64 vcc, exec, s[8:9]
	s_cbranch_vccz .LBB0_3277
	s_barrier

	.amdhsa_kernel _Z10fwd_kernel4Args
		.amdhsa_group_segment_fixed_size 0
		.amdhsa_private_segment_fixed_size 0
		.amdhsa_kernarg_size 488
		.amdhsa_user_sgpr_count 2
		.amdhsa_user_sgpr_dispatch_ptr 0
		.amdhsa_user_sgpr_queue_ptr 0
		.amdhsa_user_sgpr_kernarg_segment_ptr 1
		.amdhsa_user_sgpr_dispatch_id 0
		.amdhsa_user_sgpr_kernarg_preload_length 0
		.amdhsa_user_sgpr_kernarg_preload_offset 0
		.amdhsa_user_sgpr_private_segment_size 0
		.amdhsa_uses_dynamic_stack 0
		.amdhsa_enable_private_segment 0
		.amdhsa_system_sgpr_workgroup_id_x 1
		.amdhsa_system_sgpr_workgroup_id_y 0
		.amdhsa_system_sgpr_workgroup_id_z 0
		.amdhsa_system_sgpr_workgroup_info 0
		.amdhsa_system_vgpr_workitem_id 0
		.amdhsa_next_free_vgpr 256
		.amdhsa_next_free_sgpr 98
		.amdhsa_accum_offset 256
		.amdhsa_reserve_vcc 1
		.amdhsa_float_round_mode_32 0
		.amdhsa_float_round_mode_16_64 0
		.amdhsa_float_denorm_mode_32 3
		.amdhsa_float_denorm_mode_16_64 3
		.amdhsa_dx10_clamp 1
		.amdhsa_ieee_mode 1
		.amdhsa_fp16_overflow 0
		.amdhsa_tg_split 0
		.amdhsa_exception_fp_ieee_invalid_op 0
		.amdhsa_exception_fp_denorm_src 0
		.amdhsa_exception_fp_ieee_div_zero 0
		.amdhsa_exception_fp_ieee_overflow 0
		.amdhsa_exception_fp_ieee_underflow 0
		.amdhsa_exception_fp_ieee_inexact 0
		.amdhsa_exception_int_div_zero 0
	.end_amdhsa_kernel

amdhsa.kernels:
  - .agpr_count:     0
    .args:
      - .offset:         0
        .size:           232
        .value_kind:     by_value
      - .offset:         232
        .size:           4
        .value_kind:     hidden_block_count_x
      - .offset:         236
        .size:           4
        .value_kind:     hidden_block_count_y
      - .offset:         240
        .size:           4
        .value_kind:     hidden_block_count_z
      - .offset:         244
        .size:           2
        .value_kind:     hidden_group_size_x
      - .offset:         246
        .size:           2
        .value_kind:     hidden_group_size_y
      - .offset:         248
        .size:           2
        .value_kind:     hidden_group_size_z
      - .offset:         250
        .size:           2
        .value_kind:     hidden_remainder_x
      - .offset:         252
        .size:           2
        .value_kind:     hidden_remainder_y
      - .offset:         254
        .size:           2
        .value_kind:     hidden_remainder_z
      - .offset:         272
        .size:           8
        .value_kind:     hidden_global_offset_x
      - .offset:         280
        .size:           8
        .value_kind:     hidden_global_offset_y
      - .offset:         288
        .size:           8
        .value_kind:     hidden_global_offset_z
      - .offset:         296
        .size:           2
        .value_kind:     hidden_grid_dims
      - .offset:         352
        .size:           4
        .value_kind:     hidden_dynamic_lds_size
    .group_segment_fixed_size: 0
    .kernarg_segment_align: 8
    .kernarg_segment_size: 488
    .language:       OpenCL C
    .language_version:
      - 2
      - 0
    .max_flat_workgroup_size: 512
    .name:           _Z10fwd_kernel4Args
    .private_segment_fixed_size: 0
    .sgpr_count:     104
    .sgpr_spill_count: 47
    .symbol:         _Z10fwd_kernel4Args.kd
    .uniform_work_group_size: 1
    .uses_dynamic_stack: false
    .vgpr_count:     256
    .vgpr_spill_count: 0
    .wavefront_size: 64
